# merge phases: flat_load/flat_store dwordx4 replaced by global_load/global_store (addresses are in d_ws)
# baseline (speedup 1.0000x reference)
; __device__ __forceinline__ u32x4 pack8(const f32x4 a, const f32x4 b) { u32x4 w; w.x = pk2(a[0], a[1]); w.y = pk2(a[2], a[3]); w.z = pk2(b[0], b[1]); w.w = pk2(b[2], b[3]); return w; }
; __device__ __forceinline__ void unpack8(const u32x4 w, f32x4& a, f32x4& b) { a = (f32x4){bflo(w.x), bfhi(w.x), bflo(w.y), bfhi(w.y)}; b = (f32x4){bflo(w.z), bfhi(w.z), bflo(w.w), bfhi(w.w)}; }
;     __device__ __forceinline__ void operator()(const Acc& acc, const Unit& u, int wr, int wc, int fr, int fq) const {
;     ...
;         } else {
; #pragma unroll
;             for (int ai = 0; ai < 2; ++ai)
; #pragma unroll
;                 for (int mp = 0; mp < 2; ++mp) {
;                     u32x4 c[2][2], s[2][2];
; #pragma unroll
;                     for (int mm = 0; mm < 2; ++mm)
; #pragma unroll
;                         for (int bj = 0; bj < 2; ++bj) { c[mm][bj] = *MP(ai, 2 * mp + mm, bj); s[mm][bj] = *SP(ai, 2 * mp + mm, bj); }
; #pragma unroll
;                     for (int mm = 0; mm < 2; ++mm)
; #pragma unroll
;                         for (int bj = 0; bj < 2; ++bj) { const int m = 2 * mp + mm; f32x4 c0, c1, s0, s1; unpack8(c[mm][bj], c0, c1); unpack8(s[mm][bj], s0, s1);
;                             *MP(ai, m, bj) = pack8(c0 + s0 * acc[ai][bj][m][0], c1 + s1 * acc[ai][bj][m][1]); }
;                     asm volatile("" ::: "memory");
;                 }
.LBB0_1125:
	v_lshl_add_u32 v166, s54, 8, v1
	v_ashrrev_i32_e32 v167, 31, v166
	v_lshlrev_b64 v[130:131], 11, v[166:167]
	s_lshl_b32 s4, s4, 8
	v_lshl_add_u64 v[130:131], s[42:43], 0, v[130:131]
	s_ashr_i32 s5, s4, 31
	v_lshl_add_u64 v[130:131], s[4:5], 1, v[130:131]
	s_bitcmp1_b32 s55, 0
	v_lshl_add_u64 v[130:131], v[130:131], 0, s[26:27]
	s_cselect_b64 s[18:19], -1, 0
	v_lshl_add_u64 v[162:163], v[130:131], 0, v[148:149]
	v_mov_b64_e32 v[164:165], v[150:151]
	s_mov_b64 s[4:5], -1
	s_and_b64 vcc, exec, s[18:19]
	s_cbranch_vccz .LBB0_1131
	global_load_dwordx4 v[168:171], v[162:163], off
	s_cmp_eq_u32 s55, 1
	s_waitcnt vmcnt(0) lgkmcnt(0)
	v_lshlrev_b32_e32 v132, 16, v168
	v_and_b32_e32 v133, 0xffff0000, v168
	v_lshlrev_b32_e32 v136, 16, v169
	v_and_b32_e32 v137, 0xffff0000, v169
	v_lshlrev_b32_e32 v130, 16, v170
	v_and_b32_e32 v131, 0xffff0000, v170
	v_lshlrev_b32_e32 v134, 16, v171
	v_and_b32_e32 v135, 0xffff0000, v171
	s_cbranch_scc1 .LBB0_1128
	v_add_co_u32_e32 v168, vcc, 0x2000, v164
	global_load_dwordx4 v[176:179], v[164:165], off
	global_load_dwordx4 v[180:183], v[162:163], off offset:256
	v_addc_co_u32_e32 v169, vcc, 0, v165, vcc
	global_load_dwordx4 v[184:187], v[168:169], off
	v_add_co_u32_e32 v168, vcc, 0x8000, v162
	s_mov_b64 s[4:5], 0
	s_nop 0
	v_addc_co_u32_e32 v169, vcc, 0, v163, vcc
	v_add_co_u32_e32 v170, vcc, 0x4000, v164
	global_load_dwordx4 v[192:195], v[168:169], off
	s_nop 0
	v_addc_co_u32_e32 v171, vcc, 0, v165, vcc
	global_load_dwordx4 v[196:199], v[170:171], off
	global_load_dwordx4 v[200:203], v[168:169], off offset:256
	v_add_co_u32_e32 v170, vcc, 0x6000, v164
	s_waitcnt vmcnt(0) lgkmcnt(0)
	v_lshlrev_b32_e32 v188, 16, v178
	v_addc_co_u32_e32 v171, vcc, 0, v165, vcc
	global_load_dwordx4 v[204:207], v[170:171], off
	v_lshlrev_b32_e32 v170, 16, v176
	v_and_b32_e32 v171, 0xffff0000, v176
	v_and_b32_e32 v189, 0xffff0000, v178
	v_lshlrev_b32_e32 v178, 16, v179
	v_and_b32_e32 v179, 0xffff0000, v179
	v_lshlrev_b32_e32 v176, 16, v177
	v_and_b32_e32 v177, 0xffff0000, v177
	v_pk_fma_f32 v[170:171], v[126:127], v[170:171], v[132:133]
	v_pk_fma_f32 v[214:215], v[124:125], v[178:179], v[134:135]
	v_pk_fma_f32 v[178:179], v[122:123], v[188:189], v[130:131]
	v_lshlrev_b32_e32 v208, 16, v180
	v_and_b32_e32 v209, 0xffff0000, v180
	v_lshlrev_b32_e32 v180, 16, v181
	v_and_b32_e32 v181, 0xffff0000, v181
	v_lshlrev_b32_e32 v210, 16, v182
	v_and_b32_e32 v211, 0xffff0000, v182
	v_lshlrev_b32_e32 v182, 16, v183
	v_and_b32_e32 v183, 0xffff0000, v183
	v_pk_fma_f32 v[212:213], v[128:129], v[176:177], v[136:137]
	v_cvt_pk_bf16_f32 v176, v170, v171
	v_lshlrev_b32_e32 v170, 16, v184
	v_cvt_pk_bf16_f32 v177, v212, v213
	v_cvt_pk_bf16_f32 v178, v178, v179
	v_cvt_pk_bf16_f32 v179, v214, v215
	v_and_b32_e32 v171, 0xffff0000, v184
	v_lshlrev_b32_e32 v184, 16, v185
	v_and_b32_e32 v185, 0xffff0000, v185
	v_lshlrev_b32_e32 v188, 16, v186
	v_and_b32_e32 v189, 0xffff0000, v186
	v_lshlrev_b32_e32 v186, 16, v187
	v_and_b32_e32 v187, 0xffff0000, v187
	global_store_dwordx4 v[162:163], v[176:179], off
	v_pk_fma_f32 v[170:171], v[118:119], v[170:171], v[208:209]
	s_nop 0
	v_pk_fma_f32 v[178:179], v[120:121], v[184:185], v[180:181]
	v_pk_fma_f32 v[180:181], v[116:117], v[186:187], v[182:183]
	v_pk_fma_f32 v[182:183], v[114:115], v[188:189], v[210:211]
	v_lshlrev_b32_e32 v186, 16, v193
	v_and_b32_e32 v187, 0xffff0000, v193
	v_cvt_pk_bf16_f32 v176, v170, v171
	v_cvt_pk_bf16_f32 v177, v178, v179
	v_cvt_pk_bf16_f32 v178, v182, v183
	v_cvt_pk_bf16_f32 v179, v180, v181
	v_lshlrev_b32_e32 v180, 16, v197
	v_and_b32_e32 v181, 0xffff0000, v197
	v_lshlrev_b32_e32 v184, 16, v192
	v_and_b32_e32 v185, 0xffff0000, v192
	v_lshlrev_b32_e32 v188, 16, v194
	v_and_b32_e32 v189, 0xffff0000, v194
	v_lshlrev_b32_e32 v192, 16, v195
	v_and_b32_e32 v193, 0xffff0000, v195
	v_lshlrev_b32_e32 v170, 16, v196
	v_and_b32_e32 v171, 0xffff0000, v196
	v_lshlrev_b32_e32 v182, 16, v198
	v_and_b32_e32 v183, 0xffff0000, v198
	v_lshlrev_b32_e32 v194, 16, v199
	v_and_b32_e32 v195, 0xffff0000, v199
	global_store_dwordx4 v[162:163], v[176:179], off offset:256
	v_pk_fma_f32 v[170:171], v[110:111], v[170:171], v[184:185]
	v_pk_fma_f32 v[182:183], v[106:107], v[182:183], v[188:189]
	v_pk_fma_f32 v[178:179], v[112:113], v[180:181], v[186:187]
	v_pk_fma_f32 v[180:181], v[108:109], v[194:195], v[192:193]
	v_cvt_pk_bf16_f32 v176, v170, v171
	v_cvt_pk_bf16_f32 v177, v178, v179
	v_cvt_pk_bf16_f32 v178, v182, v183
	v_lshlrev_b32_e32 v170, 16, v200
	v_cvt_pk_bf16_f32 v179, v180, v181
	global_store_dwordx4 v[168:169], v[176:179], off
	v_lshlrev_b32_e32 v180, 16, v203
	v_and_b32_e32 v181, 0xffff0000, v203
	v_lshlrev_b32_e32 v178, 16, v202
	v_and_b32_e32 v179, 0xffff0000, v202
	v_and_b32_e32 v171, 0xffff0000, v200
	v_lshlrev_b32_e32 v176, 16, v201
	v_and_b32_e32 v177, 0xffff0000, v201
	s_waitcnt vmcnt(0) lgkmcnt(0)
	v_lshlrev_b32_e32 v186, 16, v206
	v_and_b32_e32 v187, 0xffff0000, v206
	v_lshlrev_b32_e32 v188, 16, v207
	v_and_b32_e32 v189, 0xffff0000, v207
	v_lshlrev_b32_e32 v182, 16, v204
	v_and_b32_e32 v183, 0xffff0000, v204
	v_lshlrev_b32_e32 v184, 16, v205
	v_and_b32_e32 v185, 0xffff0000, v205
	v_pk_fma_f32 v[180:181], v[100:101], v[188:189], v[180:181]
	v_pk_fma_f32 v[178:179], v[98:99], v[186:187], v[178:179]
	v_add_co_u32_e32 v188, vcc, s73, v162
	v_pk_fma_f32 v[184:185], v[104:105], v[184:185], v[176:177]
	v_pk_fma_f32 v[170:171], v[102:103], v[182:183], v[170:171]
	v_addc_co_u32_e32 v189, vcc, 0, v163, vcc
	v_cvt_pk_bf16_f32 v176, v170, v171
	v_cvt_pk_bf16_f32 v177, v184, v185
	v_cvt_pk_bf16_f32 v178, v178, v179
	v_cvt_pk_bf16_f32 v179, v180, v181
	global_store_dwordx4 v[168:169], v[176:179], off offset:256
	global_load_dwordx4 v[168:171], v[188:189], off
	s_waitcnt vmcnt(0) lgkmcnt(0)
; __device__ __forceinline__ u32x4 pack8(const f32x4 a, const f32x4 b) { u32x4 w; w.x = pk2(a[0], a[1]); w.y = pk2(a[2], a[3]); w.z = pk2(b[0], b[1]); w.w = pk2(b[2], b[3]); return w; }
; __device__ __forceinline__ void unpack8(const u32x4 w, f32x4& a, f32x4& b) { a = (f32x4){bflo(w.x), bfhi(w.x), bflo(w.y), bfhi(w.y)}; b = (f32x4){bflo(w.z), bfhi(w.z), bflo(w.w), bfhi(w.w)}; }
;     __device__ __forceinline__ void operator()(const Acc& acc, const Unit& u, int wr, int wc, int fr, int fq) const {
;     ...
;         } else {
; #pragma unroll
;             for (int ai = 0; ai < 2; ++ai)
; #pragma unroll
;                 for (int mp = 0; mp < 2; ++mp) {
;                     u32x4 c[2][2], s[2][2];
; #pragma unroll
;                     for (int mm = 0; mm < 2; ++mm)
; #pragma unroll
;                         for (int bj = 0; bj < 2; ++bj) { c[mm][bj] = *MP(ai, 2 * mp + mm, bj); s[mm][bj] = *SP(ai, 2 * mp + mm, bj); }
; #pragma unroll
;                     for (int mm = 0; mm < 2; ++mm)
; #pragma unroll
;                         for (int bj = 0; bj < 2; ++bj) { const int m = 2 * mp + mm; f32x4 c0, c1, s0, s1; unpack8(c[mm][bj], c0, c1); unpack8(s[mm][bj], s0, s1);
;                             *MP(ai, m, bj) = pack8(c0 + s0 * acc[ai][bj][m][0], c1 + s1 * acc[ai][bj][m][1]); }
;                     asm volatile("" ::: "memory");
;                 }
	v_lshlrev_b32_e32 v210, 16, v168
	v_add_co_u32_e32 v176, vcc, s81, v164
	v_and_b32_e32 v211, 0xffff0000, v168
	s_nop 0
	v_addc_co_u32_e32 v177, vcc, 0, v165, vcc
	global_load_dwordx4 v[176:179], v[176:177], off
	s_nop 0
	global_load_dwordx4 v[180:183], v[188:189], off offset:256
	v_add_co_u32_e32 v184, vcc, s82, v164
	v_lshlrev_b32_e32 v168, 16, v169
	s_nop 0
	v_addc_co_u32_e32 v185, vcc, 0, v165, vcc
	global_load_dwordx4 v[184:187], v[184:185], off
	v_add_co_u32_e32 v208, vcc, s79, v162
	v_and_b32_e32 v169, 0xffff0000, v169
	s_nop 0
	v_addc_co_u32_e32 v209, vcc, 0, v163, vcc
	v_add_co_u32_e32 v196, vcc, s88, v164
	global_load_dwordx4 v[192:195], v[208:209], off
	s_nop 0
	v_addc_co_u32_e32 v197, vcc, 0, v165, vcc
	global_load_dwordx4 v[196:199], v[196:197], off
	s_nop 0
	global_load_dwordx4 v[200:203], v[208:209], off offset:256
	v_add_co_u32_e32 v204, vcc, s89, v164
	v_lshlrev_b32_e32 v212, 16, v170
	s_nop 0
	v_addc_co_u32_e32 v205, vcc, 0, v165, vcc
	global_load_dwordx4 v[204:207], v[204:205], off
	v_and_b32_e32 v213, 0xffff0000, v170
	v_lshlrev_b32_e32 v170, 16, v171
	v_and_b32_e32 v171, 0xffff0000, v171
	s_waitcnt vmcnt(0) lgkmcnt(0)
	v_lshlrev_b32_e32 v214, 16, v176
	v_and_b32_e32 v215, 0xffff0000, v176
	v_lshlrev_b32_e32 v176, 16, v177
	v_and_b32_e32 v177, 0xffff0000, v177
	v_lshlrev_b32_e32 v216, 16, v178
	v_and_b32_e32 v217, 0xffff0000, v178
	v_lshlrev_b32_e32 v178, 16, v179
	v_and_b32_e32 v179, 0xffff0000, v179
	v_pk_fma_f32 v[176:177], v[96:97], v[176:177], v[168:169]
	v_pk_fma_f32 v[168:169], v[94:95], v[214:215], v[210:211]
	v_pk_fma_f32 v[178:179], v[92:93], v[178:179], v[170:171]
	v_pk_fma_f32 v[170:171], v[90:91], v[216:217], v[212:213]
	v_cvt_pk_bf16_f32 v168, v168, v169
	v_cvt_pk_bf16_f32 v169, v176, v177
	v_lshlrev_b32_e32 v176, 16, v182
	v_cvt_pk_bf16_f32 v170, v170, v171
	v_cvt_pk_bf16_f32 v171, v178, v179
	global_store_dwordx4 v[188:189], v[168:171], off
	v_and_b32_e32 v177, 0xffff0000, v182
	v_lshlrev_b32_e32 v178, 16, v183
	v_lshlrev_b32_e32 v168, 16, v180
	v_and_b32_e32 v169, 0xffff0000, v180
	v_lshlrev_b32_e32 v170, 16, v181
	v_and_b32_e32 v171, 0xffff0000, v181
	v_and_b32_e32 v179, 0xffff0000, v183
	v_lshlrev_b32_e32 v180, 16, v184
	v_and_b32_e32 v181, 0xffff0000, v184
	v_lshlrev_b32_e32 v182, 16, v185
	v_and_b32_e32 v183, 0xffff0000, v185
	v_lshlrev_b32_e32 v184, 16, v186
	v_and_b32_e32 v185, 0xffff0000, v186
	v_lshlrev_b32_e32 v186, 16, v187
	v_and_b32_e32 v187, 0xffff0000, v187
	v_pk_fma_f32 v[170:171], v[88:89], v[182:183], v[170:171]
	v_pk_fma_f32 v[168:169], v[86:87], v[180:181], v[168:169]
	v_pk_fma_f32 v[178:179], v[84:85], v[186:187], v[178:179]
	v_pk_fma_f32 v[176:177], v[82:83], v[184:185], v[176:177]
	v_cvt_pk_bf16_f32 v168, v168, v169
	v_cvt_pk_bf16_f32 v169, v170, v171
	v_lshlrev_b32_e32 v180, 16, v196
	v_cvt_pk_bf16_f32 v170, v176, v177
	v_cvt_pk_bf16_f32 v171, v178, v179
	global_store_dwordx4 v[188:189], v[168:171], off offset:256
	v_and_b32_e32 v181, 0xffff0000, v196
	v_lshlrev_b32_e32 v182, 16, v197
	v_lshlrev_b32_e32 v168, 16, v192
	v_and_b32_e32 v169, 0xffff0000, v192
	v_lshlrev_b32_e32 v170, 16, v193
	v_and_b32_e32 v171, 0xffff0000, v193
	v_and_b32_e32 v183, 0xffff0000, v197
	v_lshlrev_b32_e32 v176, 16, v194
	v_and_b32_e32 v177, 0xffff0000, v194
	v_lshlrev_b32_e32 v178, 16, v195
	v_and_b32_e32 v179, 0xffff0000, v195
	v_lshlrev_b32_e32 v184, 16, v198
	v_and_b32_e32 v185, 0xffff0000, v198
	v_lshlrev_b32_e32 v186, 16, v199
	v_and_b32_e32 v187, 0xffff0000, v199
	v_pk_fma_f32 v[170:171], v[80:81], v[182:183], v[170:171]
	v_pk_fma_f32 v[168:169], v[78:79], v[180:181], v[168:169]
	v_pk_fma_f32 v[178:179], v[76:77], v[186:187], v[178:179]
	v_pk_fma_f32 v[176:177], v[74:75], v[184:185], v[176:177]
	v_cvt_pk_bf16_f32 v168, v168, v169
	v_cvt_pk_bf16_f32 v169, v170, v171
	v_lshlrev_b32_e32 v180, 16, v204
	v_cvt_pk_bf16_f32 v170, v176, v177
	v_cvt_pk_bf16_f32 v171, v178, v179
	global_store_dwordx4 v[208:209], v[168:171], off
	v_and_b32_e32 v181, 0xffff0000, v204
	v_lshlrev_b32_e32 v182, 16, v205
	v_lshlrev_b32_e32 v168, 16, v200
	v_and_b32_e32 v169, 0xffff0000, v200
	v_lshlrev_b32_e32 v170, 16, v201
	v_and_b32_e32 v171, 0xffff0000, v201
	v_and_b32_e32 v183, 0xffff0000, v205
	v_lshlrev_b32_e32 v176, 16, v202
	v_and_b32_e32 v177, 0xffff0000, v202
	v_lshlrev_b32_e32 v178, 16, v203
	v_and_b32_e32 v179, 0xffff0000, v203
	v_lshlrev_b32_e32 v184, 16, v206
	v_and_b32_e32 v185, 0xffff0000, v206
	v_lshlrev_b32_e32 v186, 16, v207
	v_and_b32_e32 v187, 0xffff0000, v207
	v_pk_fma_f32 v[170:171], v[72:73], v[182:183], v[170:171]
	v_pk_fma_f32 v[168:169], v[70:71], v[180:181], v[168:169]
	v_add_co_u32_e32 v188, vcc, s90, v162
	v_pk_fma_f32 v[178:179], v[68:69], v[186:187], v[178:179]
	v_pk_fma_f32 v[176:177], v[66:67], v[184:185], v[176:177]
	v_cvt_pk_bf16_f32 v168, v168, v169
	v_cvt_pk_bf16_f32 v169, v170, v171
	v_addc_co_u32_e32 v189, vcc, 0, v163, vcc
	v_cvt_pk_bf16_f32 v170, v176, v177
	v_cvt_pk_bf16_f32 v171, v178, v179
	global_store_dwordx4 v[208:209], v[168:171], off offset:256
	v_add_co_u32_e32 v176, vcc, s73, v164
	global_load_dwordx4 v[168:171], v[188:189], off
	s_nop 0
	v_addc_co_u32_e32 v177, vcc, 0, v165, vcc
	global_load_dwordx4 v[176:179], v[176:177], off
	s_nop 0
	global_load_dwordx4 v[180:183], v[188:189], off offset:256
	v_add_co_u32_e32 v184, vcc, s74, v164
	s_waitcnt vmcnt(0) lgkmcnt(0)
; __device__ __forceinline__ u32x4 pack8(const f32x4 a, const f32x4 b) { u32x4 w; w.x = pk2(a[0], a[1]); w.y = pk2(a[2], a[3]); w.z = pk2(b[0], b[1]); w.w = pk2(b[2], b[3]); return w; }
; __device__ __forceinline__ void unpack8(const u32x4 w, f32x4& a, f32x4& b) { a = (f32x4){bflo(w.x), bfhi(w.x), bflo(w.y), bfhi(w.y)}; b = (f32x4){bflo(w.z), bfhi(w.z), bflo(w.w), bfhi(w.w)}; }
;     __device__ __forceinline__ void operator()(const Acc& acc, const Unit& u, int wr, int wc, int fr, int fq) const {
;     ...
;         } else {
; #pragma unroll
;             for (int ai = 0; ai < 2; ++ai)
; #pragma unroll
;                 for (int mp = 0; mp < 2; ++mp) {
;                     u32x4 c[2][2], s[2][2];
; #pragma unroll
;                     for (int mm = 0; mm < 2; ++mm)
; #pragma unroll
;                         for (int bj = 0; bj < 2; ++bj) { c[mm][bj] = *MP(ai, 2 * mp + mm, bj); s[mm][bj] = *SP(ai, 2 * mp + mm, bj); }
; #pragma unroll
;                     for (int mm = 0; mm < 2; ++mm)
; #pragma unroll
;                         for (int bj = 0; bj < 2; ++bj) { const int m = 2 * mp + mm; f32x4 c0, c1, s0, s1; unpack8(c[mm][bj], c0, c1); unpack8(s[mm][bj], s0, s1);
;                             *MP(ai, m, bj) = pack8(c0 + s0 * acc[ai][bj][m][0], c1 + s1 * acc[ai][bj][m][1]); }
;                     asm volatile("" ::: "memory");
;                 }
	v_lshlrev_b32_e32 v210, 16, v168
	v_addc_co_u32_e32 v185, vcc, 0, v165, vcc
	global_load_dwordx4 v[184:187], v[184:185], off
	v_add_co_u32_e32 v208, vcc, s91, v162
	v_and_b32_e32 v211, 0xffff0000, v168
	s_nop 0
	v_addc_co_u32_e32 v209, vcc, 0, v163, vcc
	v_add_co_u32_e32 v196, vcc, s75, v164
	global_load_dwordx4 v[192:195], v[208:209], off
	s_nop 0
	v_addc_co_u32_e32 v197, vcc, 0, v165, vcc
	global_load_dwordx4 v[196:199], v[196:197], off
	s_nop 0
	global_load_dwordx4 v[200:203], v[208:209], off offset:256
	v_add_co_u32_e32 v204, vcc, s76, v164
	v_lshlrev_b32_e32 v168, 16, v169
	s_nop 0
	v_addc_co_u32_e32 v205, vcc, 0, v165, vcc
	global_load_dwordx4 v[204:207], v[204:205], off
	v_and_b32_e32 v169, 0xffff0000, v169
	v_lshlrev_b32_e32 v212, 16, v170
	v_and_b32_e32 v213, 0xffff0000, v170
	v_lshlrev_b32_e32 v170, 16, v171
	v_and_b32_e32 v171, 0xffff0000, v171
	v_lshlrev_b32_e32 v214, 16, v176
	v_and_b32_e32 v215, 0xffff0000, v176
	v_lshlrev_b32_e32 v176, 16, v177
	v_and_b32_e32 v177, 0xffff0000, v177
	v_lshlrev_b32_e32 v216, 16, v178
	v_and_b32_e32 v217, 0xffff0000, v178
	v_lshlrev_b32_e32 v178, 16, v179
	v_and_b32_e32 v179, 0xffff0000, v179
	v_pk_fma_f32 v[176:177], v[64:65], v[176:177], v[168:169]
	v_pk_fma_f32 v[168:169], v[62:63], v[214:215], v[210:211]
	v_pk_fma_f32 v[178:179], v[60:61], v[178:179], v[170:171]
	v_pk_fma_f32 v[170:171], v[58:59], v[216:217], v[212:213]
	v_cvt_pk_bf16_f32 v168, v168, v169
	v_cvt_pk_bf16_f32 v169, v176, v177
	v_lshlrev_b32_e32 v176, 16, v182
	v_cvt_pk_bf16_f32 v170, v170, v171
	v_cvt_pk_bf16_f32 v171, v178, v179
	global_store_dwordx4 v[188:189], v[168:171], off
	v_and_b32_e32 v177, 0xffff0000, v182
	v_lshlrev_b32_e32 v178, 16, v183
	v_lshlrev_b32_e32 v168, 16, v180
	v_and_b32_e32 v169, 0xffff0000, v180
	v_lshlrev_b32_e32 v170, 16, v181
	v_and_b32_e32 v171, 0xffff0000, v181
	v_and_b32_e32 v179, 0xffff0000, v183
	s_waitcnt vmcnt(0) lgkmcnt(0)
	v_lshlrev_b32_e32 v180, 16, v184
	v_and_b32_e32 v181, 0xffff0000, v184
	v_lshlrev_b32_e32 v182, 16, v185
	v_and_b32_e32 v183, 0xffff0000, v185
	v_lshlrev_b32_e32 v184, 16, v186
	v_and_b32_e32 v185, 0xffff0000, v186
	v_lshlrev_b32_e32 v186, 16, v187
	v_and_b32_e32 v187, 0xffff0000, v187
	v_pk_fma_f32 v[170:171], v[56:57], v[182:183], v[170:171]
	v_pk_fma_f32 v[168:169], v[54:55], v[180:181], v[168:169]
	v_pk_fma_f32 v[178:179], v[52:53], v[186:187], v[178:179]
	v_pk_fma_f32 v[176:177], v[50:51], v[184:185], v[176:177]
	v_cvt_pk_bf16_f32 v168, v168, v169
	v_cvt_pk_bf16_f32 v169, v170, v171
	v_lshlrev_b32_e32 v180, 16, v196
	v_cvt_pk_bf16_f32 v170, v176, v177
	v_cvt_pk_bf16_f32 v171, v178, v179
	global_store_dwordx4 v[188:189], v[168:171], off offset:256
	v_and_b32_e32 v181, 0xffff0000, v196
	v_lshlrev_b32_e32 v182, 16, v197
	v_lshlrev_b32_e32 v168, 16, v192
	v_and_b32_e32 v169, 0xffff0000, v192
	v_lshlrev_b32_e32 v170, 16, v193
	v_and_b32_e32 v171, 0xffff0000, v193
	v_and_b32_e32 v183, 0xffff0000, v197
	v_lshlrev_b32_e32 v176, 16, v194
	v_and_b32_e32 v177, 0xffff0000, v194
	v_lshlrev_b32_e32 v178, 16, v195
	v_and_b32_e32 v179, 0xffff0000, v195
	v_lshlrev_b32_e32 v184, 16, v198
	v_and_b32_e32 v185, 0xffff0000, v198
	v_lshlrev_b32_e32 v186, 16, v199
	v_and_b32_e32 v187, 0xffff0000, v199
	v_pk_fma_f32 v[170:171], v[48:49], v[182:183], v[170:171]
	v_pk_fma_f32 v[168:169], v[46:47], v[180:181], v[168:169]
	v_pk_fma_f32 v[178:179], v[44:45], v[186:187], v[178:179]
	v_pk_fma_f32 v[176:177], v[42:43], v[184:185], v[176:177]
	v_cvt_pk_bf16_f32 v168, v168, v169
	v_cvt_pk_bf16_f32 v169, v170, v171
	v_lshlrev_b32_e32 v180, 16, v204
	v_cvt_pk_bf16_f32 v170, v176, v177
	v_cvt_pk_bf16_f32 v171, v178, v179
	global_store_dwordx4 v[208:209], v[168:171], off
	v_and_b32_e32 v181, 0xffff0000, v204
	v_lshlrev_b32_e32 v182, 16, v205
	v_lshlrev_b32_e32 v168, 16, v200
	v_and_b32_e32 v169, 0xffff0000, v200
	v_lshlrev_b32_e32 v170, 16, v201
	v_and_b32_e32 v171, 0xffff0000, v201
	v_and_b32_e32 v183, 0xffff0000, v205
	v_lshlrev_b32_e32 v176, 16, v202
	v_and_b32_e32 v177, 0xffff0000, v202
	v_lshlrev_b32_e32 v178, 16, v203
	v_and_b32_e32 v179, 0xffff0000, v203
	v_lshlrev_b32_e32 v184, 16, v206
	v_and_b32_e32 v185, 0xffff0000, v206
	v_lshlrev_b32_e32 v186, 16, v207
	v_and_b32_e32 v187, 0xffff0000, v207
	v_pk_fma_f32 v[170:171], v[40:41], v[182:183], v[170:171]
	v_pk_fma_f32 v[168:169], v[38:39], v[180:181], v[168:169]
	v_add_co_u32_e32 v188, vcc, s92, v162
	v_pk_fma_f32 v[178:179], v[36:37], v[186:187], v[178:179]
	v_pk_fma_f32 v[176:177], v[34:35], v[184:185], v[176:177]
	v_cvt_pk_bf16_f32 v168, v168, v169
	v_cvt_pk_bf16_f32 v169, v170, v171
	v_addc_co_u32_e32 v189, vcc, 0, v163, vcc
	v_cvt_pk_bf16_f32 v170, v176, v177
	v_cvt_pk_bf16_f32 v171, v178, v179
	global_store_dwordx4 v[208:209], v[168:171], off offset:256
	v_add_co_u32_e32 v176, vcc, s79, v164
	global_load_dwordx4 v[168:171], v[188:189], off
	s_nop 0
	v_addc_co_u32_e32 v177, vcc, 0, v165, vcc
	global_load_dwordx4 v[176:179], v[176:177], off
	s_nop 0
	global_load_dwordx4 v[180:183], v[188:189], off offset:256
	v_add_co_u32_e32 v184, vcc, s80, v164
	s_waitcnt vmcnt(0) lgkmcnt(0)
; __device__ __forceinline__ u32x4 pack8(const f32x4 a, const f32x4 b) { u32x4 w; w.x = pk2(a[0], a[1]); w.y = pk2(a[2], a[3]); w.z = pk2(b[0], b[1]); w.w = pk2(b[2], b[3]); return w; }
; __device__ __forceinline__ void unpack8(const u32x4 w, f32x4& a, f32x4& b) { a = (f32x4){bflo(w.x), bfhi(w.x), bflo(w.y), bfhi(w.y)}; b = (f32x4){bflo(w.z), bfhi(w.z), bflo(w.w), bfhi(w.w)}; }
;     __device__ __forceinline__ void operator()(const Acc& acc, const Unit& u, int wr, int wc, int fr, int fq) const {
;     ...
;         } else {
; #pragma unroll
;             for (int ai = 0; ai < 2; ++ai)
; #pragma unroll
;                 for (int mp = 0; mp < 2; ++mp) {
;                     u32x4 c[2][2], s[2][2];
; #pragma unroll
;                     for (int mm = 0; mm < 2; ++mm)
; #pragma unroll
;                         for (int bj = 0; bj < 2; ++bj) { c[mm][bj] = *MP(ai, 2 * mp + mm, bj); s[mm][bj] = *SP(ai, 2 * mp + mm, bj); }
; #pragma unroll
;                     for (int mm = 0; mm < 2; ++mm)
; #pragma unroll
;                         for (int bj = 0; bj < 2; ++bj) { const int m = 2 * mp + mm; f32x4 c0, c1, s0, s1; unpack8(c[mm][bj], c0, c1); unpack8(s[mm][bj], s0, s1);
;                             *MP(ai, m, bj) = pack8(c0 + s0 * acc[ai][bj][m][0], c1 + s1 * acc[ai][bj][m][1]); }
;                     asm volatile("" ::: "memory");
;                 }
	v_lshlrev_b32_e32 v210, 16, v168
	v_addc_co_u32_e32 v185, vcc, 0, v165, vcc
	global_load_dwordx4 v[184:187], v[184:185], off
	v_add_co_u32_e32 v208, vcc, s93, v162
	v_and_b32_e32 v211, 0xffff0000, v168
	s_nop 0
	v_addc_co_u32_e32 v209, vcc, 0, v163, vcc
	v_add_co_u32_e32 v196, vcc, s83, v164
	global_load_dwordx4 v[192:195], v[208:209], off
	s_nop 0
	v_addc_co_u32_e32 v197, vcc, 0, v165, vcc
	global_load_dwordx4 v[196:199], v[196:197], off
	s_nop 0
	global_load_dwordx4 v[200:203], v[208:209], off offset:256
	v_add_co_u32_e32 v204, vcc, s84, v164
	v_lshlrev_b32_e32 v168, 16, v169
	s_nop 0
	v_addc_co_u32_e32 v205, vcc, 0, v165, vcc
	global_load_dwordx4 v[204:207], v[204:205], off
	v_and_b32_e32 v169, 0xffff0000, v169
	v_lshlrev_b32_e32 v212, 16, v170
	v_and_b32_e32 v213, 0xffff0000, v170
	v_lshlrev_b32_e32 v170, 16, v171
	v_and_b32_e32 v171, 0xffff0000, v171
	v_lshlrev_b32_e32 v214, 16, v176
	v_and_b32_e32 v215, 0xffff0000, v176
	v_lshlrev_b32_e32 v176, 16, v177
	v_and_b32_e32 v177, 0xffff0000, v177
	v_lshlrev_b32_e32 v216, 16, v178
	v_and_b32_e32 v217, 0xffff0000, v178
	v_lshlrev_b32_e32 v178, 16, v179
	v_and_b32_e32 v179, 0xffff0000, v179
	v_pk_fma_f32 v[176:177], v[32:33], v[176:177], v[168:169]
	v_pk_fma_f32 v[168:169], v[30:31], v[214:215], v[210:211]
	v_pk_fma_f32 v[178:179], v[28:29], v[178:179], v[170:171]
	v_pk_fma_f32 v[170:171], v[26:27], v[216:217], v[212:213]
	v_cvt_pk_bf16_f32 v168, v168, v169
	v_cvt_pk_bf16_f32 v169, v176, v177
	v_lshlrev_b32_e32 v176, 16, v182
	v_cvt_pk_bf16_f32 v170, v170, v171
	v_cvt_pk_bf16_f32 v171, v178, v179
	global_store_dwordx4 v[188:189], v[168:171], off
	v_and_b32_e32 v177, 0xffff0000, v182
	v_lshlrev_b32_e32 v178, 16, v183
	v_lshlrev_b32_e32 v168, 16, v180
	v_and_b32_e32 v169, 0xffff0000, v180
	v_lshlrev_b32_e32 v170, 16, v181
	v_and_b32_e32 v171, 0xffff0000, v181
	v_and_b32_e32 v179, 0xffff0000, v183
	s_waitcnt vmcnt(0) lgkmcnt(0)
	v_lshlrev_b32_e32 v180, 16, v184
	v_and_b32_e32 v181, 0xffff0000, v184
	v_lshlrev_b32_e32 v182, 16, v185
	v_and_b32_e32 v183, 0xffff0000, v185
	v_lshlrev_b32_e32 v184, 16, v186
	v_and_b32_e32 v185, 0xffff0000, v186
	v_lshlrev_b32_e32 v186, 16, v187
	v_and_b32_e32 v187, 0xffff0000, v187
	v_pk_fma_f32 v[170:171], v[24:25], v[182:183], v[170:171]
	v_pk_fma_f32 v[168:169], v[22:23], v[180:181], v[168:169]
	v_pk_fma_f32 v[178:179], v[20:21], v[186:187], v[178:179]
	v_pk_fma_f32 v[176:177], v[18:19], v[184:185], v[176:177]
	v_cvt_pk_bf16_f32 v168, v168, v169
	v_cvt_pk_bf16_f32 v169, v170, v171
	v_lshlrev_b32_e32 v180, 16, v196
	v_cvt_pk_bf16_f32 v170, v176, v177
	v_cvt_pk_bf16_f32 v171, v178, v179
	global_store_dwordx4 v[188:189], v[168:171], off offset:256
	v_and_b32_e32 v181, 0xffff0000, v196
	v_lshlrev_b32_e32 v182, 16, v197
	v_lshlrev_b32_e32 v168, 16, v192
	v_and_b32_e32 v169, 0xffff0000, v192
	v_lshlrev_b32_e32 v170, 16, v193
	v_and_b32_e32 v171, 0xffff0000, v193
	v_and_b32_e32 v183, 0xffff0000, v197
	v_lshlrev_b32_e32 v176, 16, v194
	v_and_b32_e32 v177, 0xffff0000, v194
	v_lshlrev_b32_e32 v178, 16, v195
	v_and_b32_e32 v179, 0xffff0000, v195
	v_lshlrev_b32_e32 v184, 16, v198
	v_and_b32_e32 v185, 0xffff0000, v198
	v_lshlrev_b32_e32 v186, 16, v199
	v_and_b32_e32 v187, 0xffff0000, v199
	v_pk_fma_f32 v[170:171], v[16:17], v[182:183], v[170:171]
	v_pk_fma_f32 v[168:169], v[14:15], v[180:181], v[168:169]
	v_pk_fma_f32 v[178:179], v[12:13], v[186:187], v[178:179]
	v_pk_fma_f32 v[176:177], v[10:11], v[184:185], v[176:177]
	v_cvt_pk_bf16_f32 v168, v168, v169
	v_cvt_pk_bf16_f32 v169, v170, v171
	v_lshlrev_b32_e32 v180, 16, v204
	v_cvt_pk_bf16_f32 v170, v176, v177
	v_cvt_pk_bf16_f32 v171, v178, v179
	global_store_dwordx4 v[208:209], v[168:171], off
	v_and_b32_e32 v181, 0xffff0000, v204
	v_lshlrev_b32_e32 v182, 16, v205
	v_lshlrev_b32_e32 v168, 16, v200
	v_and_b32_e32 v169, 0xffff0000, v200
	v_lshlrev_b32_e32 v170, 16, v201
	v_and_b32_e32 v171, 0xffff0000, v201
	v_and_b32_e32 v183, 0xffff0000, v205
	v_lshlrev_b32_e32 v176, 16, v202
	v_and_b32_e32 v177, 0xffff0000, v202
	v_lshlrev_b32_e32 v178, 16, v203
	v_and_b32_e32 v179, 0xffff0000, v203
	v_lshlrev_b32_e32 v184, 16, v206
	v_and_b32_e32 v185, 0xffff0000, v206
	v_lshlrev_b32_e32 v186, 16, v207
	v_and_b32_e32 v187, 0xffff0000, v207
	v_pk_fma_f32 v[170:171], v[8:9], v[182:183], v[170:171]
	v_pk_fma_f32 v[168:169], v[6:7], v[180:181], v[168:169]
	v_pk_fma_f32 v[178:179], v[4:5], v[186:187], v[178:179]
	v_pk_fma_f32 v[176:177], v[2:3], v[184:185], v[176:177]
	v_cvt_pk_bf16_f32 v168, v168, v169
	v_cvt_pk_bf16_f32 v169, v170, v171
	s_nop 0
	v_cvt_pk_bf16_f32 v170, v176, v177
	v_cvt_pk_bf16_f32 v171, v178, v179
	global_store_dwordx4 v[208:209], v[168:171], off offset:256
; __device__ __forceinline__ u32x4 pack8(const f32x4 a, const f32x4 b) { u32x4 w; w.x = pk2(a[0], a[1]); w.y = pk2(a[2], a[3]); w.z = pk2(b[0], b[1]); w.w = pk2(b[2], b[3]); return w; }
; __device__ __forceinline__ void unpack8(const u32x4 w, f32x4& a, f32x4& b) { a = (f32x4){bflo(w.x), bfhi(w.x), bflo(w.y), bfhi(w.y)}; b = (f32x4){bflo(w.z), bfhi(w.z), bflo(w.w), bfhi(w.w)}; }
;     __device__ __forceinline__ void operator()(const Acc& acc, const Unit& u, int wr, int wc, int fr, int fq) const {
;     ...
;         } else if (sub == 1) {
; #pragma unroll
;             for (int ai = 0; ai < 2; ++ai) {
;                 u32x4 g[4][2];
; #pragma unroll
;                 for (int m = 0; m < 4; ++m)
; #pragma unroll
;                     for (int bj = 0; bj < 2; ++bj) g[m][bj] = *MP(ai, m, bj);
; #pragma unroll
;                 for (int m = 0; m < 4; ++m)
; #pragma unroll
;                     for (int bj = 0; bj < 2; ++bj) { f32x4 g0, g1; unpack8(g[m][bj], g0, g1); *MP(ai, m, bj) = pack8(g0 * acc[ai][bj][m][0], g1 * acc[ai][bj][m][1]); }
;                 asm volatile("" ::: "memory");
;             }
.LBB0_1128:
	s_andn2_b64 vcc, exec, s[4:5]
	s_cbranch_vccnz .LBB0_1130
	global_load_dwordx4 v[176:179], v[162:163], off offset:256
	v_add_co_u32_e32 v170, vcc, 0x8000, v162
	v_pk_mul_f32 v[208:209], v[124:125], v[134:135]
	s_nop 0
	v_addc_co_u32_e32 v171, vcc, 0, v163, vcc
	global_load_dwordx4 v[180:183], v[170:171], off
	global_load_dwordx4 v[184:187], v[170:171], off offset:256
	v_add_co_u32_e32 v168, vcc, 0x10000, v162
	v_pk_mul_f32 v[188:189], v[126:127], v[132:133]
	s_nop 0
	v_addc_co_u32_e32 v169, vcc, 0, v163, vcc
	global_load_dwordx4 v[192:195], v[168:169], off
	global_load_dwordx4 v[196:199], v[168:169], off offset:256
	v_add_co_u32_e32 v134, vcc, 0x18000, v162
	v_pk_mul_f32 v[206:207], v[122:123], v[130:131]
	s_nop 0
	v_addc_co_u32_e32 v135, vcc, 0, v163, vcc
	global_load_dwordx4 v[200:203], v[134:135], off
	global_load_dwordx4 v[130:133], v[134:135], off offset:256
	v_pk_mul_f32 v[136:137], v[128:129], v[136:137]
	v_cvt_pk_bf16_f32 v204, v188, v189
	s_waitcnt vmcnt(0) lgkmcnt(0)
	v_lshlrev_b32_e32 v188, 16, v178
	v_cvt_pk_bf16_f32 v205, v136, v137
	v_cvt_pk_bf16_f32 v206, v206, v207
	v_cvt_pk_bf16_f32 v207, v208, v209
	v_lshlrev_b32_e32 v136, 16, v176
	v_and_b32_e32 v137, 0xffff0000, v176
	v_and_b32_e32 v189, 0xffff0000, v178
	v_lshlrev_b32_e32 v178, 16, v179
	v_and_b32_e32 v179, 0xffff0000, v179
	global_store_dwordx4 v[162:163], v[204:207], off
	v_lshlrev_b32_e32 v176, 16, v177
	v_and_b32_e32 v177, 0xffff0000, v177
	v_pk_mul_f32 v[136:137], v[118:119], v[136:137]
	v_pk_mul_f32 v[206:207], v[116:117], v[178:179]
	v_pk_mul_f32 v[178:179], v[114:115], v[188:189]
	v_pk_mul_f32 v[204:205], v[120:121], v[176:177]
	v_cvt_pk_bf16_f32 v176, v136, v137
	v_lshlrev_b32_e32 v136, 16, v180
	v_cvt_pk_bf16_f32 v177, v204, v205
	v_cvt_pk_bf16_f32 v178, v178, v179
	v_cvt_pk_bf16_f32 v179, v206, v207
	v_and_b32_e32 v137, 0xffff0000, v180
	v_lshlrev_b32_e32 v180, 16, v181
	v_and_b32_e32 v181, 0xffff0000, v181
	v_lshlrev_b32_e32 v188, 16, v182
	v_and_b32_e32 v189, 0xffff0000, v182
	v_lshlrev_b32_e32 v182, 16, v183
	v_and_b32_e32 v183, 0xffff0000, v183
	global_store_dwordx4 v[162:163], v[176:179], off offset:256
	v_lshlrev_b32_e32 v204, 16, v184
	v_and_b32_e32 v205, 0xffff0000, v184
	v_pk_mul_f32 v[178:179], v[112:113], v[180:181]
	v_lshlrev_b32_e32 v184, 16, v185
	v_and_b32_e32 v185, 0xffff0000, v185
	v_lshlrev_b32_e32 v206, 16, v186
	v_and_b32_e32 v207, 0xffff0000, v186
	v_lshlrev_b32_e32 v186, 16, v187
	v_and_b32_e32 v187, 0xffff0000, v187
	v_pk_mul_f32 v[136:137], v[110:111], v[136:137]
	v_pk_mul_f32 v[180:181], v[108:109], v[182:183]
	v_pk_mul_f32 v[182:183], v[106:107], v[188:189]
	v_cvt_pk_bf16_f32 v176, v136, v137
	v_cvt_pk_bf16_f32 v177, v178, v179
	v_pk_mul_f32 v[184:185], v[104:105], v[184:185]
	v_cvt_pk_bf16_f32 v178, v182, v183
	v_cvt_pk_bf16_f32 v179, v180, v181
	v_pk_mul_f32 v[188:189], v[102:103], v[204:205]
	v_pk_mul_f32 v[186:187], v[100:101], v[186:187]
	v_pk_mul_f32 v[204:205], v[98:99], v[206:207]
	v_lshlrev_b32_e32 v206, 16, v192
	v_and_b32_e32 v207, 0xffff0000, v192
	v_lshlrev_b32_e32 v208, 16, v194
	global_store_dwordx4 v[170:171], v[176:179], off
	v_and_b32_e32 v209, 0xffff0000, v194
	v_lshlrev_b32_e32 v192, 16, v193
	v_cvt_pk_bf16_f32 v176, v188, v189
	v_cvt_pk_bf16_f32 v177, v184, v185
	v_cvt_pk_bf16_f32 v178, v204, v205
	v_cvt_pk_bf16_f32 v179, v186, v187
	v_and_b32_e32 v193, 0xffff0000, v193
	global_store_dwordx4 v[170:171], v[176:179], off offset:256
	v_lshlrev_b32_e32 v136, 16, v195
	v_and_b32_e32 v137, 0xffff0000, v195
	v_pk_mul_f32 v[176:177], v[94:95], v[206:207]
	v_pk_mul_f32 v[178:179], v[90:91], v[208:209]
	v_pk_mul_f32 v[170:171], v[96:97], v[192:193]
	v_pk_mul_f32 v[136:137], v[92:93], v[136:137]
	v_cvt_pk_bf16_f32 v176, v176, v177
	v_cvt_pk_bf16_f32 v177, v170, v171
	v_cvt_pk_bf16_f32 v178, v178, v179
	v_lshlrev_b32_e32 v170, 16, v197
	v_cvt_pk_bf16_f32 v179, v136, v137
	global_store_dwordx4 v[168:169], v[176:179], off
	v_lshlrev_b32_e32 v136, 16, v196
	v_and_b32_e32 v137, 0xffff0000, v196
	v_and_b32_e32 v171, 0xffff0000, v197
	v_lshlrev_b32_e32 v176, 16, v198
	v_and_b32_e32 v177, 0xffff0000, v198
	v_lshlrev_b32_e32 v178, 16, v199
	v_and_b32_e32 v179, 0xffff0000, v199
	v_pk_mul_f32 v[170:171], v[88:89], v[170:171]
	v_pk_mul_f32 v[136:137], v[86:87], v[136:137]
	v_pk_mul_f32 v[180:181], v[84:85], v[178:179]
	v_pk_mul_f32 v[178:179], v[82:83], v[176:177]
	v_cvt_pk_bf16_f32 v176, v136, v137
	v_cvt_pk_bf16_f32 v177, v170, v171
	v_lshlrev_b32_e32 v136, 16, v200
	v_cvt_pk_bf16_f32 v178, v178, v179
	v_cvt_pk_bf16_f32 v179, v180, v181
	global_store_dwordx4 v[168:169], v[176:179], off offset:256
	v_and_b32_e32 v137, 0xffff0000, v200
	v_lshlrev_b32_e32 v168, 16, v201
	v_and_b32_e32 v169, 0xffff0000, v201
	v_lshlrev_b32_e32 v170, 16, v202
	v_and_b32_e32 v171, 0xffff0000, v202
	v_lshlrev_b32_e32 v176, 16, v203
	v_and_b32_e32 v177, 0xffff0000, v203
	v_pk_mul_f32 v[178:179], v[80:81], v[168:169]
	v_pk_mul_f32 v[136:137], v[78:79], v[136:137]
	v_pk_mul_f32 v[170:171], v[74:75], v[170:171]
	v_cvt_pk_bf16_f32 v168, v136, v137
	v_cvt_pk_bf16_f32 v169, v178, v179
	v_pk_mul_f32 v[176:177], v[76:77], v[176:177]
	v_cvt_pk_bf16_f32 v170, v170, v171
	v_lshlrev_b32_e32 v136, 16, v130
	v_cvt_pk_bf16_f32 v171, v176, v177
	global_store_dwordx4 v[134:135], v[168:171], off
	v_and_b32_e32 v137, 0xffff0000, v130
	v_lshlrev_b32_e32 v130, 16, v131
	v_and_b32_e32 v131, 0xffff0000, v131
	v_lshlrev_b32_e32 v168, 16, v132
	v_and_b32_e32 v169, 0xffff0000, v132
	v_lshlrev_b32_e32 v132, 16, v133
	v_and_b32_e32 v133, 0xffff0000, v133
	v_pk_mul_f32 v[170:171], v[72:73], v[130:131]
	v_pk_mul_f32 v[130:131], v[70:71], v[136:137]
	v_pk_mul_f32 v[136:137], v[68:69], v[132:133]
	v_pk_mul_f32 v[132:133], v[66:67], v[168:169]
	v_cvt_pk_bf16_f32 v130, v130, v131
	v_cvt_pk_bf16_f32 v131, v170, v171
	v_add_co_u32_e32 v188, vcc, s90, v162
	v_cvt_pk_bf16_f32 v132, v132, v133
	v_cvt_pk_bf16_f32 v133, v136, v137
	global_store_dwordx4 v[134:135], v[130:133], off offset:256
	s_nop 0
	v_addc_co_u32_e32 v189, vcc, 0, v163, vcc
	global_load_dwordx4 v[176:179], v[188:189], off
	global_load_dwordx4 v[180:183], v[188:189], off offset:256
	v_add_co_u32_e32 v204, vcc, s91, v162
	s_waitcnt vmcnt(0) lgkmcnt(0)
; __device__ __forceinline__ u32x4 pack8(const f32x4 a, const f32x4 b) { u32x4 w; w.x = pk2(a[0], a[1]); w.y = pk2(a[2], a[3]); w.z = pk2(b[0], b[1]); w.w = pk2(b[2], b[3]); return w; }
; __device__ __forceinline__ void unpack8(const u32x4 w, f32x4& a, f32x4& b) { a = (f32x4){bflo(w.x), bfhi(w.x), bflo(w.y), bfhi(w.y)}; b = (f32x4){bflo(w.z), bfhi(w.z), bflo(w.w), bfhi(w.w)}; }
;     __device__ __forceinline__ void operator()(const Acc& acc, const Unit& u, int wr, int wc, int fr, int fq) const {
;     ...
;         } else if (sub == 1) {
; #pragma unroll
;             for (int ai = 0; ai < 2; ++ai) {
;                 u32x4 g[4][2];
; #pragma unroll
;                 for (int m = 0; m < 4; ++m)
; #pragma unroll
;                     for (int bj = 0; bj < 2; ++bj) g[m][bj] = *MP(ai, m, bj);
; #pragma unroll
;                 for (int m = 0; m < 4; ++m)
; #pragma unroll
;                     for (int bj = 0; bj < 2; ++bj) { f32x4 g0, g1; unpack8(g[m][bj], g0, g1); *MP(ai, m, bj) = pack8(g0 * acc[ai][bj][m][0], g1 * acc[ai][bj][m][1]); }
;                 asm volatile("" ::: "memory");
;             }
	v_lshlrev_b32_e32 v206, 16, v176
	v_addc_co_u32_e32 v205, vcc, 0, v163, vcc
	global_load_dwordx4 v[184:187], v[204:205], off
	global_load_dwordx4 v[192:195], v[204:205], off offset:256
	v_add_co_u32_e32 v170, vcc, s92, v162
	v_and_b32_e32 v207, 0xffff0000, v176
	s_nop 0
	v_addc_co_u32_e32 v171, vcc, 0, v163, vcc
	global_load_dwordx4 v[196:199], v[170:171], off
	global_load_dwordx4 v[200:203], v[170:171], off offset:256
	v_add_co_u32_e32 v168, vcc, s93, v162
	v_lshlrev_b32_e32 v176, 16, v177
	s_nop 0
	v_addc_co_u32_e32 v169, vcc, 0, v163, vcc
	global_load_dwordx4 v[134:137], v[168:169], off
	global_load_dwordx4 v[130:133], v[168:169], off offset:256
	v_and_b32_e32 v177, 0xffff0000, v177
	v_lshlrev_b32_e32 v208, 16, v178
	v_and_b32_e32 v209, 0xffff0000, v178
	v_lshlrev_b32_e32 v178, 16, v179
	v_and_b32_e32 v179, 0xffff0000, v179
	v_pk_mul_f32 v[210:211], v[64:65], v[176:177]
	v_pk_mul_f32 v[176:177], v[62:63], v[206:207]
	v_pk_mul_f32 v[206:207], v[60:61], v[178:179]
	v_pk_mul_f32 v[178:179], v[58:59], v[208:209]
	v_cvt_pk_bf16_f32 v176, v176, v177
	v_cvt_pk_bf16_f32 v177, v210, v211
	s_nop 0
	v_cvt_pk_bf16_f32 v178, v178, v179
	v_cvt_pk_bf16_f32 v179, v206, v207
	global_store_dwordx4 v[188:189], v[176:179], off
	s_nop 1
	v_lshlrev_b32_e32 v176, 16, v180
	v_and_b32_e32 v177, 0xffff0000, v180
	v_lshlrev_b32_e32 v178, 16, v181
	v_and_b32_e32 v179, 0xffff0000, v181
	v_pk_mul_f32 v[176:177], v[54:55], v[176:177]
	v_lshlrev_b32_e32 v180, 16, v182
	v_and_b32_e32 v181, 0xffff0000, v182
	v_lshlrev_b32_e32 v182, 16, v183
	v_and_b32_e32 v183, 0xffff0000, v183
	v_pk_mul_f32 v[178:179], v[56:57], v[178:179]
	v_cvt_pk_bf16_f32 v176, v176, v177
	v_pk_mul_f32 v[182:183], v[52:53], v[182:183]
	v_cvt_pk_bf16_f32 v177, v178, v179
	v_pk_mul_f32 v[180:181], v[50:51], v[180:181]
	s_nop 0
	v_cvt_pk_bf16_f32 v178, v180, v181
	v_cvt_pk_bf16_f32 v179, v182, v183
	global_store_dwordx4 v[188:189], v[176:179], off offset:256
	s_waitcnt vmcnt(0) lgkmcnt(0)
	v_lshlrev_b32_e32 v180, 16, v186
	v_lshlrev_b32_e32 v176, 16, v184
	v_and_b32_e32 v177, 0xffff0000, v184
	v_lshlrev_b32_e32 v178, 16, v185
	v_and_b32_e32 v179, 0xffff0000, v185
	v_pk_mul_f32 v[176:177], v[46:47], v[176:177]
	v_and_b32_e32 v181, 0xffff0000, v186
	v_lshlrev_b32_e32 v182, 16, v187
	v_and_b32_e32 v183, 0xffff0000, v187
	v_pk_mul_f32 v[178:179], v[48:49], v[178:179]
	v_cvt_pk_bf16_f32 v176, v176, v177
	v_pk_mul_f32 v[182:183], v[44:45], v[182:183]
	v_cvt_pk_bf16_f32 v177, v178, v179
	v_pk_mul_f32 v[180:181], v[42:43], v[180:181]
	s_nop 0
	v_cvt_pk_bf16_f32 v178, v180, v181
	v_cvt_pk_bf16_f32 v179, v182, v183
	global_store_dwordx4 v[204:205], v[176:179], off
	v_lshlrev_b32_e32 v180, 16, v194
	v_and_b32_e32 v181, 0xffff0000, v194
	v_lshlrev_b32_e32 v176, 16, v192
	v_and_b32_e32 v177, 0xffff0000, v192
	v_lshlrev_b32_e32 v178, 16, v193
	v_and_b32_e32 v179, 0xffff0000, v193
	v_pk_mul_f32 v[176:177], v[38:39], v[176:177]
	v_lshlrev_b32_e32 v182, 16, v195
	v_and_b32_e32 v183, 0xffff0000, v195
	v_pk_mul_f32 v[178:179], v[40:41], v[178:179]
	v_cvt_pk_bf16_f32 v176, v176, v177
	v_pk_mul_f32 v[182:183], v[36:37], v[182:183]
	v_cvt_pk_bf16_f32 v177, v178, v179
	v_pk_mul_f32 v[180:181], v[34:35], v[180:181]
	s_nop 0
	v_cvt_pk_bf16_f32 v178, v180, v181
	v_cvt_pk_bf16_f32 v179, v182, v183
	global_store_dwordx4 v[204:205], v[176:179], off offset:256
	v_lshlrev_b32_e32 v180, 16, v198
	v_and_b32_e32 v181, 0xffff0000, v198
	v_lshlrev_b32_e32 v176, 16, v196
	v_and_b32_e32 v177, 0xffff0000, v196
	v_lshlrev_b32_e32 v178, 16, v197
	v_and_b32_e32 v179, 0xffff0000, v197
	v_pk_mul_f32 v[176:177], v[30:31], v[176:177]
	v_lshlrev_b32_e32 v182, 16, v199
	v_and_b32_e32 v183, 0xffff0000, v199
	v_pk_mul_f32 v[178:179], v[32:33], v[178:179]
	v_cvt_pk_bf16_f32 v176, v176, v177
	v_pk_mul_f32 v[182:183], v[28:29], v[182:183]
	v_cvt_pk_bf16_f32 v177, v178, v179
	v_pk_mul_f32 v[180:181], v[26:27], v[180:181]
	s_nop 0
	v_cvt_pk_bf16_f32 v178, v180, v181
	v_cvt_pk_bf16_f32 v179, v182, v183
	global_store_dwordx4 v[170:171], v[176:179], off
	v_lshlrev_b32_e32 v180, 16, v202
	v_and_b32_e32 v181, 0xffff0000, v202
	v_lshlrev_b32_e32 v176, 16, v200
	v_and_b32_e32 v177, 0xffff0000, v200
	v_lshlrev_b32_e32 v178, 16, v201
	v_and_b32_e32 v179, 0xffff0000, v201
	v_pk_mul_f32 v[176:177], v[22:23], v[176:177]
	v_lshlrev_b32_e32 v182, 16, v203
	v_and_b32_e32 v183, 0xffff0000, v203
	v_pk_mul_f32 v[178:179], v[24:25], v[178:179]
	v_cvt_pk_bf16_f32 v176, v176, v177
	v_pk_mul_f32 v[182:183], v[20:21], v[182:183]
	v_cvt_pk_bf16_f32 v177, v178, v179
	v_pk_mul_f32 v[180:181], v[18:19], v[180:181]
	s_nop 0
	v_cvt_pk_bf16_f32 v178, v180, v181
	v_cvt_pk_bf16_f32 v179, v182, v183
	global_store_dwordx4 v[170:171], v[176:179], off offset:256
	v_lshlrev_b32_e32 v170, 16, v134
	v_and_b32_e32 v171, 0xffff0000, v134
	v_lshlrev_b32_e32 v134, 16, v135
	v_and_b32_e32 v135, 0xffff0000, v135
	v_lshlrev_b32_e32 v176, 16, v136
	v_and_b32_e32 v177, 0xffff0000, v136
	v_lshlrev_b32_e32 v136, 16, v137
	v_and_b32_e32 v137, 0xffff0000, v137
	v_pk_mul_f32 v[178:179], v[16:17], v[134:135]
	v_pk_mul_f32 v[134:135], v[14:15], v[170:171]
	v_pk_mul_f32 v[170:171], v[12:13], v[136:137]
	v_pk_mul_f32 v[136:137], v[10:11], v[176:177]
	v_cvt_pk_bf16_f32 v134, v134, v135
	v_cvt_pk_bf16_f32 v135, v178, v179
	s_nop 0
	v_cvt_pk_bf16_f32 v136, v136, v137
	v_cvt_pk_bf16_f32 v137, v170, v171
	global_store_dwordx4 v[168:169], v[134:137], off
	s_nop 1
	v_lshlrev_b32_e32 v134, 16, v130
	v_and_b32_e32 v135, 0xffff0000, v130
	v_lshlrev_b32_e32 v130, 16, v131
	v_and_b32_e32 v131, 0xffff0000, v131
	v_lshlrev_b32_e32 v136, 16, v132
	v_and_b32_e32 v137, 0xffff0000, v132
	v_lshlrev_b32_e32 v132, 16, v133
	v_and_b32_e32 v133, 0xffff0000, v133
	v_pk_mul_f32 v[170:171], v[8:9], v[130:131]
	v_pk_mul_f32 v[130:131], v[6:7], v[134:135]
	v_pk_mul_f32 v[134:135], v[4:5], v[132:133]
	v_pk_mul_f32 v[132:133], v[2:3], v[136:137]
	v_cvt_pk_bf16_f32 v130, v130, v131
	v_cvt_pk_bf16_f32 v131, v170, v171
	s_nop 0
	v_cvt_pk_bf16_f32 v132, v132, v133
	v_cvt_pk_bf16_f32 v133, v134, v135
	global_store_dwordx4 v[168:169], v[130:133], off offset:256

; __device__ __forceinline__ float xsum16(float s) { const auto r = __builtin_amdgcn_permlane16_swap(__float_as_uint(s), __float_as_uint(s), false, false); return __uint_as_float(r[0]) + __uint_as_float(r[1]); }
; __device__ __forceinline__ float xsum32(float s) { const auto r = __builtin_amdgcn_permlane32_swap(__float_as_uint(s), __float_as_uint(s), false, false); return __uint_as_float(r[0]) + __uint_as_float(r[1]); }
; __device__ __forceinline__ float sigmoidf_(float x) { return __builtin_amdgcn_rcpf(1.0f + __builtin_amdgcn_exp2f(-1.4426950408889634f * x)); }
; __device__ __forceinline__ u32x4 pack8(const f32x4 a, const f32x4 b) { u32x4 w; w.x = pk2(a[0], a[1]); w.y = pk2(a[2], a[3]); w.z = pk2(b[0], b[1]); w.w = pk2(b[2], b[3]); return w; }
; __device__ __forceinline__ void rstd8(const float* ssq, int row0, int fq, float (&rs)[8]) {
;     f32x4 pr[8];
; #pragma unroll
;     for (int i = 0; i < 8; ++i) pr[i] = *(const f32x4*)(ssq + (size_t)(row0 + (i >> 2) * 128 + (i & 3) * 16) * 16 + 4 * fq);
; #pragma unroll
;     for (int i = 0; i < 8; ++i) { float s = (pr[i][0] + pr[i][1]) + (pr[i][2] + pr[i][3]); s = xsum16(s); s = xsum32(s); rs[i] = __builtin_amdgcn_rsqf(s * (1.0f / DM) + NORM_EPS); }
; }
;     __device__ __forceinline__ void operator()(const Acc& acc, const Unit& u, int wr, int wc, int fr, int fq) const {
;     ...
;         if ((sub & 1) == 0) {
;             float rs[8]; rstd8(ssq, row0, fq, rs);
; #pragma unroll
;             for (int ai = 0; ai < 2; ++ai)
; #pragma unroll
;                 for (int m = 0; m < 4; ++m) {
;                     const float r1 = rs[ai * 4 + m];
; #pragma unroll
;                     for (int bj = 0; bj < 2; ++bj) {
;                         f32x4 s0, s1; const f32x4 v0 = acc[ai][bj][m][0], v1 = acc[ai][bj][m][1];
; #pragma unroll
;                         for (int e = 0; e < 4; ++e) { s0[e] = sigmoidf_(v0[e] * r1); s1[e] = sigmoidf_(v1[e] * r1); }
;                         if (sub == 0) *MP(ai, m, bj) = pack8(s0, s1); else *SP(ai, m, bj) = pack8(s0, s1);
;                     }
;                 }
.LBB0_1131:
	s_andn2_b64 vcc, exec, s[4:5]
	s_cbranch_vccnz .LBB0_1180
	v_lshlrev_b64 v[130:131], 6, v[166:167]
	v_lshl_add_u64 v[168:169], v[152:153], 0, v[130:131]
	v_or_b32_e32 v130, 16, v166
	v_ashrrev_i32_e32 v131, 31, v130
	v_lshlrev_b64 v[130:131], 6, v[130:131]
	v_lshl_add_u64 v[134:135], v[152:153], 0, v[130:131]
	v_add_co_u32_e32 v188, vcc, s72, v168
	global_load_dwordx4 v[130:133], v[168:169], off
	s_nop 0
	global_load_dwordx4 v[134:137], v[134:135], off
	v_addc_co_u32_e32 v189, vcc, 0, v169, vcc
	global_load_dwordx4 v[168:171], v[188:189], off
	global_load_dwordx4 v[176:179], v[188:189], off offset:1024
	v_or_b32_e32 v180, 32, v166
	v_ashrrev_i32_e32 v181, 31, v180
	v_lshlrev_b64 v[184:185], 6, v[180:181]
	global_load_dwordx4 v[180:183], v[188:189], off offset:2048
	v_or_b32_e32 v166, 48, v166
	v_ashrrev_i32_e32 v167, 31, v166
	v_lshl_add_u64 v[184:185], v[152:153], 0, v[184:185]
	v_lshlrev_b64 v[166:167], 6, v[166:167]
	global_load_dwordx4 v[184:187], v[184:185], off
	v_lshl_add_u64 v[166:167], v[152:153], 0, v[166:167]
	global_load_dwordx4 v[192:195], v[166:167], off
	global_load_dwordx4 v[196:199], v[188:189], off offset:3072
	s_cmp_lg_u32 s55, 0
	s_cselect_b64 s[54:55], -1, 0
	s_and_b64 vcc, exec, s[54:55]
	s_waitcnt vmcnt(0)
	v_add_f32_e32 v130, v130, v131
	v_add_f32_e32 v131, v132, v133
	v_add_f32_e32 v130, v130, v131
	v_add_f32_e32 v134, v134, v135
	v_add_f32_e32 v131, v168, v169
	v_mov_b32_e32 v169, v130
	s_nop 1
	v_permlane16_swap_b32_e32 v130, v169
	v_add_f32_e32 v130, v130, v169
	v_add_f32_e32 v133, v176, v177
	v_mov_b32_e32 v176, v130
	s_nop 1
	v_permlane32_swap_b32_e32 v130, v176
	v_add_f32_e32 v130, v130, v176
	v_fmamk_f32 v130, v130, 0x3a800000, v175
	v_rsq_f32_e32 v176, v130
	v_add_f32_e32 v132, v170, v171
	v_add_f32_e32 v166, v178, v179
	v_add_f32_e32 v167, v180, v181
	v_mul_f32_e32 v126, v126, v176
	v_mul_f32_e32 v122, v122, v176
	v_mul_f32_e32 v126, 0xbfb8aa3b, v126
	v_mul_f32_e32 v122, 0xbfb8aa3b, v122
	v_exp_f32_e32 v126, v126
	v_exp_f32_e32 v177, v122
	v_mul_f32_e32 v127, v127, v176
	v_mul_f32_e32 v123, v123, v176
	v_mul_f32_e32 v127, 0xbfb8aa3b, v127
	v_mul_f32_e32 v123, 0xbfb8aa3b, v123
	v_add_f32_e32 v122, 1.0, v126
	v_add_f32_e32 v126, 1.0, v177
	v_exp_f32_e32 v127, v127
	v_exp_f32_e32 v177, v123
	v_mul_f32_e32 v128, v128, v176
	v_mul_f32_e32 v124, v124, v176
	v_mul_f32_e32 v128, 0xbfb8aa3b, v128
	v_mul_f32_e32 v124, 0xbfb8aa3b, v124
	v_rcp_f32_e32 v123, v126
	v_add_f32_e32 v126, 1.0, v127
	v_add_f32_e32 v127, 1.0, v177
	v_exp_f32_e32 v128, v128
	v_exp_f32_e32 v177, v124
	v_mul_f32_e32 v129, v129, v176
	v_add_f32_e32 v168, v182, v183
	v_mul_f32_e32 v129, 0xbfb8aa3b, v129
	v_mul_f32_e32 v125, v125, v176
	v_add_f32_e32 v135, v136, v137
	v_add_f32_e32 v131, v131, v132
	v_add_f32_e32 v132, v133, v166
	v_add_f32_e32 v133, v167, v168
	v_exp_f32_e32 v129, v129
	v_mul_f32_e32 v125, 0xbfb8aa3b, v125
	v_add_f32_e32 v135, v134, v135
	v_mov_b32_e32 v134, v131
	v_mov_b32_e32 v167, v132
	v_mov_b32_e32 v130, v133
	v_rcp_f32_e32 v124, v127
	v_add_f32_e32 v127, 1.0, v128
	v_add_f32_e32 v128, 1.0, v177
	v_exp_f32_e32 v177, v125
	v_add_f32_e32 v136, v184, v185
	v_add_f32_e32 v137, v186, v187
	v_permlane16_swap_b32_e32 v131, v134
	v_permlane16_swap_b32_e32 v132, v167
	v_permlane16_swap_b32_e32 v133, v130
	v_add_f32_e32 v170, v192, v193
	v_add_f32_e32 v171, v194, v195
	v_add_f32_e32 v137, v136, v137
	v_add_f32_e32 v136, v131, v134
	v_add_f32_e32 v134, v132, v167
	v_add_f32_e32 v132, v133, v130
	v_add_f32_e32 v130, v196, v197
	v_add_f32_e32 v131, v198, v199
	v_add_f32_e32 v166, v170, v171
	v_add_f32_e32 v130, v130, v131
	v_rcp_f32_e32 v125, v128
	v_add_f32_e32 v128, 1.0, v129
	v_mov_b32_e32 v168, v135
	v_mov_b32_e32 v169, v137
	v_mov_b32_e32 v171, v166
	v_mov_b32_e32 v131, v130
	v_rcp_f32_e32 v129, v128
	v_add_f32_e32 v128, 1.0, v177
	v_permlane16_swap_b32_e32 v135, v168
	v_permlane16_swap_b32_e32 v137, v169
	v_permlane16_swap_b32_e32 v166, v171
	v_permlane16_swap_b32_e32 v130, v131
	v_rcp_f32_e32 v122, v122
	v_rcp_f32_e32 v126, v126
	v_rcp_f32_e32 v127, v127
	v_rcp_f32_e32 v128, v128
	v_add_f32_e32 v170, v135, v168
	v_add_f32_e32 v168, v137, v169
	v_add_f32_e32 v166, v166, v171
	v_add_f32_e32 v130, v130, v131
	v_mov_b32_e32 v137, v136
	v_mov_b32_e32 v135, v134
	v_mov_b32_e32 v171, v170
	v_mov_b32_e32 v169, v168
	v_mov_b32_e32 v167, v166
	v_mov_b32_e32 v133, v132
	v_mov_b32_e32 v131, v130
	v_permlane32_swap_b32_e32 v136, v137
	v_permlane32_swap_b32_e32 v134, v135
	v_permlane32_swap_b32_e32 v170, v171
	v_permlane32_swap_b32_e32 v168, v169
	v_permlane32_swap_b32_e32 v166, v167
	v_permlane32_swap_b32_e32 v132, v133
	v_permlane32_swap_b32_e32 v130, v131
	s_cbranch_vccz .LBB0_1183
	v_cvt_pk_bf16_f32 v178, v122, v126
	v_cvt_pk_bf16_f32 v179, v127, v129
	v_cvt_pk_bf16_f32 v180, v123, v124
	v_cvt_pk_bf16_f32 v181, v125, v128
	global_store_dwordx4 v[164:165], v[178:181], off
	s_cbranch_execnz .LBB0_1135
.LBB0_1134:
	s_nop 0
	v_cvt_pk_bf16_f32 v178, v122, v126
	v_cvt_pk_bf16_f32 v179, v127, v129
	v_cvt_pk_bf16_f32 v180, v123, v124
	v_cvt_pk_bf16_f32 v181, v125, v128
	global_store_dwordx4 v[162:163], v[178:181], off
; __device__ __forceinline__ float sigmoidf_(float x) { return __builtin_amdgcn_rcpf(1.0f + __builtin_amdgcn_exp2f(-1.4426950408889634f * x)); }
; __device__ __forceinline__ u32x4 pack8(const f32x4 a, const f32x4 b) { u32x4 w; w.x = pk2(a[0], a[1]); w.y = pk2(a[2], a[3]); w.z = pk2(b[0], b[1]); w.w = pk2(b[2], b[3]); return w; }
;     __device__ __forceinline__ void operator()(const Acc& acc, const Unit& u, int wr, int wc, int fr, int fq) const {
;     ...
;         if ((sub & 1) == 0) {
;             float rs[8]; rstd8(ssq, row0, fq, rs);
; #pragma unroll
;             for (int ai = 0; ai < 2; ++ai)
; #pragma unroll
;                 for (int m = 0; m < 4; ++m) {
;                     const float r1 = rs[ai * 4 + m];
; #pragma unroll
;                     for (int bj = 0; bj < 2; ++bj) {
;                         f32x4 s0, s1; const f32x4 v0 = acc[ai][bj][m][0], v1 = acc[ai][bj][m][1];
; #pragma unroll
;                         for (int e = 0; e < 4; ++e) { s0[e] = sigmoidf_(v0[e] * r1); s1[e] = sigmoidf_(v1[e] * r1); }
;                         if (sub == 0) *MP(ai, m, bj) = pack8(s0, s1); else *SP(ai, m, bj) = pack8(s0, s1);
;                     }
;                 }
.LBB0_1135:
	v_mul_f32_e32 v118, v118, v176
	v_mul_f32_e32 v114, v114, v176
	v_mul_f32_e32 v118, 0xbfb8aa3b, v118
	v_mul_f32_e32 v114, 0xbfb8aa3b, v114
	v_exp_f32_e32 v118, v118
	v_exp_f32_e32 v122, v114
	v_mul_f32_e32 v119, v119, v176
	v_mul_f32_e32 v115, v115, v176
	v_mul_f32_e32 v119, 0xbfb8aa3b, v119
	v_mul_f32_e32 v115, 0xbfb8aa3b, v115
	v_add_f32_e32 v114, 1.0, v118
	v_add_f32_e32 v118, 1.0, v122
	v_exp_f32_e32 v119, v119
	v_exp_f32_e32 v122, v115
	v_mul_f32_e32 v120, v120, v176
	v_mul_f32_e32 v116, v116, v176
	v_mul_f32_e32 v120, 0xbfb8aa3b, v120
	v_mul_f32_e32 v116, 0xbfb8aa3b, v116
	v_rcp_f32_e32 v115, v118
	v_add_f32_e32 v118, 1.0, v119
	v_add_f32_e32 v119, 1.0, v122
	v_exp_f32_e32 v120, v120
	v_exp_f32_e32 v122, v116
	v_mul_f32_e32 v121, v121, v176
	v_mul_f32_e32 v121, 0xbfb8aa3b, v121
	v_mul_f32_e32 v117, v117, v176
	v_exp_f32_e32 v121, v121
	v_mul_f32_e32 v117, 0xbfb8aa3b, v117
	v_rcp_f32_e32 v116, v119
	v_add_f32_e32 v119, 1.0, v120
	v_add_f32_e32 v120, 1.0, v122
	v_exp_f32_e32 v122, v117
	v_rcp_f32_e32 v117, v120
	v_add_f32_e32 v120, 1.0, v121
	v_rcp_f32_e32 v121, v120
	v_add_f32_e32 v120, 1.0, v122
	v_rcp_f32_e32 v114, v114
	v_rcp_f32_e32 v118, v118
	v_rcp_f32_e32 v119, v119
	v_rcp_f32_e32 v120, v120
	v_cndmask_b32_e64 v122, 0, 1, s[54:55]
	v_cmp_ne_u32_e64 s[4:5], 1, v122
	s_andn2_b64 vcc, exec, s[54:55]
	s_cbranch_vccnz .LBB0_1184
	v_add_co_u32_e32 v126, vcc, 0x2000, v164
	s_nop 1
	v_addc_co_u32_e32 v127, vcc, 0, v165, vcc
	v_cvt_pk_bf16_f32 v122, v114, v118
	v_cvt_pk_bf16_f32 v123, v119, v121
	v_cvt_pk_bf16_f32 v124, v115, v116
	v_cvt_pk_bf16_f32 v125, v117, v120
	global_store_dwordx4 v[126:127], v[122:125], off
	s_cbranch_execnz .LBB0_1138
.LBB0_1137:
	s_nop 0
	v_cvt_pk_bf16_f32 v122, v114, v118
	v_cvt_pk_bf16_f32 v123, v119, v121
	v_cvt_pk_bf16_f32 v124, v115, v116
	v_cvt_pk_bf16_f32 v125, v117, v120
	global_store_dwordx4 v[162:163], v[122:125], off offset:256
.LBB0_1138:
	v_add_f32_e32 v114, v170, v171
	v_fmamk_f32 v114, v114, 0x3a800000, v175
	v_rsq_f32_e32 v114, v114
	s_and_b64 vcc, exec, s[4:5]
	v_mul_f32_e32 v110, v110, v114
	v_mul_f32_e32 v106, v106, v114
	v_mul_f32_e32 v110, 0xbfb8aa3b, v110
	v_mul_f32_e32 v106, 0xbfb8aa3b, v106
	v_exp_f32_e32 v110, v110
	v_exp_f32_e32 v106, v106
	v_mul_f32_e32 v111, v111, v114
	v_mul_f32_e32 v107, v107, v114
	v_mul_f32_e32 v111, 0xbfb8aa3b, v111
	v_add_f32_e32 v110, 1.0, v110
	v_mul_f32_e32 v107, 0xbfb8aa3b, v107
	v_mul_f32_e32 v112, v112, v114
	v_mul_f32_e32 v108, v108, v114
	v_add_f32_e32 v115, 1.0, v106
	v_rcp_f32_e32 v106, v110
	v_exp_f32_e32 v110, v111
	v_exp_f32_e32 v111, v107
	v_mul_f32_e32 v112, 0xbfb8aa3b, v112
	v_mul_f32_e32 v108, 0xbfb8aa3b, v108
	v_rcp_f32_e32 v107, v115
	v_exp_f32_e32 v112, v112
	v_exp_f32_e32 v115, v108
	v_mul_f32_e32 v113, v113, v114
	v_mul_f32_e32 v113, 0xbfb8aa3b, v113
	v_mul_f32_e32 v109, v109, v114
	v_add_f32_e32 v111, 1.0, v111
	v_exp_f32_e32 v113, v113
	v_mul_f32_e32 v109, 0xbfb8aa3b, v109
	v_rcp_f32_e32 v108, v111
	v_add_f32_e32 v111, 1.0, v112
	v_add_f32_e32 v112, 1.0, v115
	v_exp_f32_e32 v115, v109
	v_rcp_f32_e32 v109, v112
	v_add_f32_e32 v112, 1.0, v113
	v_add_f32_e32 v110, 1.0, v110
	v_rcp_f32_e32 v113, v112
	v_add_f32_e32 v112, 1.0, v115
	v_rcp_f32_e32 v110, v110
	v_rcp_f32_e32 v111, v111
	v_rcp_f32_e32 v112, v112
	s_cbranch_vccnz .LBB0_1185
	v_add_co_u32_e32 v120, vcc, 0x4000, v164
	s_nop 1
	v_addc_co_u32_e32 v121, vcc, 0, v165, vcc
	v_cvt_pk_bf16_f32 v116, v106, v110
	v_cvt_pk_bf16_f32 v117, v111, v113
	v_cvt_pk_bf16_f32 v118, v107, v108
	v_cvt_pk_bf16_f32 v119, v109, v112
	global_store_dwordx4 v[120:121], v[116:119], off
	s_cbranch_execnz .LBB0_1141
.LBB0_1140:
	s_nop 0
	v_cvt_pk_bf16_f32 v116, v106, v110
	v_add_co_u32_e32 v106, vcc, 0x8000, v162
	v_cvt_pk_bf16_f32 v117, v111, v113
	v_cvt_pk_bf16_f32 v118, v107, v108
	v_cvt_pk_bf16_f32 v119, v109, v112
	s_nop 1
	v_addc_co_u32_e32 v107, vcc, 0, v163, vcc
	global_store_dwordx4 v[106:107], v[116:119], off
.LBB0_1141:
	v_mul_f32_e32 v102, v102, v114
	v_mul_f32_e32 v98, v98, v114
	v_mul_f32_e32 v102, 0xbfb8aa3b, v102
	v_mul_f32_e32 v98, 0xbfb8aa3b, v98
	v_exp_f32_e32 v102, v102
	v_exp_f32_e32 v106, v98
	v_mul_f32_e32 v103, v103, v114
	v_mul_f32_e32 v99, v99, v114
	v_mul_f32_e32 v103, 0xbfb8aa3b, v103
	v_mul_f32_e32 v99, 0xbfb8aa3b, v99
	v_add_f32_e32 v98, 1.0, v102
	v_add_f32_e32 v102, 1.0, v106
	v_exp_f32_e32 v103, v103
	v_exp_f32_e32 v106, v99
	v_mul_f32_e32 v104, v104, v114
	v_mul_f32_e32 v100, v100, v114
	v_mul_f32_e32 v104, 0xbfb8aa3b, v104
	v_mul_f32_e32 v100, 0xbfb8aa3b, v100
	v_rcp_f32_e32 v99, v102
	v_add_f32_e32 v102, 1.0, v103
	v_add_f32_e32 v103, 1.0, v106
	v_exp_f32_e32 v104, v104
	v_exp_f32_e32 v106, v100
	v_mul_f32_e32 v105, v105, v114
	v_mul_f32_e32 v105, 0xbfb8aa3b, v105
	v_mul_f32_e32 v101, v101, v114
	v_exp_f32_e32 v105, v105
	v_mul_f32_e32 v101, 0xbfb8aa3b, v101
	v_rcp_f32_e32 v100, v103
	v_add_f32_e32 v103, 1.0, v104
	v_add_f32_e32 v104, 1.0, v106
	v_exp_f32_e32 v106, v101
	v_rcp_f32_e32 v101, v104
	v_add_f32_e32 v104, 1.0, v105
	v_rcp_f32_e32 v105, v104
	v_add_f32_e32 v104, 1.0, v106
	v_rcp_f32_e32 v98, v98
	v_rcp_f32_e32 v102, v102
	v_rcp_f32_e32 v103, v103
	v_rcp_f32_e32 v104, v104
	s_and_b64 vcc, exec, s[4:5]
	s_cbranch_vccnz .LBB0_1186
	v_add_co_u32_e32 v110, vcc, 0x6000, v164
	s_nop 1
	v_addc_co_u32_e32 v111, vcc, 0, v165, vcc
	v_cvt_pk_bf16_f32 v106, v98, v102
	v_cvt_pk_bf16_f32 v107, v103, v105
	v_cvt_pk_bf16_f32 v108, v99, v100
	v_cvt_pk_bf16_f32 v109, v101, v104
	global_store_dwordx4 v[110:111], v[106:109], off
	s_cbranch_execnz .LBB0_1144
; __device__ __forceinline__ float sigmoidf_(float x) { return __builtin_amdgcn_rcpf(1.0f + __builtin_amdgcn_exp2f(-1.4426950408889634f * x)); }
; __device__ __forceinline__ u32x4 pack8(const f32x4 a, const f32x4 b) { u32x4 w; w.x = pk2(a[0], a[1]); w.y = pk2(a[2], a[3]); w.z = pk2(b[0], b[1]); w.w = pk2(b[2], b[3]); return w; }
;     __device__ __forceinline__ void operator()(const Acc& acc, const Unit& u, int wr, int wc, int fr, int fq) const {
;     ...
;         if ((sub & 1) == 0) {
;             float rs[8]; rstd8(ssq, row0, fq, rs);
; #pragma unroll
;             for (int ai = 0; ai < 2; ++ai)
; #pragma unroll
;                 for (int m = 0; m < 4; ++m) {
;                     const float r1 = rs[ai * 4 + m];
; #pragma unroll
;                     for (int bj = 0; bj < 2; ++bj) {
;                         f32x4 s0, s1; const f32x4 v0 = acc[ai][bj][m][0], v1 = acc[ai][bj][m][1];
; #pragma unroll
;                         for (int e = 0; e < 4; ++e) { s0[e] = sigmoidf_(v0[e] * r1); s1[e] = sigmoidf_(v1[e] * r1); }
;                         if (sub == 0) *MP(ai, m, bj) = pack8(s0, s1); else *SP(ai, m, bj) = pack8(s0, s1);
;                     }
;                 }
.LBB0_1143:
	s_nop 0
	v_cvt_pk_bf16_f32 v106, v98, v102
	v_add_co_u32_e32 v98, vcc, 0x8000, v162
	v_cvt_pk_bf16_f32 v107, v103, v105
	v_cvt_pk_bf16_f32 v108, v99, v100
	v_cvt_pk_bf16_f32 v109, v101, v104
	s_nop 1
	v_addc_co_u32_e32 v99, vcc, 0, v163, vcc
	global_store_dwordx4 v[98:99], v[106:109], off offset:256
.LBB0_1144:
	v_add_f32_e32 v98, v168, v169
	v_fmamk_f32 v98, v98, 0x3a800000, v175
	v_rsq_f32_e32 v98, v98
	s_and_b64 vcc, exec, s[4:5]
	v_mul_f32_e32 v94, v94, v98
	v_mul_f32_e32 v90, v90, v98
	v_mul_f32_e32 v94, 0xbfb8aa3b, v94
	v_mul_f32_e32 v90, 0xbfb8aa3b, v90
	v_exp_f32_e32 v94, v94
	v_exp_f32_e32 v90, v90
	v_mul_f32_e32 v95, v95, v98
	v_mul_f32_e32 v91, v91, v98
	v_mul_f32_e32 v95, 0xbfb8aa3b, v95
	v_add_f32_e32 v94, 1.0, v94
	v_mul_f32_e32 v91, 0xbfb8aa3b, v91
	v_mul_f32_e32 v96, v96, v98
	v_mul_f32_e32 v92, v92, v98
	v_add_f32_e32 v99, 1.0, v90
	v_rcp_f32_e32 v90, v94
	v_exp_f32_e32 v94, v95
	v_exp_f32_e32 v95, v91
	v_mul_f32_e32 v96, 0xbfb8aa3b, v96
	v_mul_f32_e32 v92, 0xbfb8aa3b, v92
	v_rcp_f32_e32 v91, v99
	v_exp_f32_e32 v96, v96
	v_exp_f32_e32 v99, v92
	v_mul_f32_e32 v97, v97, v98
	v_mul_f32_e32 v97, 0xbfb8aa3b, v97
	v_mul_f32_e32 v93, v93, v98
	v_add_f32_e32 v95, 1.0, v95
	v_exp_f32_e32 v97, v97
	v_mul_f32_e32 v93, 0xbfb8aa3b, v93
	v_rcp_f32_e32 v92, v95
	v_add_f32_e32 v95, 1.0, v96
	v_add_f32_e32 v96, 1.0, v99
	v_exp_f32_e32 v99, v93
	v_rcp_f32_e32 v93, v96
	v_add_f32_e32 v96, 1.0, v97
	v_add_f32_e32 v94, 1.0, v94
	v_rcp_f32_e32 v97, v96
	v_add_f32_e32 v96, 1.0, v99
	v_rcp_f32_e32 v94, v94
	v_rcp_f32_e32 v95, v95
	v_rcp_f32_e32 v96, v96
	s_cbranch_vccnz .LBB0_1187
	v_add_co_u32_e32 v104, vcc, 0x8000, v164
	s_nop 1
	v_addc_co_u32_e32 v105, vcc, 0, v165, vcc
	v_cvt_pk_bf16_f32 v100, v90, v94
	v_cvt_pk_bf16_f32 v101, v95, v97
	v_cvt_pk_bf16_f32 v102, v91, v92
	v_cvt_pk_bf16_f32 v103, v93, v96
	global_store_dwordx4 v[104:105], v[100:103], off
	s_cbranch_execnz .LBB0_1147
.LBB0_1146:
	s_nop 0
	v_cvt_pk_bf16_f32 v100, v90, v94
	v_add_co_u32_e32 v90, vcc, 0x10000, v162
	v_cvt_pk_bf16_f32 v101, v95, v97
	v_cvt_pk_bf16_f32 v102, v91, v92
	v_cvt_pk_bf16_f32 v103, v93, v96
	s_nop 1
	v_addc_co_u32_e32 v91, vcc, 0, v163, vcc
	global_store_dwordx4 v[90:91], v[100:103], off
.LBB0_1147:
	v_mul_f32_e32 v86, v86, v98
	v_mul_f32_e32 v82, v82, v98
	v_mul_f32_e32 v86, 0xbfb8aa3b, v86
	v_mul_f32_e32 v82, 0xbfb8aa3b, v82
	v_exp_f32_e32 v86, v86
	v_exp_f32_e32 v90, v82
	v_mul_f32_e32 v87, v87, v98
	v_mul_f32_e32 v83, v83, v98
	v_mul_f32_e32 v87, 0xbfb8aa3b, v87
	v_mul_f32_e32 v83, 0xbfb8aa3b, v83
	v_add_f32_e32 v82, 1.0, v86
	v_add_f32_e32 v86, 1.0, v90
	v_exp_f32_e32 v87, v87
	v_exp_f32_e32 v90, v83
	v_mul_f32_e32 v88, v88, v98
	v_mul_f32_e32 v84, v84, v98
	v_mul_f32_e32 v88, 0xbfb8aa3b, v88
	v_mul_f32_e32 v84, 0xbfb8aa3b, v84
	v_rcp_f32_e32 v83, v86
	v_add_f32_e32 v86, 1.0, v87
	v_add_f32_e32 v87, 1.0, v90
	v_exp_f32_e32 v88, v88
	v_exp_f32_e32 v90, v84
	v_mul_f32_e32 v89, v89, v98
	v_mul_f32_e32 v89, 0xbfb8aa3b, v89
	v_mul_f32_e32 v85, v85, v98
	v_exp_f32_e32 v89, v89
	v_mul_f32_e32 v85, 0xbfb8aa3b, v85
	v_rcp_f32_e32 v84, v87
	v_add_f32_e32 v87, 1.0, v88
	v_add_f32_e32 v88, 1.0, v90
	v_exp_f32_e32 v90, v85
	v_rcp_f32_e32 v85, v88
	v_add_f32_e32 v88, 1.0, v89
	v_rcp_f32_e32 v89, v88
	v_add_f32_e32 v88, 1.0, v90
	v_rcp_f32_e32 v82, v82
	v_rcp_f32_e32 v86, v86
	v_rcp_f32_e32 v87, v87
	v_rcp_f32_e32 v88, v88
	s_and_b64 vcc, exec, s[4:5]
	s_cbranch_vccnz .LBB0_1188
	v_add_co_u32_e32 v94, vcc, 0xa000, v164
	s_nop 1
	v_addc_co_u32_e32 v95, vcc, 0, v165, vcc
	v_cvt_pk_bf16_f32 v90, v82, v86
	v_cvt_pk_bf16_f32 v91, v87, v89
	v_cvt_pk_bf16_f32 v92, v83, v84
	v_cvt_pk_bf16_f32 v93, v85, v88
	global_store_dwordx4 v[94:95], v[90:93], off
	s_cbranch_execnz .LBB0_1150
.LBB0_1149:
	s_nop 0
	v_cvt_pk_bf16_f32 v90, v82, v86
	v_add_co_u32_e32 v82, vcc, 0x10000, v162
	v_cvt_pk_bf16_f32 v91, v87, v89
	v_cvt_pk_bf16_f32 v92, v83, v84
	v_cvt_pk_bf16_f32 v93, v85, v88
	s_nop 1
	v_addc_co_u32_e32 v83, vcc, 0, v163, vcc
	global_store_dwordx4 v[82:83], v[90:93], off offset:256
.LBB0_1150:
	v_add_f32_e32 v82, v166, v167
	v_fmamk_f32 v82, v82, 0x3a800000, v175
	v_rsq_f32_e32 v82, v82
	s_and_b64 vcc, exec, s[4:5]
	v_mul_f32_e32 v78, v78, v82
	v_mul_f32_e32 v74, v74, v82
	v_mul_f32_e32 v78, 0xbfb8aa3b, v78
	v_mul_f32_e32 v74, 0xbfb8aa3b, v74
	v_exp_f32_e32 v78, v78
	v_exp_f32_e32 v74, v74
	v_mul_f32_e32 v79, v79, v82
	v_mul_f32_e32 v75, v75, v82
	v_mul_f32_e32 v79, 0xbfb8aa3b, v79
	v_add_f32_e32 v78, 1.0, v78
	v_mul_f32_e32 v75, 0xbfb8aa3b, v75
	v_mul_f32_e32 v80, v80, v82
	v_mul_f32_e32 v76, v76, v82
	v_add_f32_e32 v83, 1.0, v74
	v_rcp_f32_e32 v74, v78
	v_exp_f32_e32 v78, v79
	v_exp_f32_e32 v79, v75
	v_mul_f32_e32 v80, 0xbfb8aa3b, v80
	v_mul_f32_e32 v76, 0xbfb8aa3b, v76
	v_rcp_f32_e32 v75, v83
	v_exp_f32_e32 v80, v80
	v_exp_f32_e32 v83, v76
	v_mul_f32_e32 v81, v81, v82
	v_mul_f32_e32 v81, 0xbfb8aa3b, v81
	v_mul_f32_e32 v77, v77, v82
	v_add_f32_e32 v79, 1.0, v79
	v_exp_f32_e32 v81, v81
	v_mul_f32_e32 v77, 0xbfb8aa3b, v77
	v_rcp_f32_e32 v76, v79
	v_add_f32_e32 v79, 1.0, v80
	v_add_f32_e32 v80, 1.0, v83
	v_exp_f32_e32 v83, v77
	v_rcp_f32_e32 v77, v80
	v_add_f32_e32 v80, 1.0, v81
	v_add_f32_e32 v78, 1.0, v78
	v_rcp_f32_e32 v81, v80
	v_add_f32_e32 v80, 1.0, v83
	v_rcp_f32_e32 v78, v78
	v_rcp_f32_e32 v79, v79
	v_rcp_f32_e32 v80, v80
	s_cbranch_vccnz .LBB0_1189
	v_add_co_u32_e32 v88, vcc, 0xc000, v164
	s_nop 1
	v_addc_co_u32_e32 v89, vcc, 0, v165, vcc
	v_cvt_pk_bf16_f32 v84, v74, v78
	v_cvt_pk_bf16_f32 v85, v79, v81
	v_cvt_pk_bf16_f32 v86, v75, v76
	v_cvt_pk_bf16_f32 v87, v77, v80
	global_store_dwordx4 v[88:89], v[84:87], off
	s_cbranch_execnz .LBB0_1153
; __device__ __forceinline__ float sigmoidf_(float x) { return __builtin_amdgcn_rcpf(1.0f + __builtin_amdgcn_exp2f(-1.4426950408889634f * x)); }
; __device__ __forceinline__ u32x4 pack8(const f32x4 a, const f32x4 b) { u32x4 w; w.x = pk2(a[0], a[1]); w.y = pk2(a[2], a[3]); w.z = pk2(b[0], b[1]); w.w = pk2(b[2], b[3]); return w; }
;     __device__ __forceinline__ void operator()(const Acc& acc, const Unit& u, int wr, int wc, int fr, int fq) const {
;     ...
;         if ((sub & 1) == 0) {
;             float rs[8]; rstd8(ssq, row0, fq, rs);
; #pragma unroll
;             for (int ai = 0; ai < 2; ++ai)
; #pragma unroll
;                 for (int m = 0; m < 4; ++m) {
;                     const float r1 = rs[ai * 4 + m];
; #pragma unroll
;                     for (int bj = 0; bj < 2; ++bj) {
;                         f32x4 s0, s1; const f32x4 v0 = acc[ai][bj][m][0], v1 = acc[ai][bj][m][1];
; #pragma unroll
;                         for (int e = 0; e < 4; ++e) { s0[e] = sigmoidf_(v0[e] * r1); s1[e] = sigmoidf_(v1[e] * r1); }
;                         if (sub == 0) *MP(ai, m, bj) = pack8(s0, s1); else *SP(ai, m, bj) = pack8(s0, s1);
;                     }
;                 }
.LBB0_1152:
	s_nop 0
	v_cvt_pk_bf16_f32 v84, v74, v78
	v_add_co_u32_e32 v74, vcc, 0x18000, v162
	v_cvt_pk_bf16_f32 v85, v79, v81
	v_cvt_pk_bf16_f32 v86, v75, v76
	v_cvt_pk_bf16_f32 v87, v77, v80
	s_nop 1
	v_addc_co_u32_e32 v75, vcc, 0, v163, vcc
	global_store_dwordx4 v[74:75], v[84:87], off
.LBB0_1153:
	v_mul_f32_e32 v70, v70, v82
	v_mul_f32_e32 v66, v66, v82
	v_mul_f32_e32 v70, 0xbfb8aa3b, v70
	v_mul_f32_e32 v66, 0xbfb8aa3b, v66
	v_exp_f32_e32 v70, v70
	v_exp_f32_e32 v74, v66
	v_mul_f32_e32 v71, v71, v82
	v_mul_f32_e32 v67, v67, v82
	v_mul_f32_e32 v71, 0xbfb8aa3b, v71
	v_mul_f32_e32 v67, 0xbfb8aa3b, v67
	v_add_f32_e32 v66, 1.0, v70
	v_add_f32_e32 v70, 1.0, v74
	v_exp_f32_e32 v71, v71
	v_exp_f32_e32 v74, v67
	v_mul_f32_e32 v72, v72, v82
	v_mul_f32_e32 v68, v68, v82
	v_mul_f32_e32 v72, 0xbfb8aa3b, v72
	v_mul_f32_e32 v68, 0xbfb8aa3b, v68
	v_rcp_f32_e32 v67, v70
	v_add_f32_e32 v70, 1.0, v71
	v_add_f32_e32 v71, 1.0, v74
	v_exp_f32_e32 v72, v72
	v_exp_f32_e32 v74, v68
	v_mul_f32_e32 v73, v73, v82
	v_mul_f32_e32 v73, 0xbfb8aa3b, v73
	v_mul_f32_e32 v69, v69, v82
	v_exp_f32_e32 v73, v73
	v_mul_f32_e32 v69, 0xbfb8aa3b, v69
	v_rcp_f32_e32 v68, v71
	v_add_f32_e32 v71, 1.0, v72
	v_add_f32_e32 v72, 1.0, v74
	v_exp_f32_e32 v74, v69
	v_rcp_f32_e32 v69, v72
	v_add_f32_e32 v72, 1.0, v73
	v_rcp_f32_e32 v73, v72
	v_add_f32_e32 v72, 1.0, v74
	v_rcp_f32_e32 v66, v66
	v_rcp_f32_e32 v70, v70
	v_rcp_f32_e32 v71, v71
	v_rcp_f32_e32 v72, v72
	s_and_b64 vcc, exec, s[4:5]
	s_cbranch_vccnz .LBB0_1190
	v_add_co_u32_e32 v78, vcc, 0xe000, v164
	s_nop 1
	v_addc_co_u32_e32 v79, vcc, 0, v165, vcc
	v_cvt_pk_bf16_f32 v74, v66, v70
	v_cvt_pk_bf16_f32 v75, v71, v73
	v_cvt_pk_bf16_f32 v76, v67, v68
	v_cvt_pk_bf16_f32 v77, v69, v72
	global_store_dwordx4 v[78:79], v[74:77], off
	s_cbranch_execnz .LBB0_1156
.LBB0_1155:
	s_nop 0
	v_cvt_pk_bf16_f32 v74, v66, v70
	v_add_co_u32_e32 v66, vcc, 0x18000, v162
	v_cvt_pk_bf16_f32 v75, v71, v73
	v_cvt_pk_bf16_f32 v76, v67, v68
	v_cvt_pk_bf16_f32 v77, v69, v72
	s_nop 1
	v_addc_co_u32_e32 v67, vcc, 0, v163, vcc
	global_store_dwordx4 v[66:67], v[74:77], off offset:256
.LBB0_1156:
	v_add_f32_e32 v66, v136, v137
	v_fmamk_f32 v66, v66, 0x3a800000, v175
	v_rsq_f32_e32 v66, v66
	s_and_b64 vcc, exec, s[4:5]
	v_mul_f32_e32 v62, v62, v66
	v_mul_f32_e32 v58, v58, v66
	v_mul_f32_e32 v62, 0xbfb8aa3b, v62
	v_mul_f32_e32 v58, 0xbfb8aa3b, v58
	v_exp_f32_e32 v62, v62
	v_exp_f32_e32 v58, v58
	v_mul_f32_e32 v63, v63, v66
	v_mul_f32_e32 v59, v59, v66
	v_mul_f32_e32 v63, 0xbfb8aa3b, v63
	v_add_f32_e32 v62, 1.0, v62
	v_mul_f32_e32 v59, 0xbfb8aa3b, v59
	v_mul_f32_e32 v64, v64, v66
	v_mul_f32_e32 v60, v60, v66
	v_add_f32_e32 v67, 1.0, v58
	v_rcp_f32_e32 v58, v62
	v_exp_f32_e32 v62, v63
	v_exp_f32_e32 v63, v59
	v_mul_f32_e32 v64, 0xbfb8aa3b, v64
	v_mul_f32_e32 v60, 0xbfb8aa3b, v60
	v_rcp_f32_e32 v59, v67
	v_exp_f32_e32 v64, v64
	v_exp_f32_e32 v67, v60
	v_mul_f32_e32 v65, v65, v66
	v_mul_f32_e32 v65, 0xbfb8aa3b, v65
	v_mul_f32_e32 v61, v61, v66
	v_add_f32_e32 v63, 1.0, v63
	v_exp_f32_e32 v65, v65
	v_mul_f32_e32 v61, 0xbfb8aa3b, v61
	v_rcp_f32_e32 v60, v63
	v_add_f32_e32 v63, 1.0, v64
	v_add_f32_e32 v64, 1.0, v67
	v_exp_f32_e32 v67, v61
	v_rcp_f32_e32 v61, v64
	v_add_f32_e32 v64, 1.0, v65
	v_add_f32_e32 v62, 1.0, v62
	v_rcp_f32_e32 v65, v64
	v_add_f32_e32 v64, 1.0, v67
	v_rcp_f32_e32 v62, v62
	v_rcp_f32_e32 v63, v63
	v_rcp_f32_e32 v64, v64
	s_cbranch_vccnz .LBB0_1191
	v_add_co_u32_e32 v72, vcc, 0x10000, v164
	s_nop 1
	v_addc_co_u32_e32 v73, vcc, 0, v165, vcc
	v_cvt_pk_bf16_f32 v68, v58, v62
	v_cvt_pk_bf16_f32 v69, v63, v65
	v_cvt_pk_bf16_f32 v70, v59, v60
	v_cvt_pk_bf16_f32 v71, v61, v64
	global_store_dwordx4 v[72:73], v[68:71], off
	s_cbranch_execnz .LBB0_1159
.LBB0_1158:
	s_nop 0
	v_cvt_pk_bf16_f32 v68, v58, v62
	v_add_co_u32_e32 v58, vcc, 0x40000, v162
	v_cvt_pk_bf16_f32 v69, v63, v65
	v_cvt_pk_bf16_f32 v70, v59, v60
	v_cvt_pk_bf16_f32 v71, v61, v64
	s_nop 1
	v_addc_co_u32_e32 v59, vcc, 0, v163, vcc
	global_store_dwordx4 v[58:59], v[68:71], off
.LBB0_1159:
	v_mul_f32_e32 v54, v54, v66
	v_mul_f32_e32 v50, v50, v66
	v_mul_f32_e32 v54, 0xbfb8aa3b, v54
	v_mul_f32_e32 v50, 0xbfb8aa3b, v50
	v_exp_f32_e32 v54, v54
	v_exp_f32_e32 v58, v50
	v_mul_f32_e32 v55, v55, v66
	v_mul_f32_e32 v51, v51, v66
	v_mul_f32_e32 v55, 0xbfb8aa3b, v55
	v_mul_f32_e32 v51, 0xbfb8aa3b, v51
	v_add_f32_e32 v50, 1.0, v54
	v_add_f32_e32 v54, 1.0, v58
	v_exp_f32_e32 v55, v55
	v_exp_f32_e32 v58, v51
	v_mul_f32_e32 v56, v56, v66
	v_mul_f32_e32 v52, v52, v66
	v_mul_f32_e32 v56, 0xbfb8aa3b, v56
	v_mul_f32_e32 v52, 0xbfb8aa3b, v52
	v_rcp_f32_e32 v51, v54
	v_add_f32_e32 v54, 1.0, v55
	v_add_f32_e32 v55, 1.0, v58
	v_exp_f32_e32 v56, v56
	v_exp_f32_e32 v58, v52
	v_mul_f32_e32 v57, v57, v66
	v_mul_f32_e32 v57, 0xbfb8aa3b, v57
	v_mul_f32_e32 v53, v53, v66
	v_exp_f32_e32 v57, v57
	v_mul_f32_e32 v53, 0xbfb8aa3b, v53
	v_rcp_f32_e32 v52, v55
	v_add_f32_e32 v55, 1.0, v56
	v_add_f32_e32 v56, 1.0, v58
	v_exp_f32_e32 v58, v53
	v_rcp_f32_e32 v53, v56
	v_add_f32_e32 v56, 1.0, v57
	v_rcp_f32_e32 v57, v56
	v_add_f32_e32 v56, 1.0, v58
	v_rcp_f32_e32 v50, v50
	v_rcp_f32_e32 v54, v54
	v_rcp_f32_e32 v55, v55
	v_rcp_f32_e32 v56, v56
	s_and_b64 vcc, exec, s[4:5]
	s_cbranch_vccnz .LBB0_1192
	v_add_co_u32_e32 v62, vcc, 0x12000, v164
	s_nop 1
	v_addc_co_u32_e32 v63, vcc, 0, v165, vcc
	v_cvt_pk_bf16_f32 v58, v50, v54
	v_cvt_pk_bf16_f32 v59, v55, v57
	v_cvt_pk_bf16_f32 v60, v51, v52
	v_cvt_pk_bf16_f32 v61, v53, v56
	global_store_dwordx4 v[62:63], v[58:61], off
	s_cbranch_execnz .LBB0_1162
; __device__ __forceinline__ float sigmoidf_(float x) { return __builtin_amdgcn_rcpf(1.0f + __builtin_amdgcn_exp2f(-1.4426950408889634f * x)); }
; __device__ __forceinline__ u32x4 pack8(const f32x4 a, const f32x4 b) { u32x4 w; w.x = pk2(a[0], a[1]); w.y = pk2(a[2], a[3]); w.z = pk2(b[0], b[1]); w.w = pk2(b[2], b[3]); return w; }
;     __device__ __forceinline__ void operator()(const Acc& acc, const Unit& u, int wr, int wc, int fr, int fq) const {
;     ...
;         if ((sub & 1) == 0) {
;             float rs[8]; rstd8(ssq, row0, fq, rs);
; #pragma unroll
;             for (int ai = 0; ai < 2; ++ai)
; #pragma unroll
;                 for (int m = 0; m < 4; ++m) {
;                     const float r1 = rs[ai * 4 + m];
; #pragma unroll
;                     for (int bj = 0; bj < 2; ++bj) {
;                         f32x4 s0, s1; const f32x4 v0 = acc[ai][bj][m][0], v1 = acc[ai][bj][m][1];
; #pragma unroll
;                         for (int e = 0; e < 4; ++e) { s0[e] = sigmoidf_(v0[e] * r1); s1[e] = sigmoidf_(v1[e] * r1); }
;                         if (sub == 0) *MP(ai, m, bj) = pack8(s0, s1); else *SP(ai, m, bj) = pack8(s0, s1);
;                     }
;                 }
.LBB0_1161:
	s_nop 0
	v_cvt_pk_bf16_f32 v58, v50, v54
	v_add_co_u32_e32 v50, vcc, 0x40000, v162
	v_cvt_pk_bf16_f32 v59, v55, v57
	v_cvt_pk_bf16_f32 v60, v51, v52
	v_cvt_pk_bf16_f32 v61, v53, v56
	s_nop 1
	v_addc_co_u32_e32 v51, vcc, 0, v163, vcc
	global_store_dwordx4 v[50:51], v[58:61], off offset:256
.LBB0_1162:
	v_add_f32_e32 v50, v134, v135
	v_fmamk_f32 v50, v50, 0x3a800000, v175
	v_rsq_f32_e32 v50, v50
	s_and_b64 vcc, exec, s[4:5]
	v_mul_f32_e32 v46, v46, v50
	v_mul_f32_e32 v42, v42, v50
	v_mul_f32_e32 v46, 0xbfb8aa3b, v46
	v_mul_f32_e32 v42, 0xbfb8aa3b, v42
	v_exp_f32_e32 v46, v46
	v_exp_f32_e32 v42, v42
	v_mul_f32_e32 v47, v47, v50
	v_mul_f32_e32 v43, v43, v50
	v_mul_f32_e32 v47, 0xbfb8aa3b, v47
	v_add_f32_e32 v46, 1.0, v46
	v_mul_f32_e32 v43, 0xbfb8aa3b, v43
	v_mul_f32_e32 v48, v48, v50
	v_mul_f32_e32 v44, v44, v50
	v_add_f32_e32 v51, 1.0, v42
	v_rcp_f32_e32 v42, v46
	v_exp_f32_e32 v46, v47
	v_exp_f32_e32 v47, v43
	v_mul_f32_e32 v48, 0xbfb8aa3b, v48
	v_mul_f32_e32 v44, 0xbfb8aa3b, v44
	v_rcp_f32_e32 v43, v51
	v_exp_f32_e32 v48, v48
	v_exp_f32_e32 v51, v44
	v_mul_f32_e32 v49, v49, v50
	v_mul_f32_e32 v49, 0xbfb8aa3b, v49
	v_mul_f32_e32 v45, v45, v50
	v_add_f32_e32 v47, 1.0, v47
	v_exp_f32_e32 v49, v49
	v_mul_f32_e32 v45, 0xbfb8aa3b, v45
	v_rcp_f32_e32 v44, v47
	v_add_f32_e32 v47, 1.0, v48
	v_add_f32_e32 v48, 1.0, v51
	v_exp_f32_e32 v51, v45
	v_rcp_f32_e32 v45, v48
	v_add_f32_e32 v48, 1.0, v49
	v_add_f32_e32 v46, 1.0, v46
	v_rcp_f32_e32 v49, v48
	v_add_f32_e32 v48, 1.0, v51
	v_rcp_f32_e32 v46, v46
	v_rcp_f32_e32 v47, v47
	v_rcp_f32_e32 v48, v48
	s_cbranch_vccnz .LBB0_1193
	v_add_co_u32_e32 v56, vcc, 0x14000, v164
	s_nop 1
	v_addc_co_u32_e32 v57, vcc, 0, v165, vcc
	v_cvt_pk_bf16_f32 v52, v42, v46
	v_cvt_pk_bf16_f32 v53, v47, v49
	v_cvt_pk_bf16_f32 v54, v43, v44
	v_cvt_pk_bf16_f32 v55, v45, v48
	global_store_dwordx4 v[56:57], v[52:55], off
	s_cbranch_execnz .LBB0_1165
.LBB0_1164:
	s_nop 0
	v_cvt_pk_bf16_f32 v52, v42, v46
	v_add_co_u32_e32 v42, vcc, 0x48000, v162
	v_cvt_pk_bf16_f32 v53, v47, v49
	v_cvt_pk_bf16_f32 v54, v43, v44
	v_cvt_pk_bf16_f32 v55, v45, v48
	s_nop 1
	v_addc_co_u32_e32 v43, vcc, 0, v163, vcc
	global_store_dwordx4 v[42:43], v[52:55], off
.LBB0_1165:
	v_mul_f32_e32 v38, v38, v50
	v_mul_f32_e32 v34, v34, v50
	v_mul_f32_e32 v38, 0xbfb8aa3b, v38
	v_mul_f32_e32 v34, 0xbfb8aa3b, v34
	v_exp_f32_e32 v38, v38
	v_exp_f32_e32 v42, v34
	v_mul_f32_e32 v39, v39, v50
	v_mul_f32_e32 v35, v35, v50
	v_mul_f32_e32 v39, 0xbfb8aa3b, v39
	v_mul_f32_e32 v35, 0xbfb8aa3b, v35
	v_add_f32_e32 v34, 1.0, v38
	v_add_f32_e32 v38, 1.0, v42
	v_exp_f32_e32 v39, v39
	v_exp_f32_e32 v42, v35
	v_mul_f32_e32 v40, v40, v50
	v_mul_f32_e32 v36, v36, v50
	v_mul_f32_e32 v40, 0xbfb8aa3b, v40
	v_mul_f32_e32 v36, 0xbfb8aa3b, v36
	v_rcp_f32_e32 v35, v38
	v_add_f32_e32 v38, 1.0, v39
	v_add_f32_e32 v39, 1.0, v42
	v_exp_f32_e32 v40, v40
	v_exp_f32_e32 v42, v36
	v_mul_f32_e32 v41, v41, v50
	v_mul_f32_e32 v41, 0xbfb8aa3b, v41
	v_mul_f32_e32 v37, v37, v50
	v_exp_f32_e32 v41, v41
	v_mul_f32_e32 v37, 0xbfb8aa3b, v37
	v_rcp_f32_e32 v36, v39
	v_add_f32_e32 v39, 1.0, v40
	v_add_f32_e32 v40, 1.0, v42
	v_exp_f32_e32 v42, v37
	v_rcp_f32_e32 v37, v40
	v_add_f32_e32 v40, 1.0, v41
	v_rcp_f32_e32 v41, v40
	v_add_f32_e32 v40, 1.0, v42
	v_rcp_f32_e32 v34, v34
	v_rcp_f32_e32 v38, v38
	v_rcp_f32_e32 v39, v39
	v_rcp_f32_e32 v40, v40
	s_and_b64 vcc, exec, s[4:5]
	s_cbranch_vccnz .LBB0_1194
	v_add_co_u32_e32 v46, vcc, 0x16000, v164
	s_nop 1
	v_addc_co_u32_e32 v47, vcc, 0, v165, vcc
	v_cvt_pk_bf16_f32 v42, v34, v38
	v_cvt_pk_bf16_f32 v43, v39, v41
	v_cvt_pk_bf16_f32 v44, v35, v36
	v_cvt_pk_bf16_f32 v45, v37, v40
	global_store_dwordx4 v[46:47], v[42:45], off
	s_cbranch_execnz .LBB0_1168
.LBB0_1167:
	s_nop 0
	v_cvt_pk_bf16_f32 v42, v34, v38
	v_add_co_u32_e32 v34, vcc, 0x48000, v162
	v_cvt_pk_bf16_f32 v43, v39, v41
	v_cvt_pk_bf16_f32 v44, v35, v36
	v_cvt_pk_bf16_f32 v45, v37, v40
	s_nop 1
	v_addc_co_u32_e32 v35, vcc, 0, v163, vcc
	global_store_dwordx4 v[34:35], v[42:45], off offset:256
.LBB0_1168:
	v_add_f32_e32 v34, v132, v133
	v_fmamk_f32 v34, v34, 0x3a800000, v175
	v_rsq_f32_e32 v34, v34
	s_and_b64 vcc, exec, s[4:5]
	v_mul_f32_e32 v30, v30, v34
	v_mul_f32_e32 v26, v26, v34
	v_mul_f32_e32 v30, 0xbfb8aa3b, v30
	v_mul_f32_e32 v26, 0xbfb8aa3b, v26
	v_exp_f32_e32 v30, v30
	v_exp_f32_e32 v26, v26
	v_mul_f32_e32 v31, v31, v34
	v_mul_f32_e32 v27, v27, v34
	v_mul_f32_e32 v31, 0xbfb8aa3b, v31
	v_add_f32_e32 v30, 1.0, v30
	v_mul_f32_e32 v27, 0xbfb8aa3b, v27
	v_mul_f32_e32 v32, v32, v34
	v_mul_f32_e32 v28, v28, v34
	v_add_f32_e32 v35, 1.0, v26
	v_rcp_f32_e32 v26, v30
	v_exp_f32_e32 v30, v31
	v_exp_f32_e32 v31, v27
	v_mul_f32_e32 v32, 0xbfb8aa3b, v32
	v_mul_f32_e32 v28, 0xbfb8aa3b, v28
	v_rcp_f32_e32 v27, v35
	v_exp_f32_e32 v32, v32
	v_exp_f32_e32 v35, v28
	v_mul_f32_e32 v33, v33, v34
	v_mul_f32_e32 v33, 0xbfb8aa3b, v33
	v_mul_f32_e32 v29, v29, v34
	v_add_f32_e32 v31, 1.0, v31
	v_exp_f32_e32 v33, v33
	v_mul_f32_e32 v29, 0xbfb8aa3b, v29
	v_rcp_f32_e32 v28, v31
	v_add_f32_e32 v31, 1.0, v32
	v_add_f32_e32 v32, 1.0, v35
	v_exp_f32_e32 v35, v29
	v_rcp_f32_e32 v29, v32
	v_add_f32_e32 v32, 1.0, v33
	v_add_f32_e32 v30, 1.0, v30
	v_rcp_f32_e32 v33, v32
	v_add_f32_e32 v32, 1.0, v35
	v_rcp_f32_e32 v30, v30
	v_rcp_f32_e32 v31, v31
	v_rcp_f32_e32 v32, v32
	s_cbranch_vccnz .LBB0_1195
	v_add_co_u32_e32 v40, vcc, 0x18000, v164
	s_nop 1
	v_addc_co_u32_e32 v41, vcc, 0, v165, vcc
	v_cvt_pk_bf16_f32 v36, v26, v30
	v_cvt_pk_bf16_f32 v37, v31, v33
	v_cvt_pk_bf16_f32 v38, v27, v28
	v_cvt_pk_bf16_f32 v39, v29, v32
	global_store_dwordx4 v[40:41], v[36:39], off
	s_cbranch_execnz .LBB0_1171
; __device__ __forceinline__ float sigmoidf_(float x) { return __builtin_amdgcn_rcpf(1.0f + __builtin_amdgcn_exp2f(-1.4426950408889634f * x)); }
; __device__ __forceinline__ u32x4 pack8(const f32x4 a, const f32x4 b) { u32x4 w; w.x = pk2(a[0], a[1]); w.y = pk2(a[2], a[3]); w.z = pk2(b[0], b[1]); w.w = pk2(b[2], b[3]); return w; }
;     __device__ __forceinline__ void operator()(const Acc& acc, const Unit& u, int wr, int wc, int fr, int fq) const {
;     ...
;         if ((sub & 1) == 0) {
;             float rs[8]; rstd8(ssq, row0, fq, rs);
; #pragma unroll
;             for (int ai = 0; ai < 2; ++ai)
; #pragma unroll
;                 for (int m = 0; m < 4; ++m) {
;                     const float r1 = rs[ai * 4 + m];
; #pragma unroll
;                     for (int bj = 0; bj < 2; ++bj) {
;                         f32x4 s0, s1; const f32x4 v0 = acc[ai][bj][m][0], v1 = acc[ai][bj][m][1];
; #pragma unroll
;                         for (int e = 0; e < 4; ++e) { s0[e] = sigmoidf_(v0[e] * r1); s1[e] = sigmoidf_(v1[e] * r1); }
;                         if (sub == 0) *MP(ai, m, bj) = pack8(s0, s1); else *SP(ai, m, bj) = pack8(s0, s1);
;                     }
;                 }
.LBB0_1170:
	s_nop 0
	v_cvt_pk_bf16_f32 v36, v26, v30
	v_add_co_u32_e32 v26, vcc, 0x50000, v162
	v_cvt_pk_bf16_f32 v37, v31, v33
	v_cvt_pk_bf16_f32 v38, v27, v28
	v_cvt_pk_bf16_f32 v39, v29, v32
	s_nop 1
	v_addc_co_u32_e32 v27, vcc, 0, v163, vcc
	global_store_dwordx4 v[26:27], v[36:39], off
.LBB0_1171:
	v_mul_f32_e32 v22, v22, v34
	v_mul_f32_e32 v18, v18, v34
	v_mul_f32_e32 v22, 0xbfb8aa3b, v22
	v_mul_f32_e32 v18, 0xbfb8aa3b, v18
	v_exp_f32_e32 v22, v22
	v_exp_f32_e32 v26, v18
	v_mul_f32_e32 v23, v23, v34
	v_mul_f32_e32 v19, v19, v34
	v_mul_f32_e32 v23, 0xbfb8aa3b, v23
	v_mul_f32_e32 v19, 0xbfb8aa3b, v19
	v_add_f32_e32 v18, 1.0, v22
	v_add_f32_e32 v22, 1.0, v26
	v_exp_f32_e32 v23, v23
	v_exp_f32_e32 v26, v19
	v_mul_f32_e32 v24, v24, v34
	v_mul_f32_e32 v20, v20, v34
	v_mul_f32_e32 v24, 0xbfb8aa3b, v24
	v_mul_f32_e32 v20, 0xbfb8aa3b, v20
	v_rcp_f32_e32 v19, v22
	v_add_f32_e32 v22, 1.0, v23
	v_add_f32_e32 v23, 1.0, v26
	v_exp_f32_e32 v24, v24
	v_exp_f32_e32 v26, v20
	v_mul_f32_e32 v25, v25, v34
	v_mul_f32_e32 v25, 0xbfb8aa3b, v25
	v_mul_f32_e32 v21, v21, v34
	v_exp_f32_e32 v25, v25
	v_mul_f32_e32 v21, 0xbfb8aa3b, v21
	v_rcp_f32_e32 v20, v23
	v_add_f32_e32 v23, 1.0, v24
	v_add_f32_e32 v24, 1.0, v26
	v_exp_f32_e32 v26, v21
	v_rcp_f32_e32 v21, v24
	v_add_f32_e32 v24, 1.0, v25
	v_rcp_f32_e32 v25, v24
	v_add_f32_e32 v24, 1.0, v26
	v_rcp_f32_e32 v18, v18
	v_rcp_f32_e32 v22, v22
	v_rcp_f32_e32 v23, v23
	v_rcp_f32_e32 v24, v24
	s_and_b64 vcc, exec, s[4:5]
	s_cbranch_vccnz .LBB0_1196
	v_add_co_u32_e32 v30, vcc, 0x1a000, v164
	s_nop 1
	v_addc_co_u32_e32 v31, vcc, 0, v165, vcc
	v_cvt_pk_bf16_f32 v26, v18, v22
	v_cvt_pk_bf16_f32 v27, v23, v25
	v_cvt_pk_bf16_f32 v28, v19, v20
	v_cvt_pk_bf16_f32 v29, v21, v24
	global_store_dwordx4 v[30:31], v[26:29], off
	s_cbranch_execnz .LBB0_1174
.LBB0_1173:
	s_nop 0
	v_cvt_pk_bf16_f32 v26, v18, v22
	v_add_co_u32_e32 v18, vcc, 0x50000, v162
	v_cvt_pk_bf16_f32 v27, v23, v25
	v_cvt_pk_bf16_f32 v28, v19, v20
	v_cvt_pk_bf16_f32 v29, v21, v24
	s_nop 1
	v_addc_co_u32_e32 v19, vcc, 0, v163, vcc
	global_store_dwordx4 v[18:19], v[26:29], off offset:256
.LBB0_1174:
	v_add_f32_e32 v18, v130, v131
	v_fmamk_f32 v18, v18, 0x3a800000, v175
	v_rsq_f32_e32 v18, v18
	s_and_b64 vcc, exec, s[4:5]
	v_mul_f32_e32 v14, v14, v18
	v_mul_f32_e32 v10, v10, v18
	v_mul_f32_e32 v14, 0xbfb8aa3b, v14
	v_mul_f32_e32 v10, 0xbfb8aa3b, v10
	v_exp_f32_e32 v14, v14
	v_exp_f32_e32 v10, v10
	v_mul_f32_e32 v15, v15, v18
	v_mul_f32_e32 v11, v11, v18
	v_mul_f32_e32 v15, 0xbfb8aa3b, v15
	v_add_f32_e32 v14, 1.0, v14
	v_mul_f32_e32 v11, 0xbfb8aa3b, v11
	v_mul_f32_e32 v16, v16, v18
	v_mul_f32_e32 v12, v12, v18
	v_add_f32_e32 v19, 1.0, v10
	v_rcp_f32_e32 v10, v14
	v_exp_f32_e32 v14, v15
	v_exp_f32_e32 v15, v11
	v_mul_f32_e32 v16, 0xbfb8aa3b, v16
	v_mul_f32_e32 v12, 0xbfb8aa3b, v12
	v_rcp_f32_e32 v11, v19
	v_exp_f32_e32 v16, v16
	v_exp_f32_e32 v19, v12
	v_mul_f32_e32 v17, v17, v18
	v_mul_f32_e32 v17, 0xbfb8aa3b, v17
	v_mul_f32_e32 v13, v13, v18
	v_add_f32_e32 v15, 1.0, v15
	v_exp_f32_e32 v17, v17
	v_mul_f32_e32 v13, 0xbfb8aa3b, v13
	v_rcp_f32_e32 v12, v15
	v_add_f32_e32 v15, 1.0, v16
	v_add_f32_e32 v16, 1.0, v19
	v_exp_f32_e32 v19, v13
	v_rcp_f32_e32 v13, v16
	v_add_f32_e32 v16, 1.0, v17
	v_add_f32_e32 v14, 1.0, v14
	v_rcp_f32_e32 v17, v16
	v_add_f32_e32 v16, 1.0, v19
	v_rcp_f32_e32 v14, v14
	v_rcp_f32_e32 v15, v15
	v_rcp_f32_e32 v16, v16
	s_cbranch_vccnz .LBB0_1197
	v_add_co_u32_e32 v24, vcc, 0x1c000, v164
	s_nop 1
	v_addc_co_u32_e32 v25, vcc, 0, v165, vcc
	v_cvt_pk_bf16_f32 v20, v10, v14
	v_cvt_pk_bf16_f32 v21, v15, v17
	v_cvt_pk_bf16_f32 v22, v11, v12
	v_cvt_pk_bf16_f32 v23, v13, v16
	global_store_dwordx4 v[24:25], v[20:23], off
	s_cbranch_execnz .LBB0_1177
.LBB0_1176:
	s_nop 0
	v_cvt_pk_bf16_f32 v20, v10, v14
	v_add_co_u32_e32 v10, vcc, 0x58000, v162
	v_cvt_pk_bf16_f32 v21, v15, v17
	v_cvt_pk_bf16_f32 v22, v11, v12
	v_cvt_pk_bf16_f32 v23, v13, v16
	s_nop 1
	v_addc_co_u32_e32 v11, vcc, 0, v163, vcc
	global_store_dwordx4 v[10:11], v[20:23], off
.LBB0_1177:
	v_mul_f32_e32 v6, v6, v18
	v_mul_f32_e32 v2, v2, v18
	v_mul_f32_e32 v6, 0xbfb8aa3b, v6
	v_mul_f32_e32 v2, 0xbfb8aa3b, v2
	v_exp_f32_e32 v6, v6
	v_exp_f32_e32 v10, v2
	v_mul_f32_e32 v7, v7, v18
	v_mul_f32_e32 v3, v3, v18
	v_mul_f32_e32 v7, 0xbfb8aa3b, v7
	v_mul_f32_e32 v3, 0xbfb8aa3b, v3
	v_add_f32_e32 v2, 1.0, v6
	v_add_f32_e32 v6, 1.0, v10
	v_exp_f32_e32 v7, v7
	v_exp_f32_e32 v10, v3
	v_mul_f32_e32 v8, v8, v18
	v_mul_f32_e32 v4, v4, v18
	v_mul_f32_e32 v8, 0xbfb8aa3b, v8
	v_mul_f32_e32 v4, 0xbfb8aa3b, v4
	v_rcp_f32_e32 v3, v6
	v_add_f32_e32 v6, 1.0, v7
	v_add_f32_e32 v7, 1.0, v10
	v_exp_f32_e32 v8, v8
	v_exp_f32_e32 v10, v4
	v_mul_f32_e32 v9, v9, v18
	v_mul_f32_e32 v9, 0xbfb8aa3b, v9
	v_mul_f32_e32 v5, v5, v18
	v_exp_f32_e32 v9, v9
	v_mul_f32_e32 v5, 0xbfb8aa3b, v5
	v_rcp_f32_e32 v4, v7
	v_add_f32_e32 v7, 1.0, v8
	v_add_f32_e32 v8, 1.0, v10
	v_exp_f32_e32 v10, v5
	v_rcp_f32_e32 v5, v8
	v_add_f32_e32 v8, 1.0, v9
	v_rcp_f32_e32 v9, v8
	v_add_f32_e32 v8, 1.0, v10
	v_rcp_f32_e32 v2, v2
	v_rcp_f32_e32 v6, v6
	v_rcp_f32_e32 v7, v7
	v_rcp_f32_e32 v8, v8
	s_and_b64 vcc, exec, s[4:5]
	s_cbranch_vccnz .LBB0_1198
	v_add_co_u32_e32 v14, vcc, 0x1e000, v164
	s_nop 1
	v_addc_co_u32_e32 v15, vcc, 0, v165, vcc
	v_cvt_pk_bf16_f32 v10, v2, v6
	v_cvt_pk_bf16_f32 v11, v7, v9
	v_cvt_pk_bf16_f32 v12, v3, v4
	v_cvt_pk_bf16_f32 v13, v5, v8
	global_store_dwordx4 v[14:15], v[10:13], off
	s_cbranch_execnz .LBB0_1180
.LBB0_1179:
	s_nop 0
	v_cvt_pk_bf16_f32 v10, v2, v6
	v_add_co_u32_e32 v2, vcc, 0x58000, v162
	v_cvt_pk_bf16_f32 v11, v7, v9
	v_cvt_pk_bf16_f32 v12, v3, v4
	v_cvt_pk_bf16_f32 v13, v5, v8
	s_nop 1
	v_addc_co_u32_e32 v3, vcc, 0, v163, vcc
	global_store_dwordx4 v[2:3], v[10:13], off offset:256

; __device__ __forceinline__ u32x4 pack8(const f32x4 a, const f32x4 b) { u32x4 w; w.x = pk2(a[0], a[1]); w.y = pk2(a[2], a[3]); w.z = pk2(b[0], b[1]); w.w = pk2(b[2], b[3]); return w; }
; __device__ __forceinline__ void unpack8(const u32x4 w, f32x4& a, f32x4& b) { a = (f32x4){bflo(w.x), bfhi(w.x), bflo(w.y), bfhi(w.y)}; b = (f32x4){bflo(w.z), bfhi(w.z), bflo(w.w), bfhi(w.w)}; }
;     __device__ __forceinline__ void operator()(const Acc& acc, const Unit& u, int wr, int wc, int fr, int fq) const {
;     ...
;         } else {
; #pragma unroll
;             for (int ai = 0; ai < 2; ++ai)
; #pragma unroll
;                 for (int mp = 0; mp < 2; ++mp) {
;                     u32x4 c[2][2], s[2][2];
; #pragma unroll
;                     for (int mm = 0; mm < 2; ++mm)
; #pragma unroll
;                         for (int bj = 0; bj < 2; ++bj) { c[mm][bj] = *MP(ai, 2 * mp + mm, bj); s[mm][bj] = *SP(ai, 2 * mp + mm, bj); }
; #pragma unroll
;                     for (int mm = 0; mm < 2; ++mm)
; #pragma unroll
;                         for (int bj = 0; bj < 2; ++bj) { const int m = 2 * mp + mm; f32x4 c0, c1, s0, s1; unpack8(c[mm][bj], c0, c1); unpack8(s[mm][bj], s0, s1);
;                             *MP(ai, m, bj) = pack8(c0 + s0 * acc[ai][bj][m][0], c1 + s1 * acc[ai][bj][m][1]); }
;                     asm volatile("" ::: "memory");
;                 }
.LBB0_5780:
	v_lshl_add_u32 v164, s52, 8, v1
	v_ashrrev_i32_e32 v165, 31, v164
	v_lshlrev_b64 v[130:131], 11, v[164:165]
	s_lshl_b32 s4, s4, 8
	v_lshl_add_u64 v[130:131], s[40:41], 0, v[130:131]
	s_ashr_i32 s5, s4, 31
	v_lshl_add_u64 v[130:131], s[4:5], 1, v[130:131]
	s_bitcmp1_b32 s53, 0
	v_lshl_add_u64 v[130:131], v[130:131], 0, s[24:25]
	s_cselect_b64 s[18:19], -1, 0
	v_lshl_add_u64 v[160:161], v[130:131], 0, v[146:147]
	v_mov_b64_e32 v[162:163], v[148:149]
	s_mov_b64 s[4:5], -1
	s_and_b64 vcc, exec, s[18:19]
	s_cbranch_vccz .LBB0_5786
	global_load_dwordx4 v[166:169], v[160:161], off
	s_cmp_eq_u32 s53, 1
	s_waitcnt vmcnt(0) lgkmcnt(0)
	v_lshlrev_b32_e32 v132, 16, v166
	v_and_b32_e32 v133, 0xffff0000, v166
	v_lshlrev_b32_e32 v136, 16, v167
	v_and_b32_e32 v137, 0xffff0000, v167
	v_lshlrev_b32_e32 v130, 16, v168
	v_and_b32_e32 v131, 0xffff0000, v168
	v_lshlrev_b32_e32 v134, 16, v169
	v_and_b32_e32 v135, 0xffff0000, v169
	s_cbranch_scc1 .LBB0_5783
	v_add_co_u32_e32 v166, vcc, 0x2000, v162
	global_load_dwordx4 v[176:179], v[162:163], off
	global_load_dwordx4 v[180:183], v[160:161], off offset:256
	v_addc_co_u32_e32 v167, vcc, 0, v163, vcc
	global_load_dwordx4 v[184:187], v[166:167], off
	v_add_co_u32_e32 v166, vcc, 0x8000, v160
	s_mov_b64 s[4:5], 0
	s_nop 0
	v_addc_co_u32_e32 v167, vcc, 0, v161, vcc
	v_add_co_u32_e32 v168, vcc, 0x4000, v162
	global_load_dwordx4 v[192:195], v[166:167], off
	s_nop 0
	v_addc_co_u32_e32 v169, vcc, 0, v163, vcc
	global_load_dwordx4 v[196:199], v[168:169], off
	global_load_dwordx4 v[200:203], v[166:167], off offset:256
	v_add_co_u32_e32 v168, vcc, 0x6000, v162
	s_waitcnt vmcnt(0) lgkmcnt(0)
	v_lshlrev_b32_e32 v188, 16, v178
	v_addc_co_u32_e32 v169, vcc, 0, v163, vcc
	global_load_dwordx4 v[204:207], v[168:169], off
	v_lshlrev_b32_e32 v168, 16, v176
	v_and_b32_e32 v169, 0xffff0000, v176
	v_and_b32_e32 v189, 0xffff0000, v178
	v_lshlrev_b32_e32 v178, 16, v179
	v_and_b32_e32 v179, 0xffff0000, v179
	v_lshlrev_b32_e32 v176, 16, v177
	v_and_b32_e32 v177, 0xffff0000, v177
	v_pk_fma_f32 v[168:169], v[126:127], v[168:169], v[132:133]
	v_pk_fma_f32 v[214:215], v[124:125], v[178:179], v[134:135]
	v_pk_fma_f32 v[178:179], v[122:123], v[188:189], v[130:131]
	v_lshlrev_b32_e32 v208, 16, v180
	v_and_b32_e32 v209, 0xffff0000, v180
	v_lshlrev_b32_e32 v180, 16, v181
	v_and_b32_e32 v181, 0xffff0000, v181
	v_lshlrev_b32_e32 v210, 16, v182
	v_and_b32_e32 v211, 0xffff0000, v182
	v_lshlrev_b32_e32 v182, 16, v183
	v_and_b32_e32 v183, 0xffff0000, v183
	v_pk_fma_f32 v[212:213], v[128:129], v[176:177], v[136:137]
	v_cvt_pk_bf16_f32 v176, v168, v169
	v_lshlrev_b32_e32 v168, 16, v184
	v_cvt_pk_bf16_f32 v177, v212, v213
	v_cvt_pk_bf16_f32 v178, v178, v179
	v_cvt_pk_bf16_f32 v179, v214, v215
	v_and_b32_e32 v169, 0xffff0000, v184
	v_lshlrev_b32_e32 v184, 16, v185
	v_and_b32_e32 v185, 0xffff0000, v185
	v_lshlrev_b32_e32 v188, 16, v186
	v_and_b32_e32 v189, 0xffff0000, v186
	v_lshlrev_b32_e32 v186, 16, v187
	v_and_b32_e32 v187, 0xffff0000, v187
	global_store_dwordx4 v[160:161], v[176:179], off
	v_pk_fma_f32 v[168:169], v[118:119], v[168:169], v[208:209]
	s_nop 0
	v_pk_fma_f32 v[178:179], v[120:121], v[184:185], v[180:181]
	v_pk_fma_f32 v[180:181], v[116:117], v[186:187], v[182:183]
	v_pk_fma_f32 v[182:183], v[114:115], v[188:189], v[210:211]
	v_lshlrev_b32_e32 v186, 16, v193
	v_and_b32_e32 v187, 0xffff0000, v193
	v_cvt_pk_bf16_f32 v176, v168, v169
	v_cvt_pk_bf16_f32 v177, v178, v179
	v_cvt_pk_bf16_f32 v178, v182, v183
	v_cvt_pk_bf16_f32 v179, v180, v181
	v_lshlrev_b32_e32 v180, 16, v197
	v_and_b32_e32 v181, 0xffff0000, v197
	v_lshlrev_b32_e32 v184, 16, v192
	v_and_b32_e32 v185, 0xffff0000, v192
	v_lshlrev_b32_e32 v188, 16, v194
	v_and_b32_e32 v189, 0xffff0000, v194
	v_lshlrev_b32_e32 v192, 16, v195
	v_and_b32_e32 v193, 0xffff0000, v195
	v_lshlrev_b32_e32 v168, 16, v196
	v_and_b32_e32 v169, 0xffff0000, v196
	v_lshlrev_b32_e32 v182, 16, v198
	v_and_b32_e32 v183, 0xffff0000, v198
	v_lshlrev_b32_e32 v194, 16, v199
	v_and_b32_e32 v195, 0xffff0000, v199
	global_store_dwordx4 v[160:161], v[176:179], off offset:256
	v_pk_fma_f32 v[168:169], v[110:111], v[168:169], v[184:185]
	v_pk_fma_f32 v[182:183], v[106:107], v[182:183], v[188:189]
	v_pk_fma_f32 v[178:179], v[112:113], v[180:181], v[186:187]
	v_pk_fma_f32 v[180:181], v[108:109], v[194:195], v[192:193]
	v_cvt_pk_bf16_f32 v176, v168, v169
	v_cvt_pk_bf16_f32 v177, v178, v179
	v_cvt_pk_bf16_f32 v178, v182, v183
	v_lshlrev_b32_e32 v168, 16, v200
	v_cvt_pk_bf16_f32 v179, v180, v181
	global_store_dwordx4 v[166:167], v[176:179], off
	v_lshlrev_b32_e32 v180, 16, v203
	v_and_b32_e32 v181, 0xffff0000, v203
	v_lshlrev_b32_e32 v178, 16, v202
	v_and_b32_e32 v179, 0xffff0000, v202
	v_and_b32_e32 v169, 0xffff0000, v200
	v_lshlrev_b32_e32 v176, 16, v201
	v_and_b32_e32 v177, 0xffff0000, v201
	s_waitcnt vmcnt(0) lgkmcnt(0)
	v_lshlrev_b32_e32 v186, 16, v206
	v_and_b32_e32 v187, 0xffff0000, v206
	v_lshlrev_b32_e32 v188, 16, v207
	v_and_b32_e32 v189, 0xffff0000, v207
	v_lshlrev_b32_e32 v182, 16, v204
	v_and_b32_e32 v183, 0xffff0000, v204
	v_lshlrev_b32_e32 v184, 16, v205
	v_and_b32_e32 v185, 0xffff0000, v205
	v_pk_fma_f32 v[180:181], v[100:101], v[188:189], v[180:181]
	v_pk_fma_f32 v[178:179], v[98:99], v[186:187], v[178:179]
	v_add_co_u32_e32 v188, vcc, s69, v160
	v_pk_fma_f32 v[184:185], v[104:105], v[184:185], v[176:177]
	v_pk_fma_f32 v[168:169], v[102:103], v[182:183], v[168:169]
	v_addc_co_u32_e32 v189, vcc, 0, v161, vcc
	v_cvt_pk_bf16_f32 v176, v168, v169
	v_cvt_pk_bf16_f32 v177, v184, v185
	v_cvt_pk_bf16_f32 v178, v178, v179
	v_cvt_pk_bf16_f32 v179, v180, v181
	global_store_dwordx4 v[166:167], v[176:179], off offset:256
	global_load_dwordx4 v[166:169], v[188:189], off
	s_waitcnt vmcnt(0) lgkmcnt(0)
; __device__ __forceinline__ u32x4 pack8(const f32x4 a, const f32x4 b) { u32x4 w; w.x = pk2(a[0], a[1]); w.y = pk2(a[2], a[3]); w.z = pk2(b[0], b[1]); w.w = pk2(b[2], b[3]); return w; }
; __device__ __forceinline__ void unpack8(const u32x4 w, f32x4& a, f32x4& b) { a = (f32x4){bflo(w.x), bfhi(w.x), bflo(w.y), bfhi(w.y)}; b = (f32x4){bflo(w.z), bfhi(w.z), bflo(w.w), bfhi(w.w)}; }
;     __device__ __forceinline__ void operator()(const Acc& acc, const Unit& u, int wr, int wc, int fr, int fq) const {
;     ...
;         } else {
; #pragma unroll
;             for (int ai = 0; ai < 2; ++ai)
; #pragma unroll
;                 for (int mp = 0; mp < 2; ++mp) {
;                     u32x4 c[2][2], s[2][2];
; #pragma unroll
;                     for (int mm = 0; mm < 2; ++mm)
; #pragma unroll
;                         for (int bj = 0; bj < 2; ++bj) { c[mm][bj] = *MP(ai, 2 * mp + mm, bj); s[mm][bj] = *SP(ai, 2 * mp + mm, bj); }
; #pragma unroll
;                     for (int mm = 0; mm < 2; ++mm)
; #pragma unroll
;                         for (int bj = 0; bj < 2; ++bj) { const int m = 2 * mp + mm; f32x4 c0, c1, s0, s1; unpack8(c[mm][bj], c0, c1); unpack8(s[mm][bj], s0, s1);
;                             *MP(ai, m, bj) = pack8(c0 + s0 * acc[ai][bj][m][0], c1 + s1 * acc[ai][bj][m][1]); }
;                     asm volatile("" ::: "memory");
;                 }
	v_lshlrev_b32_e32 v210, 16, v166
	v_add_co_u32_e32 v176, vcc, s78, v162
	v_and_b32_e32 v211, 0xffff0000, v166
	s_nop 0
	v_addc_co_u32_e32 v177, vcc, 0, v163, vcc
	global_load_dwordx4 v[176:179], v[176:177], off
	s_nop 0
	global_load_dwordx4 v[180:183], v[188:189], off offset:256
	v_add_co_u32_e32 v184, vcc, s79, v162
	v_lshlrev_b32_e32 v166, 16, v167
	s_nop 0
	v_addc_co_u32_e32 v185, vcc, 0, v163, vcc
	global_load_dwordx4 v[184:187], v[184:185], off
	v_add_co_u32_e32 v208, vcc, s76, v160
	v_and_b32_e32 v167, 0xffff0000, v167
	s_nop 0
	v_addc_co_u32_e32 v209, vcc, 0, v161, vcc
	v_add_co_u32_e32 v196, vcc, s85, v162
	global_load_dwordx4 v[192:195], v[208:209], off
	s_nop 0
	v_addc_co_u32_e32 v197, vcc, 0, v163, vcc
	global_load_dwordx4 v[196:199], v[196:197], off
	s_nop 0
	global_load_dwordx4 v[200:203], v[208:209], off offset:256
	v_add_co_u32_e32 v204, vcc, s86, v162
	v_lshlrev_b32_e32 v212, 16, v168
	s_nop 0
	v_addc_co_u32_e32 v205, vcc, 0, v163, vcc
	global_load_dwordx4 v[204:207], v[204:205], off
	v_and_b32_e32 v213, 0xffff0000, v168
	v_lshlrev_b32_e32 v168, 16, v169
	v_and_b32_e32 v169, 0xffff0000, v169
	s_waitcnt vmcnt(0) lgkmcnt(0)
	v_lshlrev_b32_e32 v214, 16, v176
	v_and_b32_e32 v215, 0xffff0000, v176
	v_lshlrev_b32_e32 v176, 16, v177
	v_and_b32_e32 v177, 0xffff0000, v177
	v_lshlrev_b32_e32 v216, 16, v178
	v_and_b32_e32 v217, 0xffff0000, v178
	v_lshlrev_b32_e32 v178, 16, v179
	v_and_b32_e32 v179, 0xffff0000, v179
	v_pk_fma_f32 v[176:177], v[96:97], v[176:177], v[166:167]
	v_pk_fma_f32 v[166:167], v[94:95], v[214:215], v[210:211]
	v_pk_fma_f32 v[178:179], v[92:93], v[178:179], v[168:169]
	v_pk_fma_f32 v[168:169], v[90:91], v[216:217], v[212:213]
	v_cvt_pk_bf16_f32 v166, v166, v167
	v_cvt_pk_bf16_f32 v167, v176, v177
	v_lshlrev_b32_e32 v176, 16, v182
	v_cvt_pk_bf16_f32 v168, v168, v169
	v_cvt_pk_bf16_f32 v169, v178, v179
	global_store_dwordx4 v[188:189], v[166:169], off
	v_and_b32_e32 v177, 0xffff0000, v182
	v_lshlrev_b32_e32 v178, 16, v183
	v_lshlrev_b32_e32 v166, 16, v180
	v_and_b32_e32 v167, 0xffff0000, v180
	v_lshlrev_b32_e32 v168, 16, v181
	v_and_b32_e32 v169, 0xffff0000, v181
	v_and_b32_e32 v179, 0xffff0000, v183
	v_lshlrev_b32_e32 v180, 16, v184
	v_and_b32_e32 v181, 0xffff0000, v184
	v_lshlrev_b32_e32 v182, 16, v185
	v_and_b32_e32 v183, 0xffff0000, v185
	v_lshlrev_b32_e32 v184, 16, v186
	v_and_b32_e32 v185, 0xffff0000, v186
	v_lshlrev_b32_e32 v186, 16, v187
	v_and_b32_e32 v187, 0xffff0000, v187
	v_pk_fma_f32 v[168:169], v[88:89], v[182:183], v[168:169]
	v_pk_fma_f32 v[166:167], v[86:87], v[180:181], v[166:167]
	v_pk_fma_f32 v[178:179], v[84:85], v[186:187], v[178:179]
	v_pk_fma_f32 v[176:177], v[82:83], v[184:185], v[176:177]
	v_cvt_pk_bf16_f32 v166, v166, v167
	v_cvt_pk_bf16_f32 v167, v168, v169
	v_lshlrev_b32_e32 v180, 16, v196
	v_cvt_pk_bf16_f32 v168, v176, v177
	v_cvt_pk_bf16_f32 v169, v178, v179
	global_store_dwordx4 v[188:189], v[166:169], off offset:256
	v_and_b32_e32 v181, 0xffff0000, v196
	v_lshlrev_b32_e32 v182, 16, v197
	v_lshlrev_b32_e32 v166, 16, v192
	v_and_b32_e32 v167, 0xffff0000, v192
	v_lshlrev_b32_e32 v168, 16, v193
	v_and_b32_e32 v169, 0xffff0000, v193
	v_and_b32_e32 v183, 0xffff0000, v197
	v_lshlrev_b32_e32 v176, 16, v194
	v_and_b32_e32 v177, 0xffff0000, v194
	v_lshlrev_b32_e32 v178, 16, v195
	v_and_b32_e32 v179, 0xffff0000, v195
	v_lshlrev_b32_e32 v184, 16, v198
	v_and_b32_e32 v185, 0xffff0000, v198
	v_lshlrev_b32_e32 v186, 16, v199
	v_and_b32_e32 v187, 0xffff0000, v199
	v_pk_fma_f32 v[168:169], v[80:81], v[182:183], v[168:169]
	v_pk_fma_f32 v[166:167], v[78:79], v[180:181], v[166:167]
	v_pk_fma_f32 v[178:179], v[76:77], v[186:187], v[178:179]
	v_pk_fma_f32 v[176:177], v[74:75], v[184:185], v[176:177]
	v_cvt_pk_bf16_f32 v166, v166, v167
	v_cvt_pk_bf16_f32 v167, v168, v169
	v_lshlrev_b32_e32 v180, 16, v204
	v_cvt_pk_bf16_f32 v168, v176, v177
	v_cvt_pk_bf16_f32 v169, v178, v179
	global_store_dwordx4 v[208:209], v[166:169], off
	v_and_b32_e32 v181, 0xffff0000, v204
	v_lshlrev_b32_e32 v182, 16, v205
	v_lshlrev_b32_e32 v166, 16, v200
	v_and_b32_e32 v167, 0xffff0000, v200
	v_lshlrev_b32_e32 v168, 16, v201
	v_and_b32_e32 v169, 0xffff0000, v201
	v_and_b32_e32 v183, 0xffff0000, v205
	v_lshlrev_b32_e32 v176, 16, v202
	v_and_b32_e32 v177, 0xffff0000, v202
	v_lshlrev_b32_e32 v178, 16, v203
	v_and_b32_e32 v179, 0xffff0000, v203
	v_lshlrev_b32_e32 v184, 16, v206
	v_and_b32_e32 v185, 0xffff0000, v206
	v_lshlrev_b32_e32 v186, 16, v207
	v_and_b32_e32 v187, 0xffff0000, v207
	v_pk_fma_f32 v[168:169], v[72:73], v[182:183], v[168:169]
	v_pk_fma_f32 v[166:167], v[70:71], v[180:181], v[166:167]
	v_add_co_u32_e32 v188, vcc, s87, v160
	v_pk_fma_f32 v[178:179], v[68:69], v[186:187], v[178:179]
	v_pk_fma_f32 v[176:177], v[66:67], v[184:185], v[176:177]
	v_cvt_pk_bf16_f32 v166, v166, v167
	v_cvt_pk_bf16_f32 v167, v168, v169
	v_addc_co_u32_e32 v189, vcc, 0, v161, vcc
	v_cvt_pk_bf16_f32 v168, v176, v177
	v_cvt_pk_bf16_f32 v169, v178, v179
	global_store_dwordx4 v[208:209], v[166:169], off offset:256
	v_add_co_u32_e32 v176, vcc, s69, v162
	global_load_dwordx4 v[166:169], v[188:189], off
	s_nop 0
	v_addc_co_u32_e32 v177, vcc, 0, v163, vcc
	global_load_dwordx4 v[176:179], v[176:177], off
	s_nop 0
	global_load_dwordx4 v[180:183], v[188:189], off offset:256
	v_add_co_u32_e32 v184, vcc, s71, v162
	s_waitcnt vmcnt(0) lgkmcnt(0)
; __device__ __forceinline__ u32x4 pack8(const f32x4 a, const f32x4 b) { u32x4 w; w.x = pk2(a[0], a[1]); w.y = pk2(a[2], a[3]); w.z = pk2(b[0], b[1]); w.w = pk2(b[2], b[3]); return w; }
; __device__ __forceinline__ void unpack8(const u32x4 w, f32x4& a, f32x4& b) { a = (f32x4){bflo(w.x), bfhi(w.x), bflo(w.y), bfhi(w.y)}; b = (f32x4){bflo(w.z), bfhi(w.z), bflo(w.w), bfhi(w.w)}; }
;     __device__ __forceinline__ void operator()(const Acc& acc, const Unit& u, int wr, int wc, int fr, int fq) const {
;     ...
;         } else {
; #pragma unroll
;             for (int ai = 0; ai < 2; ++ai)
; #pragma unroll
;                 for (int mp = 0; mp < 2; ++mp) {
;                     u32x4 c[2][2], s[2][2];
; #pragma unroll
;                     for (int mm = 0; mm < 2; ++mm)
; #pragma unroll
;                         for (int bj = 0; bj < 2; ++bj) { c[mm][bj] = *MP(ai, 2 * mp + mm, bj); s[mm][bj] = *SP(ai, 2 * mp + mm, bj); }
; #pragma unroll
;                     for (int mm = 0; mm < 2; ++mm)
; #pragma unroll
;                         for (int bj = 0; bj < 2; ++bj) { const int m = 2 * mp + mm; f32x4 c0, c1, s0, s1; unpack8(c[mm][bj], c0, c1); unpack8(s[mm][bj], s0, s1);
;                             *MP(ai, m, bj) = pack8(c0 + s0 * acc[ai][bj][m][0], c1 + s1 * acc[ai][bj][m][1]); }
;                     asm volatile("" ::: "memory");
;                 }
	v_lshlrev_b32_e32 v210, 16, v166
	v_addc_co_u32_e32 v185, vcc, 0, v163, vcc
	global_load_dwordx4 v[184:187], v[184:185], off
	v_add_co_u32_e32 v208, vcc, s88, v160
	v_and_b32_e32 v211, 0xffff0000, v166
	s_nop 0
	v_addc_co_u32_e32 v209, vcc, 0, v161, vcc
	v_add_co_u32_e32 v196, vcc, s72, v162
	global_load_dwordx4 v[192:195], v[208:209], off
	s_nop 0
	v_addc_co_u32_e32 v197, vcc, 0, v163, vcc
	global_load_dwordx4 v[196:199], v[196:197], off
	s_nop 0
	global_load_dwordx4 v[200:203], v[208:209], off offset:256
	v_add_co_u32_e32 v204, vcc, s73, v162
	v_lshlrev_b32_e32 v166, 16, v167
	s_nop 0
	v_addc_co_u32_e32 v205, vcc, 0, v163, vcc
	global_load_dwordx4 v[204:207], v[204:205], off
	v_and_b32_e32 v167, 0xffff0000, v167
	v_lshlrev_b32_e32 v212, 16, v168
	v_and_b32_e32 v213, 0xffff0000, v168
	v_lshlrev_b32_e32 v168, 16, v169
	v_and_b32_e32 v169, 0xffff0000, v169
	v_lshlrev_b32_e32 v214, 16, v176
	v_and_b32_e32 v215, 0xffff0000, v176
	v_lshlrev_b32_e32 v176, 16, v177
	v_and_b32_e32 v177, 0xffff0000, v177
	v_lshlrev_b32_e32 v216, 16, v178
	v_and_b32_e32 v217, 0xffff0000, v178
	v_lshlrev_b32_e32 v178, 16, v179
	v_and_b32_e32 v179, 0xffff0000, v179
	v_pk_fma_f32 v[176:177], v[64:65], v[176:177], v[166:167]
	v_pk_fma_f32 v[166:167], v[62:63], v[214:215], v[210:211]
	v_pk_fma_f32 v[178:179], v[60:61], v[178:179], v[168:169]
	v_pk_fma_f32 v[168:169], v[58:59], v[216:217], v[212:213]
	v_cvt_pk_bf16_f32 v166, v166, v167
	v_cvt_pk_bf16_f32 v167, v176, v177
	v_lshlrev_b32_e32 v176, 16, v182
	v_cvt_pk_bf16_f32 v168, v168, v169
	v_cvt_pk_bf16_f32 v169, v178, v179
	global_store_dwordx4 v[188:189], v[166:169], off
	v_and_b32_e32 v177, 0xffff0000, v182
	v_lshlrev_b32_e32 v178, 16, v183
	v_lshlrev_b32_e32 v166, 16, v180
	v_and_b32_e32 v167, 0xffff0000, v180
	v_lshlrev_b32_e32 v168, 16, v181
	v_and_b32_e32 v169, 0xffff0000, v181
	v_and_b32_e32 v179, 0xffff0000, v183
	s_waitcnt vmcnt(0) lgkmcnt(0)
	v_lshlrev_b32_e32 v180, 16, v184
	v_and_b32_e32 v181, 0xffff0000, v184
	v_lshlrev_b32_e32 v182, 16, v185
	v_and_b32_e32 v183, 0xffff0000, v185
	v_lshlrev_b32_e32 v184, 16, v186
	v_and_b32_e32 v185, 0xffff0000, v186
	v_lshlrev_b32_e32 v186, 16, v187
	v_and_b32_e32 v187, 0xffff0000, v187
	v_pk_fma_f32 v[168:169], v[56:57], v[182:183], v[168:169]
	v_pk_fma_f32 v[166:167], v[54:55], v[180:181], v[166:167]
	v_pk_fma_f32 v[178:179], v[52:53], v[186:187], v[178:179]
	v_pk_fma_f32 v[176:177], v[50:51], v[184:185], v[176:177]
	v_cvt_pk_bf16_f32 v166, v166, v167
	v_cvt_pk_bf16_f32 v167, v168, v169
	v_lshlrev_b32_e32 v180, 16, v196
	v_cvt_pk_bf16_f32 v168, v176, v177
	v_cvt_pk_bf16_f32 v169, v178, v179
	global_store_dwordx4 v[188:189], v[166:169], off offset:256
	v_and_b32_e32 v181, 0xffff0000, v196
	v_lshlrev_b32_e32 v182, 16, v197
	v_lshlrev_b32_e32 v166, 16, v192
	v_and_b32_e32 v167, 0xffff0000, v192
	v_lshlrev_b32_e32 v168, 16, v193
	v_and_b32_e32 v169, 0xffff0000, v193
	v_and_b32_e32 v183, 0xffff0000, v197
	v_lshlrev_b32_e32 v176, 16, v194
	v_and_b32_e32 v177, 0xffff0000, v194
	v_lshlrev_b32_e32 v178, 16, v195
	v_and_b32_e32 v179, 0xffff0000, v195
	v_lshlrev_b32_e32 v184, 16, v198
	v_and_b32_e32 v185, 0xffff0000, v198
	v_lshlrev_b32_e32 v186, 16, v199
	v_and_b32_e32 v187, 0xffff0000, v199
	v_pk_fma_f32 v[168:169], v[48:49], v[182:183], v[168:169]
	v_pk_fma_f32 v[166:167], v[46:47], v[180:181], v[166:167]
	v_pk_fma_f32 v[178:179], v[44:45], v[186:187], v[178:179]
	v_pk_fma_f32 v[176:177], v[42:43], v[184:185], v[176:177]
	v_cvt_pk_bf16_f32 v166, v166, v167
	v_cvt_pk_bf16_f32 v167, v168, v169
	v_lshlrev_b32_e32 v180, 16, v204
	v_cvt_pk_bf16_f32 v168, v176, v177
	v_cvt_pk_bf16_f32 v169, v178, v179
	global_store_dwordx4 v[208:209], v[166:169], off
	v_and_b32_e32 v181, 0xffff0000, v204
	v_lshlrev_b32_e32 v182, 16, v205
	v_lshlrev_b32_e32 v166, 16, v200
	v_and_b32_e32 v167, 0xffff0000, v200
	v_lshlrev_b32_e32 v168, 16, v201
	v_and_b32_e32 v169, 0xffff0000, v201
	v_and_b32_e32 v183, 0xffff0000, v205
	v_lshlrev_b32_e32 v176, 16, v202
	v_and_b32_e32 v177, 0xffff0000, v202
	v_lshlrev_b32_e32 v178, 16, v203
	v_and_b32_e32 v179, 0xffff0000, v203
	v_lshlrev_b32_e32 v184, 16, v206
	v_and_b32_e32 v185, 0xffff0000, v206
	v_lshlrev_b32_e32 v186, 16, v207
	v_and_b32_e32 v187, 0xffff0000, v207
	v_pk_fma_f32 v[168:169], v[40:41], v[182:183], v[168:169]
	v_pk_fma_f32 v[166:167], v[38:39], v[180:181], v[166:167]
	v_add_co_u32_e32 v188, vcc, s89, v160
	v_pk_fma_f32 v[178:179], v[36:37], v[186:187], v[178:179]
	v_pk_fma_f32 v[176:177], v[34:35], v[184:185], v[176:177]
	v_cvt_pk_bf16_f32 v166, v166, v167
	v_cvt_pk_bf16_f32 v167, v168, v169
	v_addc_co_u32_e32 v189, vcc, 0, v161, vcc
	v_cvt_pk_bf16_f32 v168, v176, v177
	v_cvt_pk_bf16_f32 v169, v178, v179
	global_store_dwordx4 v[208:209], v[166:169], off offset:256
	v_add_co_u32_e32 v176, vcc, s76, v162
	global_load_dwordx4 v[166:169], v[188:189], off
	s_nop 0
	v_addc_co_u32_e32 v177, vcc, 0, v163, vcc
	global_load_dwordx4 v[176:179], v[176:177], off
	s_nop 0
	global_load_dwordx4 v[180:183], v[188:189], off offset:256
	v_add_co_u32_e32 v184, vcc, s77, v162
	s_waitcnt vmcnt(0) lgkmcnt(0)
; __device__ __forceinline__ u32x4 pack8(const f32x4 a, const f32x4 b) { u32x4 w; w.x = pk2(a[0], a[1]); w.y = pk2(a[2], a[3]); w.z = pk2(b[0], b[1]); w.w = pk2(b[2], b[3]); return w; }
; __device__ __forceinline__ void unpack8(const u32x4 w, f32x4& a, f32x4& b) { a = (f32x4){bflo(w.x), bfhi(w.x), bflo(w.y), bfhi(w.y)}; b = (f32x4){bflo(w.z), bfhi(w.z), bflo(w.w), bfhi(w.w)}; }
;     __device__ __forceinline__ void operator()(const Acc& acc, const Unit& u, int wr, int wc, int fr, int fq) const {
;     ...
;         } else {
; #pragma unroll
;             for (int ai = 0; ai < 2; ++ai)
; #pragma unroll
;                 for (int mp = 0; mp < 2; ++mp) {
;                     u32x4 c[2][2], s[2][2];
; #pragma unroll
;                     for (int mm = 0; mm < 2; ++mm)
; #pragma unroll
;                         for (int bj = 0; bj < 2; ++bj) { c[mm][bj] = *MP(ai, 2 * mp + mm, bj); s[mm][bj] = *SP(ai, 2 * mp + mm, bj); }
; #pragma unroll
;                     for (int mm = 0; mm < 2; ++mm)
; #pragma unroll
;                         for (int bj = 0; bj < 2; ++bj) { const int m = 2 * mp + mm; f32x4 c0, c1, s0, s1; unpack8(c[mm][bj], c0, c1); unpack8(s[mm][bj], s0, s1);
;                             *MP(ai, m, bj) = pack8(c0 + s0 * acc[ai][bj][m][0], c1 + s1 * acc[ai][bj][m][1]); }
;                     asm volatile("" ::: "memory");
;                 }
	v_lshlrev_b32_e32 v210, 16, v166
	v_addc_co_u32_e32 v185, vcc, 0, v163, vcc
	global_load_dwordx4 v[184:187], v[184:185], off
	v_add_co_u32_e32 v208, vcc, s90, v160
	v_and_b32_e32 v211, 0xffff0000, v166
	s_nop 0
	v_addc_co_u32_e32 v209, vcc, 0, v161, vcc
	v_add_co_u32_e32 v196, vcc, s80, v162
	global_load_dwordx4 v[192:195], v[208:209], off
	s_nop 0
	v_addc_co_u32_e32 v197, vcc, 0, v163, vcc
	global_load_dwordx4 v[196:199], v[196:197], off
	s_nop 0
	global_load_dwordx4 v[200:203], v[208:209], off offset:256
	v_add_co_u32_e32 v204, vcc, s81, v162
	v_lshlrev_b32_e32 v166, 16, v167
	s_nop 0
	v_addc_co_u32_e32 v205, vcc, 0, v163, vcc
	global_load_dwordx4 v[204:207], v[204:205], off
	v_and_b32_e32 v167, 0xffff0000, v167
	v_lshlrev_b32_e32 v212, 16, v168
	v_and_b32_e32 v213, 0xffff0000, v168
	v_lshlrev_b32_e32 v168, 16, v169
	v_and_b32_e32 v169, 0xffff0000, v169
	v_lshlrev_b32_e32 v214, 16, v176
	v_and_b32_e32 v215, 0xffff0000, v176
	v_lshlrev_b32_e32 v176, 16, v177
	v_and_b32_e32 v177, 0xffff0000, v177
	v_lshlrev_b32_e32 v216, 16, v178
	v_and_b32_e32 v217, 0xffff0000, v178
	v_lshlrev_b32_e32 v178, 16, v179
	v_and_b32_e32 v179, 0xffff0000, v179
	v_pk_fma_f32 v[176:177], v[32:33], v[176:177], v[166:167]
	v_pk_fma_f32 v[166:167], v[30:31], v[214:215], v[210:211]
	v_pk_fma_f32 v[178:179], v[28:29], v[178:179], v[168:169]
	v_pk_fma_f32 v[168:169], v[26:27], v[216:217], v[212:213]
	v_cvt_pk_bf16_f32 v166, v166, v167
	v_cvt_pk_bf16_f32 v167, v176, v177
	v_lshlrev_b32_e32 v176, 16, v182
	v_cvt_pk_bf16_f32 v168, v168, v169
	v_cvt_pk_bf16_f32 v169, v178, v179
	global_store_dwordx4 v[188:189], v[166:169], off
	v_and_b32_e32 v177, 0xffff0000, v182
	v_lshlrev_b32_e32 v178, 16, v183
	v_lshlrev_b32_e32 v166, 16, v180
	v_and_b32_e32 v167, 0xffff0000, v180
	v_lshlrev_b32_e32 v168, 16, v181
	v_and_b32_e32 v169, 0xffff0000, v181
	v_and_b32_e32 v179, 0xffff0000, v183
	s_waitcnt vmcnt(0) lgkmcnt(0)
	v_lshlrev_b32_e32 v180, 16, v184
	v_and_b32_e32 v181, 0xffff0000, v184
	v_lshlrev_b32_e32 v182, 16, v185
	v_and_b32_e32 v183, 0xffff0000, v185
	v_lshlrev_b32_e32 v184, 16, v186
	v_and_b32_e32 v185, 0xffff0000, v186
	v_lshlrev_b32_e32 v186, 16, v187
	v_and_b32_e32 v187, 0xffff0000, v187
	v_pk_fma_f32 v[168:169], v[24:25], v[182:183], v[168:169]
	v_pk_fma_f32 v[166:167], v[22:23], v[180:181], v[166:167]
	v_pk_fma_f32 v[178:179], v[20:21], v[186:187], v[178:179]
	v_pk_fma_f32 v[176:177], v[18:19], v[184:185], v[176:177]
	v_cvt_pk_bf16_f32 v166, v166, v167
	v_cvt_pk_bf16_f32 v167, v168, v169
	v_lshlrev_b32_e32 v180, 16, v196
	v_cvt_pk_bf16_f32 v168, v176, v177
	v_cvt_pk_bf16_f32 v169, v178, v179
	global_store_dwordx4 v[188:189], v[166:169], off offset:256
	v_and_b32_e32 v181, 0xffff0000, v196
	v_lshlrev_b32_e32 v182, 16, v197
	v_lshlrev_b32_e32 v166, 16, v192
	v_and_b32_e32 v167, 0xffff0000, v192
	v_lshlrev_b32_e32 v168, 16, v193
	v_and_b32_e32 v169, 0xffff0000, v193
	v_and_b32_e32 v183, 0xffff0000, v197
	v_lshlrev_b32_e32 v176, 16, v194
	v_and_b32_e32 v177, 0xffff0000, v194
	v_lshlrev_b32_e32 v178, 16, v195
	v_and_b32_e32 v179, 0xffff0000, v195
	v_lshlrev_b32_e32 v184, 16, v198
	v_and_b32_e32 v185, 0xffff0000, v198
	v_lshlrev_b32_e32 v186, 16, v199
	v_and_b32_e32 v187, 0xffff0000, v199
	v_pk_fma_f32 v[168:169], v[16:17], v[182:183], v[168:169]
	v_pk_fma_f32 v[166:167], v[14:15], v[180:181], v[166:167]
	v_pk_fma_f32 v[178:179], v[12:13], v[186:187], v[178:179]
	v_pk_fma_f32 v[176:177], v[10:11], v[184:185], v[176:177]
	v_cvt_pk_bf16_f32 v166, v166, v167
	v_cvt_pk_bf16_f32 v167, v168, v169
	v_lshlrev_b32_e32 v180, 16, v204
	v_cvt_pk_bf16_f32 v168, v176, v177
	v_cvt_pk_bf16_f32 v169, v178, v179
	global_store_dwordx4 v[208:209], v[166:169], off
	v_and_b32_e32 v181, 0xffff0000, v204
	v_lshlrev_b32_e32 v182, 16, v205
	v_lshlrev_b32_e32 v166, 16, v200
	v_and_b32_e32 v167, 0xffff0000, v200
	v_lshlrev_b32_e32 v168, 16, v201
	v_and_b32_e32 v169, 0xffff0000, v201
	v_and_b32_e32 v183, 0xffff0000, v205
	v_lshlrev_b32_e32 v176, 16, v202
	v_and_b32_e32 v177, 0xffff0000, v202
	v_lshlrev_b32_e32 v178, 16, v203
	v_and_b32_e32 v179, 0xffff0000, v203
	v_lshlrev_b32_e32 v184, 16, v206
	v_and_b32_e32 v185, 0xffff0000, v206
	v_lshlrev_b32_e32 v186, 16, v207
	v_and_b32_e32 v187, 0xffff0000, v207
	v_pk_fma_f32 v[168:169], v[8:9], v[182:183], v[168:169]
	v_pk_fma_f32 v[166:167], v[6:7], v[180:181], v[166:167]
	v_pk_fma_f32 v[178:179], v[4:5], v[186:187], v[178:179]
	v_pk_fma_f32 v[176:177], v[2:3], v[184:185], v[176:177]
	v_cvt_pk_bf16_f32 v166, v166, v167
	v_cvt_pk_bf16_f32 v167, v168, v169
	s_nop 0
	v_cvt_pk_bf16_f32 v168, v176, v177
	v_cvt_pk_bf16_f32 v169, v178, v179
	global_store_dwordx4 v[208:209], v[166:169], off offset:256
; __device__ __forceinline__ u32x4 pack8(const f32x4 a, const f32x4 b) { u32x4 w; w.x = pk2(a[0], a[1]); w.y = pk2(a[2], a[3]); w.z = pk2(b[0], b[1]); w.w = pk2(b[2], b[3]); return w; }
; __device__ __forceinline__ void unpack8(const u32x4 w, f32x4& a, f32x4& b) { a = (f32x4){bflo(w.x), bfhi(w.x), bflo(w.y), bfhi(w.y)}; b = (f32x4){bflo(w.z), bfhi(w.z), bflo(w.w), bfhi(w.w)}; }
;     __device__ __forceinline__ void operator()(const Acc& acc, const Unit& u, int wr, int wc, int fr, int fq) const {
;     ...
;         } else if (sub == 1) {
; #pragma unroll
;             for (int ai = 0; ai < 2; ++ai) {
;                 u32x4 g[4][2];
; #pragma unroll
;                 for (int m = 0; m < 4; ++m)
; #pragma unroll
;                     for (int bj = 0; bj < 2; ++bj) g[m][bj] = *MP(ai, m, bj);
; #pragma unroll
;                 for (int m = 0; m < 4; ++m)
; #pragma unroll
;                     for (int bj = 0; bj < 2; ++bj) { f32x4 g0, g1; unpack8(g[m][bj], g0, g1); *MP(ai, m, bj) = pack8(g0 * acc[ai][bj][m][0], g1 * acc[ai][bj][m][1]); }
;                 asm volatile("" ::: "memory");
;             }
.LBB0_5783:
	s_andn2_b64 vcc, exec, s[4:5]
	s_cbranch_vccnz .LBB0_5785
	global_load_dwordx4 v[176:179], v[160:161], off offset:256
	v_add_co_u32_e32 v168, vcc, 0x8000, v160
	v_pk_mul_f32 v[208:209], v[124:125], v[134:135]
	s_nop 0
	v_addc_co_u32_e32 v169, vcc, 0, v161, vcc
	global_load_dwordx4 v[180:183], v[168:169], off
	global_load_dwordx4 v[184:187], v[168:169], off offset:256
	v_add_co_u32_e32 v166, vcc, 0x10000, v160
	v_pk_mul_f32 v[188:189], v[126:127], v[132:133]
	s_nop 0
	v_addc_co_u32_e32 v167, vcc, 0, v161, vcc
	global_load_dwordx4 v[192:195], v[166:167], off
	global_load_dwordx4 v[196:199], v[166:167], off offset:256
	v_add_co_u32_e32 v134, vcc, 0x18000, v160
	v_pk_mul_f32 v[206:207], v[122:123], v[130:131]
	s_nop 0
	v_addc_co_u32_e32 v135, vcc, 0, v161, vcc
	global_load_dwordx4 v[200:203], v[134:135], off
	global_load_dwordx4 v[130:133], v[134:135], off offset:256
	v_pk_mul_f32 v[136:137], v[128:129], v[136:137]
	v_cvt_pk_bf16_f32 v204, v188, v189
	s_waitcnt vmcnt(0) lgkmcnt(0)
	v_lshlrev_b32_e32 v188, 16, v178
	v_cvt_pk_bf16_f32 v205, v136, v137
	v_cvt_pk_bf16_f32 v206, v206, v207
	v_cvt_pk_bf16_f32 v207, v208, v209
	v_lshlrev_b32_e32 v136, 16, v176
	v_and_b32_e32 v137, 0xffff0000, v176
	v_and_b32_e32 v189, 0xffff0000, v178
	v_lshlrev_b32_e32 v178, 16, v179
	v_and_b32_e32 v179, 0xffff0000, v179
	global_store_dwordx4 v[160:161], v[204:207], off
	v_lshlrev_b32_e32 v176, 16, v177
	v_and_b32_e32 v177, 0xffff0000, v177
	v_pk_mul_f32 v[136:137], v[118:119], v[136:137]
	v_pk_mul_f32 v[206:207], v[116:117], v[178:179]
	v_pk_mul_f32 v[178:179], v[114:115], v[188:189]
	v_pk_mul_f32 v[204:205], v[120:121], v[176:177]
	v_cvt_pk_bf16_f32 v176, v136, v137
	v_lshlrev_b32_e32 v136, 16, v180
	v_cvt_pk_bf16_f32 v177, v204, v205
	v_cvt_pk_bf16_f32 v178, v178, v179
	v_cvt_pk_bf16_f32 v179, v206, v207
	v_and_b32_e32 v137, 0xffff0000, v180
	v_lshlrev_b32_e32 v180, 16, v181
	v_and_b32_e32 v181, 0xffff0000, v181
	v_lshlrev_b32_e32 v188, 16, v182
	v_and_b32_e32 v189, 0xffff0000, v182
	v_lshlrev_b32_e32 v182, 16, v183
	v_and_b32_e32 v183, 0xffff0000, v183
	global_store_dwordx4 v[160:161], v[176:179], off offset:256
	v_lshlrev_b32_e32 v204, 16, v184
	v_and_b32_e32 v205, 0xffff0000, v184
	v_pk_mul_f32 v[178:179], v[112:113], v[180:181]
	v_lshlrev_b32_e32 v184, 16, v185
	v_and_b32_e32 v185, 0xffff0000, v185
	v_lshlrev_b32_e32 v206, 16, v186
	v_and_b32_e32 v207, 0xffff0000, v186
	v_lshlrev_b32_e32 v186, 16, v187
	v_and_b32_e32 v187, 0xffff0000, v187
	v_pk_mul_f32 v[136:137], v[110:111], v[136:137]
	v_pk_mul_f32 v[180:181], v[108:109], v[182:183]
	v_pk_mul_f32 v[182:183], v[106:107], v[188:189]
	v_cvt_pk_bf16_f32 v176, v136, v137
	v_cvt_pk_bf16_f32 v177, v178, v179
	v_pk_mul_f32 v[184:185], v[104:105], v[184:185]
	v_cvt_pk_bf16_f32 v178, v182, v183
	v_cvt_pk_bf16_f32 v179, v180, v181
	v_pk_mul_f32 v[188:189], v[102:103], v[204:205]
	v_pk_mul_f32 v[186:187], v[100:101], v[186:187]
	v_pk_mul_f32 v[204:205], v[98:99], v[206:207]
	v_lshlrev_b32_e32 v206, 16, v192
	v_and_b32_e32 v207, 0xffff0000, v192
	v_lshlrev_b32_e32 v208, 16, v194
	global_store_dwordx4 v[168:169], v[176:179], off
	v_and_b32_e32 v209, 0xffff0000, v194
	v_lshlrev_b32_e32 v192, 16, v193
	v_cvt_pk_bf16_f32 v176, v188, v189
	v_cvt_pk_bf16_f32 v177, v184, v185
	v_cvt_pk_bf16_f32 v178, v204, v205
	v_cvt_pk_bf16_f32 v179, v186, v187
	v_and_b32_e32 v193, 0xffff0000, v193
	global_store_dwordx4 v[168:169], v[176:179], off offset:256
	v_lshlrev_b32_e32 v136, 16, v195
	v_and_b32_e32 v137, 0xffff0000, v195
	v_pk_mul_f32 v[176:177], v[94:95], v[206:207]
	v_pk_mul_f32 v[178:179], v[90:91], v[208:209]
	v_pk_mul_f32 v[168:169], v[96:97], v[192:193]
	v_pk_mul_f32 v[136:137], v[92:93], v[136:137]
	v_cvt_pk_bf16_f32 v176, v176, v177
	v_cvt_pk_bf16_f32 v177, v168, v169
	v_cvt_pk_bf16_f32 v178, v178, v179
	v_lshlrev_b32_e32 v168, 16, v197
	v_cvt_pk_bf16_f32 v179, v136, v137
	global_store_dwordx4 v[166:167], v[176:179], off
	v_lshlrev_b32_e32 v136, 16, v196
	v_and_b32_e32 v137, 0xffff0000, v196
	v_and_b32_e32 v169, 0xffff0000, v197
	v_lshlrev_b32_e32 v176, 16, v198
	v_and_b32_e32 v177, 0xffff0000, v198
	v_lshlrev_b32_e32 v178, 16, v199
	v_and_b32_e32 v179, 0xffff0000, v199
	v_pk_mul_f32 v[168:169], v[88:89], v[168:169]
	v_pk_mul_f32 v[136:137], v[86:87], v[136:137]
	v_pk_mul_f32 v[180:181], v[84:85], v[178:179]
	v_pk_mul_f32 v[178:179], v[82:83], v[176:177]
	v_cvt_pk_bf16_f32 v176, v136, v137
	v_cvt_pk_bf16_f32 v177, v168, v169
	v_lshlrev_b32_e32 v136, 16, v200
	v_cvt_pk_bf16_f32 v178, v178, v179
	v_cvt_pk_bf16_f32 v179, v180, v181
	global_store_dwordx4 v[166:167], v[176:179], off offset:256
	v_and_b32_e32 v137, 0xffff0000, v200
	v_lshlrev_b32_e32 v166, 16, v201
	v_and_b32_e32 v167, 0xffff0000, v201
	v_lshlrev_b32_e32 v168, 16, v202
	v_and_b32_e32 v169, 0xffff0000, v202
	v_lshlrev_b32_e32 v176, 16, v203
	v_and_b32_e32 v177, 0xffff0000, v203
	v_pk_mul_f32 v[178:179], v[80:81], v[166:167]
	v_pk_mul_f32 v[136:137], v[78:79], v[136:137]
	v_pk_mul_f32 v[168:169], v[74:75], v[168:169]
	v_cvt_pk_bf16_f32 v166, v136, v137
	v_cvt_pk_bf16_f32 v167, v178, v179
	v_pk_mul_f32 v[176:177], v[76:77], v[176:177]
	v_cvt_pk_bf16_f32 v168, v168, v169
	v_lshlrev_b32_e32 v136, 16, v130
	v_cvt_pk_bf16_f32 v169, v176, v177
	global_store_dwordx4 v[134:135], v[166:169], off
	v_and_b32_e32 v137, 0xffff0000, v130
	v_lshlrev_b32_e32 v130, 16, v131
	v_and_b32_e32 v131, 0xffff0000, v131
	v_lshlrev_b32_e32 v166, 16, v132
	v_and_b32_e32 v167, 0xffff0000, v132
	v_lshlrev_b32_e32 v132, 16, v133
	v_and_b32_e32 v133, 0xffff0000, v133
	v_pk_mul_f32 v[168:169], v[72:73], v[130:131]
	v_pk_mul_f32 v[130:131], v[70:71], v[136:137]
	v_pk_mul_f32 v[136:137], v[68:69], v[132:133]
	v_pk_mul_f32 v[132:133], v[66:67], v[166:167]
	v_cvt_pk_bf16_f32 v130, v130, v131
	v_cvt_pk_bf16_f32 v131, v168, v169
	v_add_co_u32_e32 v188, vcc, s87, v160
	v_cvt_pk_bf16_f32 v132, v132, v133
	v_cvt_pk_bf16_f32 v133, v136, v137
	global_store_dwordx4 v[134:135], v[130:133], off offset:256
	s_nop 0
	v_addc_co_u32_e32 v189, vcc, 0, v161, vcc
	global_load_dwordx4 v[176:179], v[188:189], off
	global_load_dwordx4 v[180:183], v[188:189], off offset:256
	v_add_co_u32_e32 v204, vcc, s88, v160
	s_waitcnt vmcnt(0) lgkmcnt(0)
; __device__ __forceinline__ u32x4 pack8(const f32x4 a, const f32x4 b) { u32x4 w; w.x = pk2(a[0], a[1]); w.y = pk2(a[2], a[3]); w.z = pk2(b[0], b[1]); w.w = pk2(b[2], b[3]); return w; }
; __device__ __forceinline__ void unpack8(const u32x4 w, f32x4& a, f32x4& b) { a = (f32x4){bflo(w.x), bfhi(w.x), bflo(w.y), bfhi(w.y)}; b = (f32x4){bflo(w.z), bfhi(w.z), bflo(w.w), bfhi(w.w)}; }
;     __device__ __forceinline__ void operator()(const Acc& acc, const Unit& u, int wr, int wc, int fr, int fq) const {
;     ...
;                     for (int bj = 0; bj < 2; ++bj) g[m][bj] = *MP(ai, m, bj);
; #pragma unroll
;                 for (int m = 0; m < 4; ++m)
; #pragma unroll
;                     for (int bj = 0; bj < 2; ++bj) { f32x4 g0, g1; unpack8(g[m][bj], g0, g1); *MP(ai, m, bj) = pack8(g0 * acc[ai][bj][m][0], g1 * acc[ai][bj][m][1]); }
;                 asm volatile("" ::: "memory");
	v_lshlrev_b32_e32 v206, 16, v176
	v_addc_co_u32_e32 v205, vcc, 0, v161, vcc
	global_load_dwordx4 v[184:187], v[204:205], off
	global_load_dwordx4 v[192:195], v[204:205], off offset:256
	v_add_co_u32_e32 v168, vcc, s89, v160
	v_and_b32_e32 v207, 0xffff0000, v176
	s_nop 0
	v_addc_co_u32_e32 v169, vcc, 0, v161, vcc
	global_load_dwordx4 v[196:199], v[168:169], off
	global_load_dwordx4 v[200:203], v[168:169], off offset:256
	v_add_co_u32_e32 v166, vcc, s90, v160
	v_lshlrev_b32_e32 v176, 16, v177
	s_nop 0
	v_addc_co_u32_e32 v167, vcc, 0, v161, vcc
	global_load_dwordx4 v[134:137], v[166:167], off
	global_load_dwordx4 v[130:133], v[166:167], off offset:256
	v_and_b32_e32 v177, 0xffff0000, v177
	v_lshlrev_b32_e32 v208, 16, v178
	v_and_b32_e32 v209, 0xffff0000, v178
	v_lshlrev_b32_e32 v178, 16, v179
	v_and_b32_e32 v179, 0xffff0000, v179
	v_pk_mul_f32 v[210:211], v[64:65], v[176:177]
	v_pk_mul_f32 v[176:177], v[62:63], v[206:207]
	v_pk_mul_f32 v[206:207], v[60:61], v[178:179]
	v_pk_mul_f32 v[178:179], v[58:59], v[208:209]
	v_cvt_pk_bf16_f32 v176, v176, v177
	v_cvt_pk_bf16_f32 v177, v210, v211
	s_nop 0
	v_cvt_pk_bf16_f32 v178, v178, v179
	v_cvt_pk_bf16_f32 v179, v206, v207
	global_store_dwordx4 v[188:189], v[176:179], off
	s_nop 1
	v_lshlrev_b32_e32 v176, 16, v180
	v_and_b32_e32 v177, 0xffff0000, v180
	v_lshlrev_b32_e32 v178, 16, v181
	v_and_b32_e32 v179, 0xffff0000, v181
	v_pk_mul_f32 v[176:177], v[54:55], v[176:177]
	v_lshlrev_b32_e32 v180, 16, v182
	v_and_b32_e32 v181, 0xffff0000, v182
	v_lshlrev_b32_e32 v182, 16, v183
	v_and_b32_e32 v183, 0xffff0000, v183
	v_pk_mul_f32 v[178:179], v[56:57], v[178:179]
	v_cvt_pk_bf16_f32 v176, v176, v177
	v_pk_mul_f32 v[182:183], v[52:53], v[182:183]
	v_cvt_pk_bf16_f32 v177, v178, v179
	v_pk_mul_f32 v[180:181], v[50:51], v[180:181]
	s_nop 0
	v_cvt_pk_bf16_f32 v178, v180, v181
	v_cvt_pk_bf16_f32 v179, v182, v183
	global_store_dwordx4 v[188:189], v[176:179], off offset:256
	s_waitcnt vmcnt(0) lgkmcnt(0)
	v_lshlrev_b32_e32 v180, 16, v186
	v_lshlrev_b32_e32 v176, 16, v184
	v_and_b32_e32 v177, 0xffff0000, v184
	v_lshlrev_b32_e32 v178, 16, v185
	v_and_b32_e32 v179, 0xffff0000, v185
	v_pk_mul_f32 v[176:177], v[46:47], v[176:177]
	v_and_b32_e32 v181, 0xffff0000, v186
	v_lshlrev_b32_e32 v182, 16, v187
	v_and_b32_e32 v183, 0xffff0000, v187
	v_pk_mul_f32 v[178:179], v[48:49], v[178:179]
	v_cvt_pk_bf16_f32 v176, v176, v177
	v_pk_mul_f32 v[182:183], v[44:45], v[182:183]
	v_cvt_pk_bf16_f32 v177, v178, v179
	v_pk_mul_f32 v[180:181], v[42:43], v[180:181]
	s_nop 0
	v_cvt_pk_bf16_f32 v178, v180, v181
	v_cvt_pk_bf16_f32 v179, v182, v183
	global_store_dwordx4 v[204:205], v[176:179], off
	v_lshlrev_b32_e32 v180, 16, v194
	v_and_b32_e32 v181, 0xffff0000, v194
	v_lshlrev_b32_e32 v176, 16, v192
	v_and_b32_e32 v177, 0xffff0000, v192
	v_lshlrev_b32_e32 v178, 16, v193
	v_and_b32_e32 v179, 0xffff0000, v193
	v_pk_mul_f32 v[176:177], v[38:39], v[176:177]
	v_lshlrev_b32_e32 v182, 16, v195
	v_and_b32_e32 v183, 0xffff0000, v195
	v_pk_mul_f32 v[178:179], v[40:41], v[178:179]
	v_cvt_pk_bf16_f32 v176, v176, v177
	v_pk_mul_f32 v[182:183], v[36:37], v[182:183]
	v_cvt_pk_bf16_f32 v177, v178, v179
	v_pk_mul_f32 v[180:181], v[34:35], v[180:181]
	s_nop 0
	v_cvt_pk_bf16_f32 v178, v180, v181
	v_cvt_pk_bf16_f32 v179, v182, v183
	global_store_dwordx4 v[204:205], v[176:179], off offset:256
	v_lshlrev_b32_e32 v180, 16, v198
	v_and_b32_e32 v181, 0xffff0000, v198
	v_lshlrev_b32_e32 v176, 16, v196
	v_and_b32_e32 v177, 0xffff0000, v196
	v_lshlrev_b32_e32 v178, 16, v197
	v_and_b32_e32 v179, 0xffff0000, v197
	v_pk_mul_f32 v[176:177], v[30:31], v[176:177]
	v_lshlrev_b32_e32 v182, 16, v199
	v_and_b32_e32 v183, 0xffff0000, v199
	v_pk_mul_f32 v[178:179], v[32:33], v[178:179]
	v_cvt_pk_bf16_f32 v176, v176, v177
	v_pk_mul_f32 v[182:183], v[28:29], v[182:183]
	v_cvt_pk_bf16_f32 v177, v178, v179
	v_pk_mul_f32 v[180:181], v[26:27], v[180:181]
	s_nop 0
	v_cvt_pk_bf16_f32 v178, v180, v181
	v_cvt_pk_bf16_f32 v179, v182, v183
	global_store_dwordx4 v[168:169], v[176:179], off
	v_lshlrev_b32_e32 v180, 16, v202
	v_and_b32_e32 v181, 0xffff0000, v202
	v_lshlrev_b32_e32 v176, 16, v200
	v_and_b32_e32 v177, 0xffff0000, v200
	v_lshlrev_b32_e32 v178, 16, v201
	v_and_b32_e32 v179, 0xffff0000, v201
	v_pk_mul_f32 v[176:177], v[22:23], v[176:177]
	v_lshlrev_b32_e32 v182, 16, v203
	v_and_b32_e32 v183, 0xffff0000, v203
	v_pk_mul_f32 v[178:179], v[24:25], v[178:179]
	v_cvt_pk_bf16_f32 v176, v176, v177
	v_pk_mul_f32 v[182:183], v[20:21], v[182:183]
	v_cvt_pk_bf16_f32 v177, v178, v179
	v_pk_mul_f32 v[180:181], v[18:19], v[180:181]
	s_nop 0
	v_cvt_pk_bf16_f32 v178, v180, v181
	v_cvt_pk_bf16_f32 v179, v182, v183
	global_store_dwordx4 v[168:169], v[176:179], off offset:256
	v_lshlrev_b32_e32 v168, 16, v134
	v_and_b32_e32 v169, 0xffff0000, v134
	v_lshlrev_b32_e32 v134, 16, v135
	v_and_b32_e32 v135, 0xffff0000, v135
	v_lshlrev_b32_e32 v176, 16, v136
	v_and_b32_e32 v177, 0xffff0000, v136
	v_lshlrev_b32_e32 v136, 16, v137
	v_and_b32_e32 v137, 0xffff0000, v137
	v_pk_mul_f32 v[178:179], v[16:17], v[134:135]
	v_pk_mul_f32 v[134:135], v[14:15], v[168:169]
	v_pk_mul_f32 v[168:169], v[12:13], v[136:137]
	v_pk_mul_f32 v[136:137], v[10:11], v[176:177]
	v_cvt_pk_bf16_f32 v134, v134, v135
	v_cvt_pk_bf16_f32 v135, v178, v179
	s_nop 0
	v_cvt_pk_bf16_f32 v136, v136, v137
	v_cvt_pk_bf16_f32 v137, v168, v169
	global_store_dwordx4 v[166:167], v[134:137], off
	s_nop 1
	v_lshlrev_b32_e32 v134, 16, v130
	v_and_b32_e32 v135, 0xffff0000, v130
	v_lshlrev_b32_e32 v130, 16, v131
	v_and_b32_e32 v131, 0xffff0000, v131
	v_lshlrev_b32_e32 v136, 16, v132
	v_and_b32_e32 v137, 0xffff0000, v132
	v_lshlrev_b32_e32 v132, 16, v133
	v_and_b32_e32 v133, 0xffff0000, v133
	v_pk_mul_f32 v[168:169], v[8:9], v[130:131]
	v_pk_mul_f32 v[130:131], v[6:7], v[134:135]
	v_pk_mul_f32 v[134:135], v[4:5], v[132:133]
	v_pk_mul_f32 v[132:133], v[2:3], v[136:137]
	v_cvt_pk_bf16_f32 v130, v130, v131
	v_cvt_pk_bf16_f32 v131, v168, v169
	s_nop 0
	v_cvt_pk_bf16_f32 v132, v132, v133
	v_cvt_pk_bf16_f32 v133, v134, v135
	global_store_dwordx4 v[166:167], v[130:133], off offset:256

; __device__ __forceinline__ float xsum16(float s) { const auto r = __builtin_amdgcn_permlane16_swap(__float_as_uint(s), __float_as_uint(s), false, false); return __uint_as_float(r[0]) + __uint_as_float(r[1]); }
; __device__ __forceinline__ float xsum32(float s) { const auto r = __builtin_amdgcn_permlane32_swap(__float_as_uint(s), __float_as_uint(s), false, false); return __uint_as_float(r[0]) + __uint_as_float(r[1]); }
; __device__ __forceinline__ float sigmoidf_(float x) { return __builtin_amdgcn_rcpf(1.0f + __builtin_amdgcn_exp2f(-1.4426950408889634f * x)); }
; __device__ __forceinline__ u32x4 pack8(const f32x4 a, const f32x4 b) { u32x4 w; w.x = pk2(a[0], a[1]); w.y = pk2(a[2], a[3]); w.z = pk2(b[0], b[1]); w.w = pk2(b[2], b[3]); return w; }
; __device__ __forceinline__ void rstd8(const float* ssq, int row0, int fq, float (&rs)[8]) {
;     f32x4 pr[8];
; #pragma unroll
;     for (int i = 0; i < 8; ++i) pr[i] = *(const f32x4*)(ssq + (size_t)(row0 + (i >> 2) * 128 + (i & 3) * 16) * 16 + 4 * fq);
; #pragma unroll
;     for (int i = 0; i < 8; ++i) { float s = (pr[i][0] + pr[i][1]) + (pr[i][2] + pr[i][3]); s = xsum16(s); s = xsum32(s); rs[i] = __builtin_amdgcn_rsqf(s * (1.0f / DM) + NORM_EPS); }
; }
;     __device__ __forceinline__ void operator()(const Acc& acc, const Unit& u, int wr, int wc, int fr, int fq) const {
;     ...
;         if ((sub & 1) == 0) {
;             float rs[8]; rstd8(ssq, row0, fq, rs);
; #pragma unroll
;             for (int ai = 0; ai < 2; ++ai)
; #pragma unroll
;                 for (int m = 0; m < 4; ++m) {
;                     const float r1 = rs[ai * 4 + m];
; #pragma unroll
;                     for (int bj = 0; bj < 2; ++bj) {
;                         f32x4 s0, s1; const f32x4 v0 = acc[ai][bj][m][0], v1 = acc[ai][bj][m][1];
; #pragma unroll
;                         for (int e = 0; e < 4; ++e) { s0[e] = sigmoidf_(v0[e] * r1); s1[e] = sigmoidf_(v1[e] * r1); }
;                         if (sub == 0) *MP(ai, m, bj) = pack8(s0, s1); else *SP(ai, m, bj) = pack8(s0, s1);
.LBB0_5786:
	s_andn2_b64 vcc, exec, s[4:5]
	s_cbranch_vccnz .LBB0_5835
	v_lshlrev_b64 v[130:131], 6, v[164:165]
	v_lshl_add_u64 v[166:167], v[150:151], 0, v[130:131]
	v_or_b32_e32 v130, 16, v164
	v_ashrrev_i32_e32 v131, 31, v130
	v_lshlrev_b64 v[130:131], 6, v[130:131]
	v_lshl_add_u64 v[134:135], v[150:151], 0, v[130:131]
	v_add_co_u32_e32 v188, vcc, s68, v166
	global_load_dwordx4 v[130:133], v[166:167], off
	s_nop 0
	global_load_dwordx4 v[134:137], v[134:135], off
	v_addc_co_u32_e32 v189, vcc, 0, v167, vcc
	global_load_dwordx4 v[166:169], v[188:189], off
	global_load_dwordx4 v[176:179], v[188:189], off offset:1024
	v_or_b32_e32 v180, 32, v164
	v_ashrrev_i32_e32 v181, 31, v180
	v_lshlrev_b64 v[184:185], 6, v[180:181]
	global_load_dwordx4 v[180:183], v[188:189], off offset:2048
	v_or_b32_e32 v164, 48, v164
	v_ashrrev_i32_e32 v165, 31, v164
	v_lshl_add_u64 v[184:185], v[150:151], 0, v[184:185]
	v_lshlrev_b64 v[164:165], 6, v[164:165]
	global_load_dwordx4 v[184:187], v[184:185], off
	v_lshl_add_u64 v[164:165], v[150:151], 0, v[164:165]
	global_load_dwordx4 v[192:195], v[164:165], off
	global_load_dwordx4 v[196:199], v[188:189], off offset:3072
	s_cmp_lg_u32 s53, 0
	s_cselect_b64 s[52:53], -1, 0
	s_and_b64 vcc, exec, s[52:53]
	s_waitcnt vmcnt(0)
	v_add_f32_e32 v130, v130, v131
	v_add_f32_e32 v131, v132, v133
	v_add_f32_e32 v130, v130, v131
	v_add_f32_e32 v134, v134, v135
	v_add_f32_e32 v131, v166, v167
	v_mov_b32_e32 v167, v130
	s_nop 1
	v_permlane16_swap_b32_e32 v130, v167
	v_add_f32_e32 v130, v130, v167
	v_mov_b32_e32 v175, v130
	s_nop 1
	v_permlane32_swap_b32_e32 v130, v175
	v_add_f32_e32 v130, v130, v175
	v_fmamk_f32 v130, v130, 0x3a800000, v174
	v_rsq_f32_e32 v175, v130
	v_add_f32_e32 v133, v176, v177
	v_add_f32_e32 v132, v168, v169
	v_add_f32_e32 v164, v178, v179
	v_mul_f32_e32 v126, v126, v175
	v_mul_f32_e32 v122, v122, v175
	v_mul_f32_e32 v126, 0xbfb8aa3b, v126
	v_mul_f32_e32 v122, 0xbfb8aa3b, v122
	v_exp_f32_e32 v126, v126
	v_exp_f32_e32 v176, v122
	v_mul_f32_e32 v127, v127, v175
	v_mul_f32_e32 v123, v123, v175
	v_mul_f32_e32 v127, 0xbfb8aa3b, v127
	v_mul_f32_e32 v123, 0xbfb8aa3b, v123
	v_add_f32_e32 v122, 1.0, v126
	v_add_f32_e32 v126, 1.0, v176
	v_exp_f32_e32 v127, v127
	v_exp_f32_e32 v176, v123
	v_mul_f32_e32 v128, v128, v175
	v_mul_f32_e32 v124, v124, v175
	v_mul_f32_e32 v128, 0xbfb8aa3b, v128
	v_mul_f32_e32 v124, 0xbfb8aa3b, v124
	v_rcp_f32_e32 v123, v126
	v_add_f32_e32 v126, 1.0, v127
	v_add_f32_e32 v127, 1.0, v176
	v_exp_f32_e32 v128, v128
	v_exp_f32_e32 v176, v124
	v_mul_f32_e32 v129, v129, v175
	v_add_f32_e32 v165, v180, v181
	v_add_f32_e32 v166, v182, v183
	v_mul_f32_e32 v129, 0xbfb8aa3b, v129
	v_mul_f32_e32 v125, v125, v175
	v_add_f32_e32 v135, v136, v137
	v_add_f32_e32 v131, v131, v132
	v_add_f32_e32 v132, v133, v164
	v_add_f32_e32 v133, v165, v166
	v_exp_f32_e32 v129, v129
	v_mul_f32_e32 v125, 0xbfb8aa3b, v125
	v_add_f32_e32 v135, v134, v135
	v_mov_b32_e32 v134, v131
	v_mov_b32_e32 v165, v132
	v_mov_b32_e32 v130, v133
	v_rcp_f32_e32 v124, v127
	v_add_f32_e32 v127, 1.0, v128
	v_add_f32_e32 v128, 1.0, v176
	v_exp_f32_e32 v176, v125
	v_add_f32_e32 v136, v184, v185
	v_add_f32_e32 v137, v186, v187
	v_permlane16_swap_b32_e32 v131, v134
	v_permlane16_swap_b32_e32 v132, v165
	v_permlane16_swap_b32_e32 v133, v130
	v_add_f32_e32 v168, v192, v193
	v_add_f32_e32 v169, v194, v195
	v_add_f32_e32 v137, v136, v137
	v_add_f32_e32 v136, v131, v134
	v_add_f32_e32 v134, v132, v165
	v_add_f32_e32 v132, v133, v130
	v_add_f32_e32 v130, v196, v197
	v_add_f32_e32 v131, v198, v199
	v_add_f32_e32 v164, v168, v169
	v_add_f32_e32 v130, v130, v131
	v_rcp_f32_e32 v125, v128
	v_add_f32_e32 v128, 1.0, v129
	v_mov_b32_e32 v166, v135
	v_mov_b32_e32 v167, v137
	v_mov_b32_e32 v169, v164
	v_mov_b32_e32 v131, v130
	v_rcp_f32_e32 v129, v128
	v_add_f32_e32 v128, 1.0, v176
	v_permlane16_swap_b32_e32 v135, v166
	v_permlane16_swap_b32_e32 v137, v167
	v_permlane16_swap_b32_e32 v164, v169
	v_permlane16_swap_b32_e32 v130, v131
	v_rcp_f32_e32 v122, v122
	v_rcp_f32_e32 v126, v126
	v_rcp_f32_e32 v127, v127
	v_rcp_f32_e32 v128, v128
	v_add_f32_e32 v168, v135, v166
	v_add_f32_e32 v166, v137, v167
	v_add_f32_e32 v164, v164, v169
	v_add_f32_e32 v130, v130, v131
	v_mov_b32_e32 v137, v136
	v_mov_b32_e32 v135, v134
	v_mov_b32_e32 v169, v168
	v_mov_b32_e32 v167, v166
	v_mov_b32_e32 v165, v164
	v_mov_b32_e32 v133, v132
	v_mov_b32_e32 v131, v130
	v_permlane32_swap_b32_e32 v136, v137
	v_permlane32_swap_b32_e32 v134, v135
	v_permlane32_swap_b32_e32 v168, v169
	v_permlane32_swap_b32_e32 v166, v167
	v_permlane32_swap_b32_e32 v164, v165
	v_permlane32_swap_b32_e32 v132, v133
	v_permlane32_swap_b32_e32 v130, v131
	s_cbranch_vccz .LBB0_5838
	v_cvt_pk_bf16_f32 v176, v122, v126
	v_cvt_pk_bf16_f32 v177, v127, v129
	v_cvt_pk_bf16_f32 v178, v123, v124
	v_cvt_pk_bf16_f32 v179, v125, v128
	global_store_dwordx4 v[162:163], v[176:179], off
	s_cbranch_execnz .LBB0_5790
.LBB0_5789:
	s_nop 0
	v_cvt_pk_bf16_f32 v176, v122, v126
	v_cvt_pk_bf16_f32 v177, v127, v129
	v_cvt_pk_bf16_f32 v178, v123, v124
	v_cvt_pk_bf16_f32 v179, v125, v128
	global_store_dwordx4 v[160:161], v[176:179], off
; __device__ __forceinline__ float sigmoidf_(float x) { return __builtin_amdgcn_rcpf(1.0f + __builtin_amdgcn_exp2f(-1.4426950408889634f * x)); }
; __device__ __forceinline__ u32x4 pack8(const f32x4 a, const f32x4 b) { u32x4 w; w.x = pk2(a[0], a[1]); w.y = pk2(a[2], a[3]); w.z = pk2(b[0], b[1]); w.w = pk2(b[2], b[3]); return w; }
;     __device__ __forceinline__ void operator()(const Acc& acc, const Unit& u, int wr, int wc, int fr, int fq) const {
;     ...
;                     const float r1 = rs[ai * 4 + m];
; #pragma unroll
;                     for (int bj = 0; bj < 2; ++bj) {
;                         f32x4 s0, s1; const f32x4 v0 = acc[ai][bj][m][0], v1 = acc[ai][bj][m][1];
; #pragma unroll
;                         for (int e = 0; e < 4; ++e) { s0[e] = sigmoidf_(v0[e] * r1); s1[e] = sigmoidf_(v1[e] * r1); }
;                         if (sub == 0) *MP(ai, m, bj) = pack8(s0, s1); else *SP(ai, m, bj) = pack8(s0, s1);
.LBB0_5790:
	v_mul_f32_e32 v118, v118, v175
	v_mul_f32_e32 v114, v114, v175
	v_mul_f32_e32 v118, 0xbfb8aa3b, v118
	v_mul_f32_e32 v114, 0xbfb8aa3b, v114
	v_exp_f32_e32 v118, v118
	v_exp_f32_e32 v122, v114
	v_mul_f32_e32 v119, v119, v175
	v_mul_f32_e32 v115, v115, v175
	v_mul_f32_e32 v119, 0xbfb8aa3b, v119
	v_mul_f32_e32 v115, 0xbfb8aa3b, v115
	v_add_f32_e32 v114, 1.0, v118
	v_add_f32_e32 v118, 1.0, v122
	v_exp_f32_e32 v119, v119
	v_exp_f32_e32 v122, v115
	v_mul_f32_e32 v120, v120, v175
	v_mul_f32_e32 v116, v116, v175
	v_mul_f32_e32 v120, 0xbfb8aa3b, v120
	v_mul_f32_e32 v116, 0xbfb8aa3b, v116
	v_rcp_f32_e32 v115, v118
	v_add_f32_e32 v118, 1.0, v119
	v_add_f32_e32 v119, 1.0, v122
	v_exp_f32_e32 v120, v120
	v_exp_f32_e32 v122, v116
	v_mul_f32_e32 v121, v121, v175
	v_mul_f32_e32 v121, 0xbfb8aa3b, v121
	v_mul_f32_e32 v117, v117, v175
	v_exp_f32_e32 v121, v121
	v_mul_f32_e32 v117, 0xbfb8aa3b, v117
	v_rcp_f32_e32 v116, v119
	v_add_f32_e32 v119, 1.0, v120
	v_add_f32_e32 v120, 1.0, v122
	v_exp_f32_e32 v122, v117
	v_rcp_f32_e32 v117, v120
	v_add_f32_e32 v120, 1.0, v121
	v_rcp_f32_e32 v121, v120
	v_add_f32_e32 v120, 1.0, v122
	v_rcp_f32_e32 v114, v114
	v_rcp_f32_e32 v118, v118
	v_rcp_f32_e32 v119, v119
	v_rcp_f32_e32 v120, v120
	v_cndmask_b32_e64 v122, 0, 1, s[52:53]
	v_cmp_ne_u32_e64 s[4:5], 1, v122
	s_andn2_b64 vcc, exec, s[52:53]
	s_cbranch_vccnz .LBB0_5839
	v_add_co_u32_e32 v126, vcc, 0x2000, v162
	s_nop 1
	v_addc_co_u32_e32 v127, vcc, 0, v163, vcc
	v_cvt_pk_bf16_f32 v122, v114, v118
	v_cvt_pk_bf16_f32 v123, v119, v121
	v_cvt_pk_bf16_f32 v124, v115, v116
	v_cvt_pk_bf16_f32 v125, v117, v120
	global_store_dwordx4 v[126:127], v[122:125], off
	s_cbranch_execnz .LBB0_5793
.LBB0_5792:
	s_nop 0
	v_cvt_pk_bf16_f32 v122, v114, v118
	v_cvt_pk_bf16_f32 v123, v119, v121
	v_cvt_pk_bf16_f32 v124, v115, v116
	v_cvt_pk_bf16_f32 v125, v117, v120
	global_store_dwordx4 v[160:161], v[122:125], off offset:256
.LBB0_5793:
	v_add_f32_e32 v114, v168, v169
	v_fmamk_f32 v114, v114, 0x3a800000, v174
	v_rsq_f32_e32 v114, v114
	s_and_b64 vcc, exec, s[4:5]
	v_mul_f32_e32 v110, v110, v114
	v_mul_f32_e32 v106, v106, v114
	v_mul_f32_e32 v110, 0xbfb8aa3b, v110
	v_mul_f32_e32 v106, 0xbfb8aa3b, v106
	v_exp_f32_e32 v110, v110
	v_exp_f32_e32 v106, v106
	v_mul_f32_e32 v111, v111, v114
	v_mul_f32_e32 v107, v107, v114
	v_mul_f32_e32 v111, 0xbfb8aa3b, v111
	v_add_f32_e32 v110, 1.0, v110
	v_mul_f32_e32 v107, 0xbfb8aa3b, v107
	v_mul_f32_e32 v112, v112, v114
	v_mul_f32_e32 v108, v108, v114
	v_add_f32_e32 v115, 1.0, v106
	v_rcp_f32_e32 v106, v110
	v_exp_f32_e32 v110, v111
	v_exp_f32_e32 v111, v107
	v_mul_f32_e32 v112, 0xbfb8aa3b, v112
	v_mul_f32_e32 v108, 0xbfb8aa3b, v108
	v_rcp_f32_e32 v107, v115
	v_exp_f32_e32 v112, v112
	v_exp_f32_e32 v115, v108
	v_mul_f32_e32 v113, v113, v114
	v_mul_f32_e32 v113, 0xbfb8aa3b, v113
	v_mul_f32_e32 v109, v109, v114
	v_add_f32_e32 v111, 1.0, v111
	v_exp_f32_e32 v113, v113
	v_mul_f32_e32 v109, 0xbfb8aa3b, v109
	v_rcp_f32_e32 v108, v111
	v_add_f32_e32 v111, 1.0, v112
	v_add_f32_e32 v112, 1.0, v115
	v_exp_f32_e32 v115, v109
	v_rcp_f32_e32 v109, v112
	v_add_f32_e32 v112, 1.0, v113
	v_add_f32_e32 v110, 1.0, v110
	v_rcp_f32_e32 v113, v112
	v_add_f32_e32 v112, 1.0, v115
	v_rcp_f32_e32 v110, v110
	v_rcp_f32_e32 v111, v111
	v_rcp_f32_e32 v112, v112
	s_cbranch_vccnz .LBB0_5840
	v_add_co_u32_e32 v120, vcc, 0x4000, v162
	s_nop 1
	v_addc_co_u32_e32 v121, vcc, 0, v163, vcc
	v_cvt_pk_bf16_f32 v116, v106, v110
	v_cvt_pk_bf16_f32 v117, v111, v113
	v_cvt_pk_bf16_f32 v118, v107, v108
	v_cvt_pk_bf16_f32 v119, v109, v112
	global_store_dwordx4 v[120:121], v[116:119], off
	s_cbranch_execnz .LBB0_5796
.LBB0_5795:
	s_nop 0
	v_cvt_pk_bf16_f32 v116, v106, v110
	v_add_co_u32_e32 v106, vcc, 0x8000, v160
	v_cvt_pk_bf16_f32 v117, v111, v113
	v_cvt_pk_bf16_f32 v118, v107, v108
	v_cvt_pk_bf16_f32 v119, v109, v112
	s_nop 1
	v_addc_co_u32_e32 v107, vcc, 0, v161, vcc
	global_store_dwordx4 v[106:107], v[116:119], off
.LBB0_5796:
	v_mul_f32_e32 v102, v102, v114
	v_mul_f32_e32 v98, v98, v114
	v_mul_f32_e32 v102, 0xbfb8aa3b, v102
	v_mul_f32_e32 v98, 0xbfb8aa3b, v98
	v_exp_f32_e32 v102, v102
	v_exp_f32_e32 v106, v98
	v_mul_f32_e32 v103, v103, v114
	v_mul_f32_e32 v99, v99, v114
	v_mul_f32_e32 v103, 0xbfb8aa3b, v103
	v_mul_f32_e32 v99, 0xbfb8aa3b, v99
	v_add_f32_e32 v98, 1.0, v102
	v_add_f32_e32 v102, 1.0, v106
	v_exp_f32_e32 v103, v103
	v_exp_f32_e32 v106, v99
	v_mul_f32_e32 v104, v104, v114
	v_mul_f32_e32 v100, v100, v114
	v_mul_f32_e32 v104, 0xbfb8aa3b, v104
	v_mul_f32_e32 v100, 0xbfb8aa3b, v100
	v_rcp_f32_e32 v99, v102
	v_add_f32_e32 v102, 1.0, v103
	v_add_f32_e32 v103, 1.0, v106
	v_exp_f32_e32 v104, v104
	v_exp_f32_e32 v106, v100
	v_mul_f32_e32 v105, v105, v114
	v_mul_f32_e32 v105, 0xbfb8aa3b, v105
	v_mul_f32_e32 v101, v101, v114
	v_exp_f32_e32 v105, v105
	v_mul_f32_e32 v101, 0xbfb8aa3b, v101
	v_rcp_f32_e32 v100, v103
	v_add_f32_e32 v103, 1.0, v104
	v_add_f32_e32 v104, 1.0, v106
	v_exp_f32_e32 v106, v101
	v_rcp_f32_e32 v101, v104
	v_add_f32_e32 v104, 1.0, v105
	v_rcp_f32_e32 v105, v104
	v_add_f32_e32 v104, 1.0, v106
	v_rcp_f32_e32 v98, v98
	v_rcp_f32_e32 v102, v102
	v_rcp_f32_e32 v103, v103
	v_rcp_f32_e32 v104, v104
	s_and_b64 vcc, exec, s[4:5]
	s_cbranch_vccnz .LBB0_5841
	v_add_co_u32_e32 v110, vcc, 0x6000, v162
	s_nop 1
	v_addc_co_u32_e32 v111, vcc, 0, v163, vcc
	v_cvt_pk_bf16_f32 v106, v98, v102
	v_cvt_pk_bf16_f32 v107, v103, v105
	v_cvt_pk_bf16_f32 v108, v99, v100
	v_cvt_pk_bf16_f32 v109, v101, v104
	global_store_dwordx4 v[110:111], v[106:109], off
	s_cbranch_execnz .LBB0_5799
; __device__ __forceinline__ float sigmoidf_(float x) { return __builtin_amdgcn_rcpf(1.0f + __builtin_amdgcn_exp2f(-1.4426950408889634f * x)); }
; __device__ __forceinline__ u32x4 pack8(const f32x4 a, const f32x4 b) { u32x4 w; w.x = pk2(a[0], a[1]); w.y = pk2(a[2], a[3]); w.z = pk2(b[0], b[1]); w.w = pk2(b[2], b[3]); return w; }
;     __device__ __forceinline__ void operator()(const Acc& acc, const Unit& u, int wr, int wc, int fr, int fq) const {
;     ...
;                     const float r1 = rs[ai * 4 + m];
; #pragma unroll
;                     for (int bj = 0; bj < 2; ++bj) {
;                         f32x4 s0, s1; const f32x4 v0 = acc[ai][bj][m][0], v1 = acc[ai][bj][m][1];
; #pragma unroll
;                         for (int e = 0; e < 4; ++e) { s0[e] = sigmoidf_(v0[e] * r1); s1[e] = sigmoidf_(v1[e] * r1); }
;                         if (sub == 0) *MP(ai, m, bj) = pack8(s0, s1); else *SP(ai, m, bj) = pack8(s0, s1);
.LBB0_5798:
	s_nop 0
	v_cvt_pk_bf16_f32 v106, v98, v102
	v_add_co_u32_e32 v98, vcc, 0x8000, v160
	v_cvt_pk_bf16_f32 v107, v103, v105
	v_cvt_pk_bf16_f32 v108, v99, v100
	v_cvt_pk_bf16_f32 v109, v101, v104
	s_nop 1
	v_addc_co_u32_e32 v99, vcc, 0, v161, vcc
	global_store_dwordx4 v[98:99], v[106:109], off offset:256
.LBB0_5799:
	v_add_f32_e32 v98, v166, v167
	v_fmamk_f32 v98, v98, 0x3a800000, v174
	v_rsq_f32_e32 v98, v98
	s_and_b64 vcc, exec, s[4:5]
	v_mul_f32_e32 v94, v94, v98
	v_mul_f32_e32 v90, v90, v98
	v_mul_f32_e32 v94, 0xbfb8aa3b, v94
	v_mul_f32_e32 v90, 0xbfb8aa3b, v90
	v_exp_f32_e32 v94, v94
	v_exp_f32_e32 v90, v90
	v_mul_f32_e32 v95, v95, v98
	v_mul_f32_e32 v91, v91, v98
	v_mul_f32_e32 v95, 0xbfb8aa3b, v95
	v_add_f32_e32 v94, 1.0, v94
	v_mul_f32_e32 v91, 0xbfb8aa3b, v91
	v_mul_f32_e32 v96, v96, v98
	v_mul_f32_e32 v92, v92, v98
	v_add_f32_e32 v99, 1.0, v90
	v_rcp_f32_e32 v90, v94
	v_exp_f32_e32 v94, v95
	v_exp_f32_e32 v95, v91
	v_mul_f32_e32 v96, 0xbfb8aa3b, v96
	v_mul_f32_e32 v92, 0xbfb8aa3b, v92
	v_rcp_f32_e32 v91, v99
	v_exp_f32_e32 v96, v96
	v_exp_f32_e32 v99, v92
	v_mul_f32_e32 v97, v97, v98
	v_mul_f32_e32 v97, 0xbfb8aa3b, v97
	v_mul_f32_e32 v93, v93, v98
	v_add_f32_e32 v95, 1.0, v95
	v_exp_f32_e32 v97, v97
	v_mul_f32_e32 v93, 0xbfb8aa3b, v93
	v_rcp_f32_e32 v92, v95
	v_add_f32_e32 v95, 1.0, v96
	v_add_f32_e32 v96, 1.0, v99
	v_exp_f32_e32 v99, v93
	v_rcp_f32_e32 v93, v96
	v_add_f32_e32 v96, 1.0, v97
	v_add_f32_e32 v94, 1.0, v94
	v_rcp_f32_e32 v97, v96
	v_add_f32_e32 v96, 1.0, v99
	v_rcp_f32_e32 v94, v94
	v_rcp_f32_e32 v95, v95
	v_rcp_f32_e32 v96, v96
	s_cbranch_vccnz .LBB0_5842
	v_add_co_u32_e32 v104, vcc, 0x8000, v162
	s_nop 1
	v_addc_co_u32_e32 v105, vcc, 0, v163, vcc
	v_cvt_pk_bf16_f32 v100, v90, v94
	v_cvt_pk_bf16_f32 v101, v95, v97
	v_cvt_pk_bf16_f32 v102, v91, v92
	v_cvt_pk_bf16_f32 v103, v93, v96
	global_store_dwordx4 v[104:105], v[100:103], off
	s_cbranch_execnz .LBB0_5802
.LBB0_5801:
	s_nop 0
	v_cvt_pk_bf16_f32 v100, v90, v94
	v_add_co_u32_e32 v90, vcc, 0x10000, v160
	v_cvt_pk_bf16_f32 v101, v95, v97
	v_cvt_pk_bf16_f32 v102, v91, v92
	v_cvt_pk_bf16_f32 v103, v93, v96
	s_nop 1
	v_addc_co_u32_e32 v91, vcc, 0, v161, vcc
	global_store_dwordx4 v[90:91], v[100:103], off
.LBB0_5802:
	v_mul_f32_e32 v86, v86, v98
	v_mul_f32_e32 v82, v82, v98
	v_mul_f32_e32 v86, 0xbfb8aa3b, v86
	v_mul_f32_e32 v82, 0xbfb8aa3b, v82
	v_exp_f32_e32 v86, v86
	v_exp_f32_e32 v90, v82
	v_mul_f32_e32 v87, v87, v98
	v_mul_f32_e32 v83, v83, v98
	v_mul_f32_e32 v87, 0xbfb8aa3b, v87
	v_mul_f32_e32 v83, 0xbfb8aa3b, v83
	v_add_f32_e32 v82, 1.0, v86
	v_add_f32_e32 v86, 1.0, v90
	v_exp_f32_e32 v87, v87
	v_exp_f32_e32 v90, v83
	v_mul_f32_e32 v88, v88, v98
	v_mul_f32_e32 v84, v84, v98
	v_mul_f32_e32 v88, 0xbfb8aa3b, v88
	v_mul_f32_e32 v84, 0xbfb8aa3b, v84
	v_rcp_f32_e32 v83, v86
	v_add_f32_e32 v86, 1.0, v87
	v_add_f32_e32 v87, 1.0, v90
	v_exp_f32_e32 v88, v88
	v_exp_f32_e32 v90, v84
	v_mul_f32_e32 v89, v89, v98
	v_mul_f32_e32 v89, 0xbfb8aa3b, v89
	v_mul_f32_e32 v85, v85, v98
	v_exp_f32_e32 v89, v89
	v_mul_f32_e32 v85, 0xbfb8aa3b, v85
	v_rcp_f32_e32 v84, v87
	v_add_f32_e32 v87, 1.0, v88
	v_add_f32_e32 v88, 1.0, v90
	v_exp_f32_e32 v90, v85
	v_rcp_f32_e32 v85, v88
	v_add_f32_e32 v88, 1.0, v89
	v_rcp_f32_e32 v89, v88
	v_add_f32_e32 v88, 1.0, v90
	v_rcp_f32_e32 v82, v82
	v_rcp_f32_e32 v86, v86
	v_rcp_f32_e32 v87, v87
	v_rcp_f32_e32 v88, v88
	s_and_b64 vcc, exec, s[4:5]
	s_cbranch_vccnz .LBB0_5843
	v_add_co_u32_e32 v94, vcc, 0xa000, v162
	s_nop 1
	v_addc_co_u32_e32 v95, vcc, 0, v163, vcc
	v_cvt_pk_bf16_f32 v90, v82, v86
	v_cvt_pk_bf16_f32 v91, v87, v89
	v_cvt_pk_bf16_f32 v92, v83, v84
	v_cvt_pk_bf16_f32 v93, v85, v88
	global_store_dwordx4 v[94:95], v[90:93], off
	s_cbranch_execnz .LBB0_5805
.LBB0_5804:
	s_nop 0
	v_cvt_pk_bf16_f32 v90, v82, v86
	v_add_co_u32_e32 v82, vcc, 0x10000, v160
	v_cvt_pk_bf16_f32 v91, v87, v89
	v_cvt_pk_bf16_f32 v92, v83, v84
	v_cvt_pk_bf16_f32 v93, v85, v88
	s_nop 1
	v_addc_co_u32_e32 v83, vcc, 0, v161, vcc
	global_store_dwordx4 v[82:83], v[90:93], off offset:256
.LBB0_5805:
	v_add_f32_e32 v82, v164, v165
	v_fmamk_f32 v82, v82, 0x3a800000, v174
	v_rsq_f32_e32 v82, v82
	s_and_b64 vcc, exec, s[4:5]
	v_mul_f32_e32 v78, v78, v82
	v_mul_f32_e32 v74, v74, v82
	v_mul_f32_e32 v78, 0xbfb8aa3b, v78
	v_mul_f32_e32 v74, 0xbfb8aa3b, v74
	v_exp_f32_e32 v78, v78
	v_exp_f32_e32 v74, v74
	v_mul_f32_e32 v79, v79, v82
	v_mul_f32_e32 v75, v75, v82
	v_mul_f32_e32 v79, 0xbfb8aa3b, v79
	v_add_f32_e32 v78, 1.0, v78
	v_mul_f32_e32 v75, 0xbfb8aa3b, v75
	v_mul_f32_e32 v80, v80, v82
	v_mul_f32_e32 v76, v76, v82
	v_add_f32_e32 v83, 1.0, v74
	v_rcp_f32_e32 v74, v78
	v_exp_f32_e32 v78, v79
	v_exp_f32_e32 v79, v75
	v_mul_f32_e32 v80, 0xbfb8aa3b, v80
	v_mul_f32_e32 v76, 0xbfb8aa3b, v76
	v_rcp_f32_e32 v75, v83
	v_exp_f32_e32 v80, v80
	v_exp_f32_e32 v83, v76
	v_mul_f32_e32 v81, v81, v82
	v_mul_f32_e32 v81, 0xbfb8aa3b, v81
	v_mul_f32_e32 v77, v77, v82
	v_add_f32_e32 v79, 1.0, v79
	v_exp_f32_e32 v81, v81
	v_mul_f32_e32 v77, 0xbfb8aa3b, v77
	v_rcp_f32_e32 v76, v79
	v_add_f32_e32 v79, 1.0, v80
	v_add_f32_e32 v80, 1.0, v83
	v_exp_f32_e32 v83, v77
	v_rcp_f32_e32 v77, v80
	v_add_f32_e32 v80, 1.0, v81
	v_add_f32_e32 v78, 1.0, v78
	v_rcp_f32_e32 v81, v80
	v_add_f32_e32 v80, 1.0, v83
	v_rcp_f32_e32 v78, v78
	v_rcp_f32_e32 v79, v79
	v_rcp_f32_e32 v80, v80
	s_cbranch_vccnz .LBB0_5844
	v_add_co_u32_e32 v88, vcc, 0xc000, v162
	s_nop 1
	v_addc_co_u32_e32 v89, vcc, 0, v163, vcc
	v_cvt_pk_bf16_f32 v84, v74, v78
	v_cvt_pk_bf16_f32 v85, v79, v81
	v_cvt_pk_bf16_f32 v86, v75, v76
	v_cvt_pk_bf16_f32 v87, v77, v80
	global_store_dwordx4 v[88:89], v[84:87], off
	s_cbranch_execnz .LBB0_5808
; __device__ __forceinline__ float sigmoidf_(float x) { return __builtin_amdgcn_rcpf(1.0f + __builtin_amdgcn_exp2f(-1.4426950408889634f * x)); }
; __device__ __forceinline__ u32x4 pack8(const f32x4 a, const f32x4 b) { u32x4 w; w.x = pk2(a[0], a[1]); w.y = pk2(a[2], a[3]); w.z = pk2(b[0], b[1]); w.w = pk2(b[2], b[3]); return w; }
;     __device__ __forceinline__ void operator()(const Acc& acc, const Unit& u, int wr, int wc, int fr, int fq) const {
;     ...
;                     const float r1 = rs[ai * 4 + m];
; #pragma unroll
;                     for (int bj = 0; bj < 2; ++bj) {
;                         f32x4 s0, s1; const f32x4 v0 = acc[ai][bj][m][0], v1 = acc[ai][bj][m][1];
; #pragma unroll
;                         for (int e = 0; e < 4; ++e) { s0[e] = sigmoidf_(v0[e] * r1); s1[e] = sigmoidf_(v1[e] * r1); }
;                         if (sub == 0) *MP(ai, m, bj) = pack8(s0, s1); else *SP(ai, m, bj) = pack8(s0, s1);
.LBB0_5807:
	s_nop 0
	v_cvt_pk_bf16_f32 v84, v74, v78
	v_add_co_u32_e32 v74, vcc, 0x18000, v160
	v_cvt_pk_bf16_f32 v85, v79, v81
	v_cvt_pk_bf16_f32 v86, v75, v76
	v_cvt_pk_bf16_f32 v87, v77, v80
	s_nop 1
	v_addc_co_u32_e32 v75, vcc, 0, v161, vcc
	global_store_dwordx4 v[74:75], v[84:87], off
.LBB0_5808:
	v_mul_f32_e32 v70, v70, v82
	v_mul_f32_e32 v66, v66, v82
	v_mul_f32_e32 v70, 0xbfb8aa3b, v70
	v_mul_f32_e32 v66, 0xbfb8aa3b, v66
	v_exp_f32_e32 v70, v70
	v_exp_f32_e32 v74, v66
	v_mul_f32_e32 v71, v71, v82
	v_mul_f32_e32 v67, v67, v82
	v_mul_f32_e32 v71, 0xbfb8aa3b, v71
	v_mul_f32_e32 v67, 0xbfb8aa3b, v67
	v_add_f32_e32 v66, 1.0, v70
	v_add_f32_e32 v70, 1.0, v74
	v_exp_f32_e32 v71, v71
	v_exp_f32_e32 v74, v67
	v_mul_f32_e32 v72, v72, v82
	v_mul_f32_e32 v68, v68, v82
	v_mul_f32_e32 v72, 0xbfb8aa3b, v72
	v_mul_f32_e32 v68, 0xbfb8aa3b, v68
	v_rcp_f32_e32 v67, v70
	v_add_f32_e32 v70, 1.0, v71
	v_add_f32_e32 v71, 1.0, v74
	v_exp_f32_e32 v72, v72
	v_exp_f32_e32 v74, v68
	v_mul_f32_e32 v73, v73, v82
	v_mul_f32_e32 v73, 0xbfb8aa3b, v73
	v_mul_f32_e32 v69, v69, v82
	v_exp_f32_e32 v73, v73
	v_mul_f32_e32 v69, 0xbfb8aa3b, v69
	v_rcp_f32_e32 v68, v71
	v_add_f32_e32 v71, 1.0, v72
	v_add_f32_e32 v72, 1.0, v74
	v_exp_f32_e32 v74, v69
	v_rcp_f32_e32 v69, v72
	v_add_f32_e32 v72, 1.0, v73
	v_rcp_f32_e32 v73, v72
	v_add_f32_e32 v72, 1.0, v74
	v_rcp_f32_e32 v66, v66
	v_rcp_f32_e32 v70, v70
	v_rcp_f32_e32 v71, v71
	v_rcp_f32_e32 v72, v72
	s_and_b64 vcc, exec, s[4:5]
	s_cbranch_vccnz .LBB0_5845
	v_add_co_u32_e32 v78, vcc, 0xe000, v162
	s_nop 1
	v_addc_co_u32_e32 v79, vcc, 0, v163, vcc
	v_cvt_pk_bf16_f32 v74, v66, v70
	v_cvt_pk_bf16_f32 v75, v71, v73
	v_cvt_pk_bf16_f32 v76, v67, v68
	v_cvt_pk_bf16_f32 v77, v69, v72
	global_store_dwordx4 v[78:79], v[74:77], off
	s_cbranch_execnz .LBB0_5811
.LBB0_5810:
	s_nop 0
	v_cvt_pk_bf16_f32 v74, v66, v70
	v_add_co_u32_e32 v66, vcc, 0x18000, v160
	v_cvt_pk_bf16_f32 v75, v71, v73
	v_cvt_pk_bf16_f32 v76, v67, v68
	v_cvt_pk_bf16_f32 v77, v69, v72
	s_nop 1
	v_addc_co_u32_e32 v67, vcc, 0, v161, vcc
	global_store_dwordx4 v[66:67], v[74:77], off offset:256
.LBB0_5811:
	v_add_f32_e32 v66, v136, v137
	v_fmamk_f32 v66, v66, 0x3a800000, v174
	v_rsq_f32_e32 v66, v66
	s_and_b64 vcc, exec, s[4:5]
	v_mul_f32_e32 v62, v62, v66
	v_mul_f32_e32 v58, v58, v66
	v_mul_f32_e32 v62, 0xbfb8aa3b, v62
	v_mul_f32_e32 v58, 0xbfb8aa3b, v58
	v_exp_f32_e32 v62, v62
	v_exp_f32_e32 v58, v58
	v_mul_f32_e32 v63, v63, v66
	v_mul_f32_e32 v59, v59, v66
	v_mul_f32_e32 v63, 0xbfb8aa3b, v63
	v_add_f32_e32 v62, 1.0, v62
	v_mul_f32_e32 v59, 0xbfb8aa3b, v59
	v_mul_f32_e32 v64, v64, v66
	v_mul_f32_e32 v60, v60, v66
	v_add_f32_e32 v67, 1.0, v58
	v_rcp_f32_e32 v58, v62
	v_exp_f32_e32 v62, v63
	v_exp_f32_e32 v63, v59
	v_mul_f32_e32 v64, 0xbfb8aa3b, v64
	v_mul_f32_e32 v60, 0xbfb8aa3b, v60
	v_rcp_f32_e32 v59, v67
	v_exp_f32_e32 v64, v64
	v_exp_f32_e32 v67, v60
	v_mul_f32_e32 v65, v65, v66
	v_mul_f32_e32 v65, 0xbfb8aa3b, v65
	v_mul_f32_e32 v61, v61, v66
	v_add_f32_e32 v63, 1.0, v63
	v_exp_f32_e32 v65, v65
	v_mul_f32_e32 v61, 0xbfb8aa3b, v61
	v_rcp_f32_e32 v60, v63
	v_add_f32_e32 v63, 1.0, v64
	v_add_f32_e32 v64, 1.0, v67
	v_exp_f32_e32 v67, v61
	v_rcp_f32_e32 v61, v64
	v_add_f32_e32 v64, 1.0, v65
	v_add_f32_e32 v62, 1.0, v62
	v_rcp_f32_e32 v65, v64
	v_add_f32_e32 v64, 1.0, v67
	v_rcp_f32_e32 v62, v62
	v_rcp_f32_e32 v63, v63
	v_rcp_f32_e32 v64, v64
	s_cbranch_vccnz .LBB0_5846
	v_add_co_u32_e32 v72, vcc, 0x10000, v162
	s_nop 1
	v_addc_co_u32_e32 v73, vcc, 0, v163, vcc
	v_cvt_pk_bf16_f32 v68, v58, v62
	v_cvt_pk_bf16_f32 v69, v63, v65
	v_cvt_pk_bf16_f32 v70, v59, v60
	v_cvt_pk_bf16_f32 v71, v61, v64
	global_store_dwordx4 v[72:73], v[68:71], off
	s_cbranch_execnz .LBB0_5814
.LBB0_5813:
	s_nop 0
	v_cvt_pk_bf16_f32 v68, v58, v62
	v_add_co_u32_e32 v58, vcc, 0x40000, v160
	v_cvt_pk_bf16_f32 v69, v63, v65
	v_cvt_pk_bf16_f32 v70, v59, v60
	v_cvt_pk_bf16_f32 v71, v61, v64
	s_nop 1
	v_addc_co_u32_e32 v59, vcc, 0, v161, vcc
	global_store_dwordx4 v[58:59], v[68:71], off
.LBB0_5814:
	v_mul_f32_e32 v54, v54, v66
	v_mul_f32_e32 v50, v50, v66
	v_mul_f32_e32 v54, 0xbfb8aa3b, v54
	v_mul_f32_e32 v50, 0xbfb8aa3b, v50
	v_exp_f32_e32 v54, v54
	v_exp_f32_e32 v58, v50
	v_mul_f32_e32 v55, v55, v66
	v_mul_f32_e32 v51, v51, v66
	v_mul_f32_e32 v55, 0xbfb8aa3b, v55
	v_mul_f32_e32 v51, 0xbfb8aa3b, v51
	v_add_f32_e32 v50, 1.0, v54
	v_add_f32_e32 v54, 1.0, v58
	v_exp_f32_e32 v55, v55
	v_exp_f32_e32 v58, v51
	v_mul_f32_e32 v56, v56, v66
	v_mul_f32_e32 v52, v52, v66
	v_mul_f32_e32 v56, 0xbfb8aa3b, v56
	v_mul_f32_e32 v52, 0xbfb8aa3b, v52
	v_rcp_f32_e32 v51, v54
	v_add_f32_e32 v54, 1.0, v55
	v_add_f32_e32 v55, 1.0, v58
	v_exp_f32_e32 v56, v56
	v_exp_f32_e32 v58, v52
	v_mul_f32_e32 v57, v57, v66
	v_mul_f32_e32 v57, 0xbfb8aa3b, v57
	v_mul_f32_e32 v53, v53, v66
	v_exp_f32_e32 v57, v57
	v_mul_f32_e32 v53, 0xbfb8aa3b, v53
	v_rcp_f32_e32 v52, v55
	v_add_f32_e32 v55, 1.0, v56
	v_add_f32_e32 v56, 1.0, v58
	v_exp_f32_e32 v58, v53
	v_rcp_f32_e32 v53, v56
	v_add_f32_e32 v56, 1.0, v57
	v_rcp_f32_e32 v57, v56
	v_add_f32_e32 v56, 1.0, v58
	v_rcp_f32_e32 v50, v50
	v_rcp_f32_e32 v54, v54
	v_rcp_f32_e32 v55, v55
	v_rcp_f32_e32 v56, v56
	s_and_b64 vcc, exec, s[4:5]
	s_cbranch_vccnz .LBB0_5847
	v_add_co_u32_e32 v62, vcc, 0x12000, v162
	s_nop 1
	v_addc_co_u32_e32 v63, vcc, 0, v163, vcc
	v_cvt_pk_bf16_f32 v58, v50, v54
	v_cvt_pk_bf16_f32 v59, v55, v57
	v_cvt_pk_bf16_f32 v60, v51, v52
	v_cvt_pk_bf16_f32 v61, v53, v56
	global_store_dwordx4 v[62:63], v[58:61], off
	s_cbranch_execnz .LBB0_5817
; __device__ __forceinline__ float sigmoidf_(float x) { return __builtin_amdgcn_rcpf(1.0f + __builtin_amdgcn_exp2f(-1.4426950408889634f * x)); }
; __device__ __forceinline__ u32x4 pack8(const f32x4 a, const f32x4 b) { u32x4 w; w.x = pk2(a[0], a[1]); w.y = pk2(a[2], a[3]); w.z = pk2(b[0], b[1]); w.w = pk2(b[2], b[3]); return w; }
;     __device__ __forceinline__ void operator()(const Acc& acc, const Unit& u, int wr, int wc, int fr, int fq) const {
;     ...
;                     const float r1 = rs[ai * 4 + m];
; #pragma unroll
;                     for (int bj = 0; bj < 2; ++bj) {
;                         f32x4 s0, s1; const f32x4 v0 = acc[ai][bj][m][0], v1 = acc[ai][bj][m][1];
; #pragma unroll
;                         for (int e = 0; e < 4; ++e) { s0[e] = sigmoidf_(v0[e] * r1); s1[e] = sigmoidf_(v1[e] * r1); }
;                         if (sub == 0) *MP(ai, m, bj) = pack8(s0, s1); else *SP(ai, m, bj) = pack8(s0, s1);
.LBB0_5816:
	s_nop 0
	v_cvt_pk_bf16_f32 v58, v50, v54
	v_add_co_u32_e32 v50, vcc, 0x40000, v160
	v_cvt_pk_bf16_f32 v59, v55, v57
	v_cvt_pk_bf16_f32 v60, v51, v52
	v_cvt_pk_bf16_f32 v61, v53, v56
	s_nop 1
	v_addc_co_u32_e32 v51, vcc, 0, v161, vcc
	global_store_dwordx4 v[50:51], v[58:61], off offset:256
.LBB0_5817:
	v_add_f32_e32 v50, v134, v135
	v_fmamk_f32 v50, v50, 0x3a800000, v174
	v_rsq_f32_e32 v50, v50
	s_and_b64 vcc, exec, s[4:5]
	v_mul_f32_e32 v46, v46, v50
	v_mul_f32_e32 v42, v42, v50
	v_mul_f32_e32 v46, 0xbfb8aa3b, v46
	v_mul_f32_e32 v42, 0xbfb8aa3b, v42
	v_exp_f32_e32 v46, v46
	v_exp_f32_e32 v42, v42
	v_mul_f32_e32 v47, v47, v50
	v_mul_f32_e32 v43, v43, v50
	v_mul_f32_e32 v47, 0xbfb8aa3b, v47
	v_add_f32_e32 v46, 1.0, v46
	v_mul_f32_e32 v43, 0xbfb8aa3b, v43
	v_mul_f32_e32 v48, v48, v50
	v_mul_f32_e32 v44, v44, v50
	v_add_f32_e32 v51, 1.0, v42
	v_rcp_f32_e32 v42, v46
	v_exp_f32_e32 v46, v47
	v_exp_f32_e32 v47, v43
	v_mul_f32_e32 v48, 0xbfb8aa3b, v48
	v_mul_f32_e32 v44, 0xbfb8aa3b, v44
	v_rcp_f32_e32 v43, v51
	v_exp_f32_e32 v48, v48
	v_exp_f32_e32 v51, v44
	v_mul_f32_e32 v49, v49, v50
	v_mul_f32_e32 v49, 0xbfb8aa3b, v49
	v_mul_f32_e32 v45, v45, v50
	v_add_f32_e32 v47, 1.0, v47
	v_exp_f32_e32 v49, v49
	v_mul_f32_e32 v45, 0xbfb8aa3b, v45
	v_rcp_f32_e32 v44, v47
	v_add_f32_e32 v47, 1.0, v48
	v_add_f32_e32 v48, 1.0, v51
	v_exp_f32_e32 v51, v45
	v_rcp_f32_e32 v45, v48
	v_add_f32_e32 v48, 1.0, v49
	v_add_f32_e32 v46, 1.0, v46
	v_rcp_f32_e32 v49, v48
	v_add_f32_e32 v48, 1.0, v51
	v_rcp_f32_e32 v46, v46
	v_rcp_f32_e32 v47, v47
	v_rcp_f32_e32 v48, v48
	s_cbranch_vccnz .LBB0_5848
	v_add_co_u32_e32 v56, vcc, 0x14000, v162
	s_nop 1
	v_addc_co_u32_e32 v57, vcc, 0, v163, vcc
	v_cvt_pk_bf16_f32 v52, v42, v46
	v_cvt_pk_bf16_f32 v53, v47, v49
	v_cvt_pk_bf16_f32 v54, v43, v44
	v_cvt_pk_bf16_f32 v55, v45, v48
	global_store_dwordx4 v[56:57], v[52:55], off
	s_cbranch_execnz .LBB0_5820
.LBB0_5819:
	s_nop 0
	v_cvt_pk_bf16_f32 v52, v42, v46
	v_add_co_u32_e32 v42, vcc, 0x48000, v160
	v_cvt_pk_bf16_f32 v53, v47, v49
	v_cvt_pk_bf16_f32 v54, v43, v44
	v_cvt_pk_bf16_f32 v55, v45, v48
	s_nop 1
	v_addc_co_u32_e32 v43, vcc, 0, v161, vcc
	global_store_dwordx4 v[42:43], v[52:55], off
.LBB0_5820:
	v_mul_f32_e32 v38, v38, v50
	v_mul_f32_e32 v34, v34, v50
	v_mul_f32_e32 v38, 0xbfb8aa3b, v38
	v_mul_f32_e32 v34, 0xbfb8aa3b, v34
	v_exp_f32_e32 v38, v38
	v_exp_f32_e32 v42, v34
	v_mul_f32_e32 v39, v39, v50
	v_mul_f32_e32 v35, v35, v50
	v_mul_f32_e32 v39, 0xbfb8aa3b, v39
	v_mul_f32_e32 v35, 0xbfb8aa3b, v35
	v_add_f32_e32 v34, 1.0, v38
	v_add_f32_e32 v38, 1.0, v42
	v_exp_f32_e32 v39, v39
	v_exp_f32_e32 v42, v35
	v_mul_f32_e32 v40, v40, v50
	v_mul_f32_e32 v36, v36, v50
	v_mul_f32_e32 v40, 0xbfb8aa3b, v40
	v_mul_f32_e32 v36, 0xbfb8aa3b, v36
	v_rcp_f32_e32 v35, v38
	v_add_f32_e32 v38, 1.0, v39
	v_add_f32_e32 v39, 1.0, v42
	v_exp_f32_e32 v40, v40
	v_exp_f32_e32 v42, v36
	v_mul_f32_e32 v41, v41, v50
	v_mul_f32_e32 v41, 0xbfb8aa3b, v41
	v_mul_f32_e32 v37, v37, v50
	v_exp_f32_e32 v41, v41
	v_mul_f32_e32 v37, 0xbfb8aa3b, v37
	v_rcp_f32_e32 v36, v39
	v_add_f32_e32 v39, 1.0, v40
	v_add_f32_e32 v40, 1.0, v42
	v_exp_f32_e32 v42, v37
	v_rcp_f32_e32 v37, v40
	v_add_f32_e32 v40, 1.0, v41
	v_rcp_f32_e32 v41, v40
	v_add_f32_e32 v40, 1.0, v42
	v_rcp_f32_e32 v34, v34
	v_rcp_f32_e32 v38, v38
	v_rcp_f32_e32 v39, v39
	v_rcp_f32_e32 v40, v40
	s_and_b64 vcc, exec, s[4:5]
	s_cbranch_vccnz .LBB0_5849
	v_add_co_u32_e32 v46, vcc, 0x16000, v162
	s_nop 1
	v_addc_co_u32_e32 v47, vcc, 0, v163, vcc
	v_cvt_pk_bf16_f32 v42, v34, v38
	v_cvt_pk_bf16_f32 v43, v39, v41
	v_cvt_pk_bf16_f32 v44, v35, v36
	v_cvt_pk_bf16_f32 v45, v37, v40
	global_store_dwordx4 v[46:47], v[42:45], off
	s_cbranch_execnz .LBB0_5823
.LBB0_5822:
	s_nop 0
	v_cvt_pk_bf16_f32 v42, v34, v38
	v_add_co_u32_e32 v34, vcc, 0x48000, v160
	v_cvt_pk_bf16_f32 v43, v39, v41
	v_cvt_pk_bf16_f32 v44, v35, v36
	v_cvt_pk_bf16_f32 v45, v37, v40
	s_nop 1
	v_addc_co_u32_e32 v35, vcc, 0, v161, vcc
	global_store_dwordx4 v[34:35], v[42:45], off offset:256
.LBB0_5823:
	v_add_f32_e32 v34, v132, v133
	v_fmamk_f32 v34, v34, 0x3a800000, v174
	v_rsq_f32_e32 v34, v34
	s_and_b64 vcc, exec, s[4:5]
	v_mul_f32_e32 v30, v30, v34
	v_mul_f32_e32 v26, v26, v34
	v_mul_f32_e32 v30, 0xbfb8aa3b, v30
	v_mul_f32_e32 v26, 0xbfb8aa3b, v26
	v_exp_f32_e32 v30, v30
	v_exp_f32_e32 v26, v26
	v_mul_f32_e32 v31, v31, v34
	v_mul_f32_e32 v27, v27, v34
	v_mul_f32_e32 v31, 0xbfb8aa3b, v31
	v_add_f32_e32 v30, 1.0, v30
	v_mul_f32_e32 v27, 0xbfb8aa3b, v27
	v_mul_f32_e32 v32, v32, v34
	v_mul_f32_e32 v28, v28, v34
	v_add_f32_e32 v35, 1.0, v26
	v_rcp_f32_e32 v26, v30
	v_exp_f32_e32 v30, v31
	v_exp_f32_e32 v31, v27
	v_mul_f32_e32 v32, 0xbfb8aa3b, v32
	v_mul_f32_e32 v28, 0xbfb8aa3b, v28
	v_rcp_f32_e32 v27, v35
	v_exp_f32_e32 v32, v32
	v_exp_f32_e32 v35, v28
	v_mul_f32_e32 v33, v33, v34
	v_mul_f32_e32 v33, 0xbfb8aa3b, v33
	v_mul_f32_e32 v29, v29, v34
	v_add_f32_e32 v31, 1.0, v31
	v_exp_f32_e32 v33, v33
	v_mul_f32_e32 v29, 0xbfb8aa3b, v29
	v_rcp_f32_e32 v28, v31
	v_add_f32_e32 v31, 1.0, v32
	v_add_f32_e32 v32, 1.0, v35
	v_exp_f32_e32 v35, v29
	v_rcp_f32_e32 v29, v32
	v_add_f32_e32 v32, 1.0, v33
	v_add_f32_e32 v30, 1.0, v30
	v_rcp_f32_e32 v33, v32
	v_add_f32_e32 v32, 1.0, v35
	v_rcp_f32_e32 v30, v30
	v_rcp_f32_e32 v31, v31
	v_rcp_f32_e32 v32, v32
	s_cbranch_vccnz .LBB0_5850
	v_add_co_u32_e32 v40, vcc, 0x18000, v162
	s_nop 1
	v_addc_co_u32_e32 v41, vcc, 0, v163, vcc
	v_cvt_pk_bf16_f32 v36, v26, v30
	v_cvt_pk_bf16_f32 v37, v31, v33
	v_cvt_pk_bf16_f32 v38, v27, v28
	v_cvt_pk_bf16_f32 v39, v29, v32
	global_store_dwordx4 v[40:41], v[36:39], off
	s_cbranch_execnz .LBB0_5826
; __device__ __forceinline__ float sigmoidf_(float x) { return __builtin_amdgcn_rcpf(1.0f + __builtin_amdgcn_exp2f(-1.4426950408889634f * x)); }
; __device__ __forceinline__ u32x4 pack8(const f32x4 a, const f32x4 b) { u32x4 w; w.x = pk2(a[0], a[1]); w.y = pk2(a[2], a[3]); w.z = pk2(b[0], b[1]); w.w = pk2(b[2], b[3]); return w; }
;     __device__ __forceinline__ void operator()(const Acc& acc, const Unit& u, int wr, int wc, int fr, int fq) const {
;     ...
;                     const float r1 = rs[ai * 4 + m];
; #pragma unroll
;                     for (int bj = 0; bj < 2; ++bj) {
;                         f32x4 s0, s1; const f32x4 v0 = acc[ai][bj][m][0], v1 = acc[ai][bj][m][1];
; #pragma unroll
;                         for (int e = 0; e < 4; ++e) { s0[e] = sigmoidf_(v0[e] * r1); s1[e] = sigmoidf_(v1[e] * r1); }
;                         if (sub == 0) *MP(ai, m, bj) = pack8(s0, s1); else *SP(ai, m, bj) = pack8(s0, s1);
.LBB0_5825:
	s_nop 0
	v_cvt_pk_bf16_f32 v36, v26, v30
	v_add_co_u32_e32 v26, vcc, 0x50000, v160
	v_cvt_pk_bf16_f32 v37, v31, v33
	v_cvt_pk_bf16_f32 v38, v27, v28
	v_cvt_pk_bf16_f32 v39, v29, v32
	s_nop 1
	v_addc_co_u32_e32 v27, vcc, 0, v161, vcc
	global_store_dwordx4 v[26:27], v[36:39], off
.LBB0_5826:
	v_mul_f32_e32 v22, v22, v34
	v_mul_f32_e32 v18, v18, v34
	v_mul_f32_e32 v22, 0xbfb8aa3b, v22
	v_mul_f32_e32 v18, 0xbfb8aa3b, v18
	v_exp_f32_e32 v22, v22
	v_exp_f32_e32 v26, v18
	v_mul_f32_e32 v23, v23, v34
	v_mul_f32_e32 v19, v19, v34
	v_mul_f32_e32 v23, 0xbfb8aa3b, v23
	v_mul_f32_e32 v19, 0xbfb8aa3b, v19
	v_add_f32_e32 v18, 1.0, v22
	v_add_f32_e32 v22, 1.0, v26
	v_exp_f32_e32 v23, v23
	v_exp_f32_e32 v26, v19
	v_mul_f32_e32 v24, v24, v34
	v_mul_f32_e32 v20, v20, v34
	v_mul_f32_e32 v24, 0xbfb8aa3b, v24
	v_mul_f32_e32 v20, 0xbfb8aa3b, v20
	v_rcp_f32_e32 v19, v22
	v_add_f32_e32 v22, 1.0, v23
	v_add_f32_e32 v23, 1.0, v26
	v_exp_f32_e32 v24, v24
	v_exp_f32_e32 v26, v20
	v_mul_f32_e32 v25, v25, v34
	v_mul_f32_e32 v25, 0xbfb8aa3b, v25
	v_mul_f32_e32 v21, v21, v34
	v_exp_f32_e32 v25, v25
	v_mul_f32_e32 v21, 0xbfb8aa3b, v21
	v_rcp_f32_e32 v20, v23
	v_add_f32_e32 v23, 1.0, v24
	v_add_f32_e32 v24, 1.0, v26
	v_exp_f32_e32 v26, v21
	v_rcp_f32_e32 v21, v24
	v_add_f32_e32 v24, 1.0, v25
	v_rcp_f32_e32 v25, v24
	v_add_f32_e32 v24, 1.0, v26
	v_rcp_f32_e32 v18, v18
	v_rcp_f32_e32 v22, v22
	v_rcp_f32_e32 v23, v23
	v_rcp_f32_e32 v24, v24
	s_and_b64 vcc, exec, s[4:5]
	s_cbranch_vccnz .LBB0_5851
	v_add_co_u32_e32 v30, vcc, 0x1a000, v162
	s_nop 1
	v_addc_co_u32_e32 v31, vcc, 0, v163, vcc
	v_cvt_pk_bf16_f32 v26, v18, v22
	v_cvt_pk_bf16_f32 v27, v23, v25
	v_cvt_pk_bf16_f32 v28, v19, v20
	v_cvt_pk_bf16_f32 v29, v21, v24
	global_store_dwordx4 v[30:31], v[26:29], off
	s_cbranch_execnz .LBB0_5829
.LBB0_5828:
	s_nop 0
	v_cvt_pk_bf16_f32 v26, v18, v22
	v_add_co_u32_e32 v18, vcc, 0x50000, v160
	v_cvt_pk_bf16_f32 v27, v23, v25
	v_cvt_pk_bf16_f32 v28, v19, v20
	v_cvt_pk_bf16_f32 v29, v21, v24
	s_nop 1
	v_addc_co_u32_e32 v19, vcc, 0, v161, vcc
	global_store_dwordx4 v[18:19], v[26:29], off offset:256
.LBB0_5829:
	v_add_f32_e32 v18, v130, v131
	v_fmamk_f32 v18, v18, 0x3a800000, v174
	v_rsq_f32_e32 v18, v18
	s_and_b64 vcc, exec, s[4:5]
	v_mul_f32_e32 v14, v14, v18
	v_mul_f32_e32 v10, v10, v18
	v_mul_f32_e32 v14, 0xbfb8aa3b, v14
	v_mul_f32_e32 v10, 0xbfb8aa3b, v10
	v_exp_f32_e32 v14, v14
	v_exp_f32_e32 v10, v10
	v_mul_f32_e32 v15, v15, v18
	v_mul_f32_e32 v11, v11, v18
	v_mul_f32_e32 v15, 0xbfb8aa3b, v15
	v_add_f32_e32 v14, 1.0, v14
	v_mul_f32_e32 v11, 0xbfb8aa3b, v11
	v_mul_f32_e32 v16, v16, v18
	v_mul_f32_e32 v12, v12, v18
	v_add_f32_e32 v19, 1.0, v10
	v_rcp_f32_e32 v10, v14
	v_exp_f32_e32 v14, v15
	v_exp_f32_e32 v15, v11
	v_mul_f32_e32 v16, 0xbfb8aa3b, v16
	v_mul_f32_e32 v12, 0xbfb8aa3b, v12
	v_rcp_f32_e32 v11, v19
	v_exp_f32_e32 v16, v16
	v_exp_f32_e32 v19, v12
	v_mul_f32_e32 v17, v17, v18
	v_mul_f32_e32 v17, 0xbfb8aa3b, v17
	v_mul_f32_e32 v13, v13, v18
	v_add_f32_e32 v15, 1.0, v15
	v_exp_f32_e32 v17, v17
	v_mul_f32_e32 v13, 0xbfb8aa3b, v13
	v_rcp_f32_e32 v12, v15
	v_add_f32_e32 v15, 1.0, v16
	v_add_f32_e32 v16, 1.0, v19
	v_exp_f32_e32 v19, v13
	v_rcp_f32_e32 v13, v16
	v_add_f32_e32 v16, 1.0, v17
	v_add_f32_e32 v14, 1.0, v14
	v_rcp_f32_e32 v17, v16
	v_add_f32_e32 v16, 1.0, v19
	v_rcp_f32_e32 v14, v14
	v_rcp_f32_e32 v15, v15
	v_rcp_f32_e32 v16, v16
	s_cbranch_vccnz .LBB0_5852
	v_add_co_u32_e32 v24, vcc, 0x1c000, v162
	s_nop 1
	v_addc_co_u32_e32 v25, vcc, 0, v163, vcc
	v_cvt_pk_bf16_f32 v20, v10, v14
	v_cvt_pk_bf16_f32 v21, v15, v17
	v_cvt_pk_bf16_f32 v22, v11, v12
	v_cvt_pk_bf16_f32 v23, v13, v16
	global_store_dwordx4 v[24:25], v[20:23], off
	s_cbranch_execnz .LBB0_5832
.LBB0_5831:
	s_nop 0
	v_cvt_pk_bf16_f32 v20, v10, v14
	v_add_co_u32_e32 v10, vcc, 0x58000, v160
	v_cvt_pk_bf16_f32 v21, v15, v17
	v_cvt_pk_bf16_f32 v22, v11, v12
	v_cvt_pk_bf16_f32 v23, v13, v16
	s_nop 1
	v_addc_co_u32_e32 v11, vcc, 0, v161, vcc
	global_store_dwordx4 v[10:11], v[20:23], off
.LBB0_5832:
	v_mul_f32_e32 v6, v6, v18
	v_mul_f32_e32 v2, v2, v18
	v_mul_f32_e32 v6, 0xbfb8aa3b, v6
	v_mul_f32_e32 v2, 0xbfb8aa3b, v2
	v_exp_f32_e32 v6, v6
	v_exp_f32_e32 v10, v2
	v_mul_f32_e32 v7, v7, v18
	v_mul_f32_e32 v3, v3, v18
	v_mul_f32_e32 v7, 0xbfb8aa3b, v7
	v_mul_f32_e32 v3, 0xbfb8aa3b, v3
	v_add_f32_e32 v2, 1.0, v6
	v_add_f32_e32 v6, 1.0, v10
	v_exp_f32_e32 v7, v7
	v_exp_f32_e32 v10, v3
	v_mul_f32_e32 v8, v8, v18
	v_mul_f32_e32 v4, v4, v18
	v_mul_f32_e32 v8, 0xbfb8aa3b, v8
	v_mul_f32_e32 v4, 0xbfb8aa3b, v4
	v_rcp_f32_e32 v3, v6
	v_add_f32_e32 v6, 1.0, v7
	v_add_f32_e32 v7, 1.0, v10
	v_exp_f32_e32 v8, v8
	v_exp_f32_e32 v10, v4
	v_mul_f32_e32 v9, v9, v18
	v_mul_f32_e32 v9, 0xbfb8aa3b, v9
	v_mul_f32_e32 v5, v5, v18
	v_exp_f32_e32 v9, v9
	v_mul_f32_e32 v5, 0xbfb8aa3b, v5
	v_rcp_f32_e32 v4, v7
	v_add_f32_e32 v7, 1.0, v8
	v_add_f32_e32 v8, 1.0, v10
	v_exp_f32_e32 v10, v5
	v_rcp_f32_e32 v5, v8
	v_add_f32_e32 v8, 1.0, v9
	v_rcp_f32_e32 v9, v8
	v_add_f32_e32 v8, 1.0, v10
	v_rcp_f32_e32 v2, v2
	v_rcp_f32_e32 v6, v6
	v_rcp_f32_e32 v7, v7
	v_rcp_f32_e32 v8, v8
	s_and_b64 vcc, exec, s[4:5]
	s_cbranch_vccnz .LBB0_5853
	v_add_co_u32_e32 v14, vcc, 0x1e000, v162
	s_nop 1
	v_addc_co_u32_e32 v15, vcc, 0, v163, vcc
	v_cvt_pk_bf16_f32 v10, v2, v6
	v_cvt_pk_bf16_f32 v11, v7, v9
	v_cvt_pk_bf16_f32 v12, v3, v4
	v_cvt_pk_bf16_f32 v13, v5, v8
	global_store_dwordx4 v[14:15], v[10:13], off
	s_cbranch_execnz .LBB0_5835
.LBB0_5834:
	s_nop 0
	v_cvt_pk_bf16_f32 v10, v2, v6
	v_add_co_u32_e32 v2, vcc, 0x58000, v160
	v_cvt_pk_bf16_f32 v11, v7, v9
	v_cvt_pk_bf16_f32 v12, v3, v4
	v_cvt_pk_bf16_f32 v13, v5, v8
	s_nop 1
	v_addc_co_u32_e32 v3, vcc, 0, v161, vcc
	global_store_dwordx4 v[2:3], v[10:13], off offset:256
